# in-proj / ff1 tiles: first MFMA per accumulator starts from inline 0, the 64 accumulator-zeroing moves per tile are gone
# baseline (speedup 1.0000x reference)
; template <class Epi, class ColV>
; DI void gemm_tile(const bf16_t* __restrict__ A, int lda, const bf16_t* __restrict__ Bt, int ldb, int K, int m0, int n0, unsigned char* smem, Epi epi, ColV colv, const bf16_t* __restrict__ HYT = nullptr) {
;     ...
;     const int tid = get_tid(), lane = tid & 63, wave = tid >> 6, wr = wave >> 1, wc = wave & 1, li = lane & 31, lh = lane >> 5;
;     f32x16 acc[2][2];
; #pragma unroll
;     for (int a = 0; a < 2; ++a)
; #pragma unroll
;         for (int b = 0; b < 2; ++b) acc[a][b] = zero16();
;     u32x4 R0[8], R1[8];
;     const int nk = K >> 6;
;     auto gload = [&](u32x4 (&r)[8], int kt) {
; #pragma unroll
;         for (int i = 0; i < 4; ++i) { int id = tid + 256 * i, row = id >> 3, kc = id & 7;
;             if (HYT && kt >= 12) r[i] = *(const u32x4*)(HYT + (size_t)((kt - 12) * 64 + (id >> 4)) * NT + m0 + (id & 15) * 8);
;             else r[i] = *(const u32x4*)(A + (size_t)(m0 + row) * lda + kt * 64 + kc * 8);
;             r[4 + i] = *(const u32x4*)(Bt + (size_t)(n0 + row) * ldb + kt * 64 + kc * 8); }
;     };
;     auto sstore = [&](const u32x4 (&r)[8], int buf, int kt) {
; #pragma unroll
;         for (int i = 0; i < 4; ++i) { int id = tid + 256 * i, row = id >> 3, kc = id & 7;
;             if (HYT && kt >= 12) { const int kk = id >> 4, rr = (id & 15) * 8; bf16_t* d = As + (buf * 128 + rr) * LS + kk; const bf16x8 v = __builtin_bit_cast(bf16x8, r[i]);
; #pragma unroll
;                 for (int e = 0; e < 8; ++e) d[e * LS] = (bf16_t)v[e]; }
;             else *(u32x4*)(As + (buf * 128 + row) * LS + kc * 8) = r[i];
;             *(u32x4*)(Bs + (buf * 128 + row) * LS + kc * 8) = r[4 + i]; }
;     };
;     auto step = [&](int kt, u32x4 (&ldset)[8], const u32x4 (&stset)[8]) {
;         const int buf = kt & 1;
;         if (kt + 2 < nk) gload(ldset, kt + 2);
;         const bf16_t* Ab = As + (buf * 128 + 64 * wr + li) * LS + 8 * lh;
;         const bf16_t* Bb = Bs + (buf * 128 + 64 * wc + li) * LS + 8 * lh;
;         bf16x8 fa[2][2], fb[2][2], ga[2][2], gb[2][2];
; #pragma unroll
;         for (int k2 = 0; k2 < 2; ++k2) { fa[k2][0] = ld8(Ab + 16 * k2); fa[k2][1] = ld8(Ab + 32 * LS + 16 * k2); fb[k2][0] = ld8(Bb + 16 * k2); fb[k2][1] = ld8(Bb + 32 * LS + 16 * k2); }
;         __builtin_amdgcn_sched_barrier(0);
; #pragma unroll
;         for (int k2 = 0; k2 < 2; ++k2) {
.Lff1_mapdone:
	v_add_u32_e32 v10, 0x100, v34
	v_add_u32_e32 v18, 0x200, v34
	v_add_u32_e32 v26, 0x300, v34
	s_lshl_b32 s38, s13, 7
	v_ashrrev_i32_e32 v35, 3, v34
	v_ashrrev_i32_e32 v36, 3, v10
	v_ashrrev_i32_e32 v37, 3, v18
	v_ashrrev_i32_e32 v38, 3, v26
	v_add_u32_e32 v0, s39, v35
	v_add_u32_e32 v6, s38, v35
	v_add_u32_e32 v10, s39, v36
	v_add_u32_e32 v14, s38, v36
	v_add_u32_e32 v18, s39, v37
	v_add_u32_e32 v22, s38, v37
	v_add_u32_e32 v26, s39, v38
	v_add_u32_e32 v30, s38, v38
	v_ashrrev_i32_e32 v1, 31, v0
	v_readlane_b32 s12, v252, 8
	v_ashrrev_i32_e32 v7, 31, v6
	v_ashrrev_i32_e32 v11, 31, v10
	v_ashrrev_i32_e32 v15, 31, v14
	v_ashrrev_i32_e32 v19, 31, v18
	v_ashrrev_i32_e32 v23, 31, v22
	v_ashrrev_i32_e32 v27, 31, v26
	v_ashrrev_i32_e32 v31, 31, v30
	v_lshlrev_b64 v[4:5], 11, v[0:1]
	v_readlane_b32 s13, v252, 9
	v_lshlrev_b32_e32 v2, 4, v34
	v_lshlrev_b64 v[6:7], 11, v[6:7]
	v_lshlrev_b64 v[10:11], 11, v[10:11]
	v_lshlrev_b64 v[14:15], 11, v[14:15]
	v_lshlrev_b64 v[18:19], 11, v[18:19]
	v_lshlrev_b64 v[22:23], 11, v[22:23]
	v_lshlrev_b64 v[26:27], 11, v[26:27]
	v_lshlrev_b64 v[30:31], 11, v[30:31]
	v_lshl_add_u64 v[0:1], s[12:13], 0, v[4:5]
	v_and_b32_e32 v2, 0x70, v2
	v_lshl_add_u64 v[8:9], s[10:11], 0, v[6:7]
	v_lshl_add_u64 v[12:13], s[12:13], 0, v[10:11]
	v_lshl_add_u64 v[16:17], s[10:11], 0, v[14:15]
	v_lshl_add_u64 v[20:21], s[12:13], 0, v[18:19]
	v_lshl_add_u64 v[24:25], s[10:11], 0, v[22:23]
	v_lshl_add_u64 v[28:29], s[12:13], 0, v[26:27]
	v_lshl_add_u64 v[32:33], s[10:11], 0, v[30:31]
	v_lshl_add_u64 v[0:1], v[0:1], 0, v[2:3]
	v_lshl_add_u64 v[8:9], v[8:9], 0, v[2:3]
	v_lshl_add_u64 v[12:13], v[12:13], 0, v[2:3]
	v_lshl_add_u64 v[16:17], v[16:17], 0, v[2:3]
	v_lshl_add_u64 v[20:21], v[20:21], 0, v[2:3]
	v_lshl_add_u64 v[24:25], v[24:25], 0, v[2:3]
	v_lshl_add_u64 v[28:29], v[28:29], 0, v[2:3]
	v_lshl_add_u64 v[32:33], v[32:33], 0, v[2:3]
	global_load_dwordx4 v[68:71], v[0:1], off
	global_load_dwordx4 v[72:75], v[8:9], off
	global_load_dwordx4 v[76:79], v[12:13], off
	global_load_dwordx4 v[80:83], v[16:17], off
	global_load_dwordx4 v[84:87], v[20:21], off
	global_load_dwordx4 v[92:95], v[24:25], off
	global_load_dwordx4 v[104:107], v[28:29], off
	global_load_dwordx4 v[112:115], v[32:33], off
	global_load_dwordx4 v[88:91], v[0:1], off offset:128
	global_load_dwordx4 v[96:99], v[8:9], off offset:128
	global_load_dwordx4 v[100:103], v[12:13], off offset:128
	global_load_dwordx4 v[108:111], v[16:17], off offset:128
	global_load_dwordx4 v[116:119], v[20:21], off offset:128
	global_load_dwordx4 v[120:123], v[24:25], off offset:128
	global_load_dwordx4 v[124:127], v[28:29], off offset:128
	global_load_dwordx4 v[128:131], v[32:33], off offset:128
	v_ashrrev_i32_e32 v0, 1, v34
	v_and_b32_e32 v151, 31, v34
	v_and_b32_e32 v193, 0xffffffc0, v0
	v_bfe_u32 v166, v34, 5, 1
	v_or_b32_e32 v0, v193, v151
	v_mul_lo_u32 v0, v0, s6
	v_lshlrev_b32_e32 v1, 4, v166
	v_add3_u32 v194, 0, v0, v1
	v_and_b32_e32 v0, 0x5f, v34
	v_mul_u32_u24_e32 v0, 0x90, v0
	v_and_b32_e32 v148, 64, v34
	v_add3_u32 v195, 0, v0, v1
	v_or_b32_e32 v0, 0x80, v151
	v_add_u32_e32 v8, v0, v193
	v_or_b32_e32 v0, v0, v148
	v_mul_u32_u24_e32 v0, 0x90, v0
	v_mul_lo_u32 v35, v35, s6
	v_mul_lo_u32 v36, v36, s6
	v_mul_lo_u32 v37, v37, s6
	v_mul_lo_u32 v38, v38, s6
	v_add3_u32 v197, 0, v0, v1
	v_add_u32_e32 v0, 0, v2
	v_mul_lo_u32 v8, v8, s6
	v_add_u32_e32 v198, v0, v35
	v_add_u32_e32 v199, v0, v36
	v_add_u32_e32 v200, v0, v37
	v_add_u32_e32 v201, v0, v38
	v_and_b32_e32 v0, 7, v34
	v_lshl_add_u64 v[144:145], s[26:27], 0, v[4:5]
	v_add3_u32 v167, 0, v35, v2
	v_add3_u32 v190, 0, v36, v2
	v_add3_u32 v191, 0, v37, v2
	v_add3_u32 v192, 0, v38, v2
	v_add3_u32 v196, 0, v8, v1
	v_lshlrev_b32_e32 v2, 4, v0
	v_lshl_add_u64 v[0:1], s[0:1], 0, v[30:31]
	v_lshl_add_u64 v[132:133], s[26:27], 0, v[26:27]
	v_lshl_add_u64 v[134:135], s[0:1], 0, v[22:23]
	v_lshl_add_u64 v[136:137], s[26:27], 0, v[18:19]
	v_lshl_add_u64 v[138:139], s[0:1], 0, v[14:15]
	v_lshl_add_u64 v[140:141], s[26:27], 0, v[10:11]
	v_lshl_add_u64 v[142:143], s[0:1], 0, v[6:7]
	s_mov_b32 s40, 0
	s_waitcnt vmcnt(33)
	s_waitcnt vmcnt(32)
	s_waitcnt vmcnt(15)
	ds_write_b128 v167, v[68:71]
	s_waitcnt vmcnt(14)
	ds_write_b128 v167, v[72:75] offset:36864
	s_waitcnt vmcnt(13)
	ds_write_b128 v190, v[76:79]
	s_waitcnt vmcnt(12)
	ds_write_b128 v190, v[80:83] offset:36864
	s_waitcnt vmcnt(11)
	ds_write_b128 v191, v[84:87]
	s_waitcnt vmcnt(10)
	ds_write_b128 v191, v[92:95] offset:36864
	s_waitcnt vmcnt(9)
	ds_write_b128 v192, v[104:107]
	s_waitcnt vmcnt(8)
	ds_write_b128 v192, v[112:115] offset:36864
	s_waitcnt lgkmcnt(0)
	s_barrier
	s_branch .LBB0_56
; #define MFMA(a, b, c) __builtin_amdgcn_mfma_f32_32x32x16_bf16((a), (b), (c), 0, 0, 0)
; template <class Epi, class ColV>
; DI void gemm_tile(const bf16_t* __restrict__ A, int lda, const bf16_t* __restrict__ Bt, int ldb, int K, int m0, int n0, unsigned char* smem, Epi epi, ColV colv, const bf16_t* __restrict__ HYT = nullptr) {
;     ...
;     auto step = [&](int kt, u32x4 (&ldset)[8], const u32x4 (&stset)[8]) {
;         const int buf = kt & 1;
;         if (kt + 2 < nk) gload(ldset, kt + 2);
;         const bf16_t* Ab = As + (buf * 128 + 64 * wr + li) * LS + 8 * lh;
;         const bf16_t* Bb = Bs + (buf * 128 + 64 * wc + li) * LS + 8 * lh;
;         bf16x8 fa[2][2], fb[2][2], ga[2][2], gb[2][2];
; #pragma unroll
;         for (int k2 = 0; k2 < 2; ++k2) { fa[k2][0] = ld8(Ab + 16 * k2); fa[k2][1] = ld8(Ab + 32 * LS + 16 * k2); fb[k2][0] = ld8(Bb + 16 * k2); fb[k2][1] = ld8(Bb + 32 * LS + 16 * k2); }
;         __builtin_amdgcn_sched_barrier(0);
; #pragma unroll
;         for (int k2 = 0; k2 < 2; ++k2) {
;             acc[0][0] = MFMA(fa[k2][0], fb[k2][0], acc[0][0]); acc[0][1] = MFMA(fa[k2][0], fb[k2][1], acc[0][1]);
;             acc[1][0] = MFMA(fa[k2][1], fb[k2][0], acc[1][0]); acc[1][1] = MFMA(fa[k2][1], fb[k2][1], acc[1][1]);
;         }
; #pragma unroll
;         for (int k2 = 0; k2 < 2; ++k2) { const int ks = 2 + k2; ga[k2][0] = ld8(Ab + 16 * ks); ga[k2][1] = ld8(Ab + 32 * LS + 16 * ks); gb[k2][0] = ld8(Bb + 16 * ks); gb[k2][1] = ld8(Bb + 32 * LS + 16 * ks); }
; #pragma unroll
;         for (int k2 = 0; k2 < 2; ++k2) {
;             acc[0][0] = MFMA(ga[k2][0], gb[k2][0], acc[0][0]); acc[0][1] = MFMA(ga[k2][0], gb[k2][1], acc[0][1]);
;             acc[1][0] = MFMA(ga[k2][1], gb[k2][0], acc[1][0]); acc[1][1] = MFMA(ga[k2][1], gb[k2][1], acc[1][1]);
;         }
;         if (kt + 1 < nk) sstore(stset, buf ^ 1, kt + 1);
; #pragma unroll
;         for (int i = 0; i < 8; ++i) { __builtin_amdgcn_sched_group_barrier(0x008, 1, 0); __builtin_amdgcn_sched_group_barrier(0x100, 1, 0); }
; #pragma unroll
;         for (int i = 0; i < 8; ++i) { __builtin_amdgcn_sched_group_barrier(0x008, 1, 0); __builtin_amdgcn_sched_group_barrier(0x200, 1, 0); }
;         __builtin_amdgcn_sched_barrier(0);
;         __syncthreads();
;     };
.LBB0_56:
	s_cmp_lt_u32 s40, 14
	s_cselect_b64 s[18:19], -1, 0
	s_cmp_gt_u32 s40, 13
	s_cselect_b64 s[12:13], -1, 0
	s_and_b64 vcc, exec, s[12:13]
	v_lshl_add_u64 v[164:165], v[144:145], 0, v[2:3]
	v_lshl_add_u64 v[162:163], v[142:143], 0, v[2:3]
	v_lshl_add_u64 v[160:161], v[140:141], 0, v[2:3]
	v_lshl_add_u64 v[158:159], v[138:139], 0, v[2:3]
	v_lshl_add_u64 v[156:157], v[136:137], 0, v[2:3]
	v_lshl_add_u64 v[154:155], v[134:135], 0, v[2:3]
	v_lshl_add_u64 v[152:153], v[132:133], 0, v[2:3]
	v_lshl_add_u64 v[146:147], v[0:1], 0, v[2:3]
	s_mov_b32 s100, 0x26ca000
	s_mov_b32 s101, 0
	v_lshl_add_u64 v[164:165], v[164:165], 0, s[100:101]
	v_lshl_add_u64 v[160:161], v[160:161], 0, s[100:101]
	v_lshl_add_u64 v[156:157], v[156:157], 0, s[100:101]
	v_lshl_add_u64 v[152:153], v[152:153], 0, s[100:101]
	s_mov_b32 s100, 0x680000
	s_mov_b32 s101, 0
	v_lshl_add_u64 v[162:163], v[162:163], 0, s[100:101]
	v_lshl_add_u64 v[158:159], v[158:159], 0, s[100:101]
	v_lshl_add_u64 v[154:155], v[154:155], 0, s[100:101]
	v_lshl_add_u64 v[146:147], v[146:147], 0, s[100:101]
	ds_read_b128 v[174:177], v194
	ds_read_b128 v[210:213], v195 offset:36864
	ds_read_b128 v[218:221], v195 offset:41472
	ds_read_b128 v[202:205], v194 offset:4608
	ds_read_b128 v[178:181], v194 offset:32
	ds_read_b128 v[222:225], v195 offset:41504
	ds_read_b128 v[206:209], v194 offset:4640
	ds_read_b128 v[214:217], v195 offset:36896
	s_waitcnt lgkmcnt(6)
	v_mfma_f32_32x32x16_bf16 v[52:67], v[174:177], v[210:213], 0
	global_load_dwordx4 v[132:135], v[164:165], off offset:256
	global_load_dwordx4 v[136:139], v[162:163], off offset:256
	s_waitcnt lgkmcnt(5)
	v_mfma_f32_32x32x16_bf16 v[36:51], v[174:177], v[218:221], 0
	global_load_dwordx4 v[140:143], v[160:161], off offset:256
	global_load_dwordx4 v[198:201], v[158:159], off offset:256
	s_waitcnt lgkmcnt(4)
	v_mfma_f32_32x32x16_bf16 v[4:19], v[202:205], v[218:221], 0
	global_load_dwordx4 v[226:229], v[156:157], off offset:256
	global_load_dwordx4 v[230:233], v[154:155], off offset:256
	s_waitcnt lgkmcnt(2)
	v_mfma_f32_32x32x16_bf16 v[36:51], v[178:181], v[222:225], v[36:51]
	global_load_dwordx4 v[242:245], v[152:153], off offset:256
	global_load_dwordx4 v[246:249], v[146:147], off offset:256
	s_waitcnt lgkmcnt(1)
	v_mfma_f32_32x32x16_bf16 v[4:19], v[206:209], v[222:225], v[4:19]
	global_load_dwordx4 v[68:71], v[164:165], off offset:384
	global_load_dwordx4 v[72:75], v[162:163], off offset:384
	ds_read_b128 v[222:225], v195 offset:41568
	ds_read_b128 v[174:177], v194 offset:4672
	v_mfma_f32_32x32x16_bf16 v[20:35], v[202:205], v[210:213], 0
	global_load_dwordx4 v[76:79], v[160:161], off offset:384
	global_load_dwordx4 v[80:83], v[158:159], off offset:384
	ds_read_b128 v[210:213], v194 offset:4704
	ds_read_b128 v[202:205], v194 offset:64
	s_waitcnt lgkmcnt(4)
	v_mfma_f32_32x32x16_bf16 v[52:67], v[178:181], v[214:217], v[52:67]
	global_load_dwordx4 v[84:87], v[156:157], off offset:384
	global_load_dwordx4 v[92:95], v[154:155], off offset:384
	ds_read_b128 v[218:221], v195 offset:36960
	ds_read_b128 v[178:181], v195 offset:41536
	v_mfma_f32_32x32x16_bf16 v[20:35], v[206:209], v[214:217], v[20:35]
	global_load_dwordx4 v[104:107], v[152:153], off offset:384
	global_load_dwordx4 v[112:115], v[146:147], off offset:384
	ds_read_b128 v[214:217], v195 offset:36928
	ds_read_b128 v[206:209], v194 offset:96
	s_waitcnt lgkmcnt(1)
	v_mfma_f32_32x32x16_bf16 v[52:67], v[202:205], v[214:217], v[52:67]
	s_waitcnt vmcnt(16)
	ds_write_b128 v167, v[88:91] offset:18432
	v_mfma_f32_32x32x16_bf16 v[36:51], v[202:205], v[178:181], v[36:51]
	ds_write_b128 v167, v[96:99] offset:55296
	v_mfma_f32_32x32x16_bf16 v[20:35], v[174:177], v[214:217], v[20:35]
	ds_write_b128 v190, v[100:103] offset:18432
	v_mfma_f32_32x32x16_bf16 v[4:19], v[174:177], v[178:181], v[4:19]
	ds_write_b128 v190, v[108:111] offset:55296
	s_waitcnt lgkmcnt(4)
	v_mfma_f32_32x32x16_bf16 v[52:67], v[206:209], v[218:221], v[52:67]
	ds_write_b128 v191, v[116:119] offset:18432
	v_mfma_f32_32x32x16_bf16 v[36:51], v[206:209], v[222:225], v[36:51]
	ds_write_b128 v191, v[120:123] offset:55296
	v_mfma_f32_32x32x16_bf16 v[20:35], v[210:213], v[218:221], v[20:35]
	ds_write_b128 v192, v[124:127] offset:18432
	v_mfma_f32_32x32x16_bf16 v[4:19], v[210:213], v[222:225], v[4:19]
	ds_write_b128 v192, v[128:131] offset:55296
	s_waitcnt lgkmcnt(0)
	s_barrier
; #define MFMA(a, b, c) __builtin_amdgcn_mfma_f32_32x32x16_bf16((a), (b), (c), 0, 0, 0)
; template <class Epi, class ColV>
; DI void gemm_tile(const bf16_t* __restrict__ A, int lda, const bf16_t* __restrict__ Bt, int ldb, int K, int m0, int n0, unsigned char* smem, Epi epi, ColV colv, const bf16_t* __restrict__ HYT = nullptr) {
;     ...
;     auto step = [&](int kt, u32x4 (&ldset)[8], const u32x4 (&stset)[8]) {
;         const int buf = kt & 1;
;         if (kt + 2 < nk) gload(ldset, kt + 2);
;         const bf16_t* Ab = As + (buf * 128 + 64 * wr + li) * LS + 8 * lh;
;         const bf16_t* Bb = Bs + (buf * 128 + 64 * wc + li) * LS + 8 * lh;
;         bf16x8 fa[2][2], fb[2][2], ga[2][2], gb[2][2];
; #pragma unroll
;         for (int k2 = 0; k2 < 2; ++k2) { fa[k2][0] = ld8(Ab + 16 * k2); fa[k2][1] = ld8(Ab + 32 * LS + 16 * k2); fb[k2][0] = ld8(Bb + 16 * k2); fb[k2][1] = ld8(Bb + 32 * LS + 16 * k2); }
;         __builtin_amdgcn_sched_barrier(0);
; #pragma unroll
;         for (int k2 = 0; k2 < 2; ++k2) {
;             acc[0][0] = MFMA(fa[k2][0], fb[k2][0], acc[0][0]); acc[0][1] = MFMA(fa[k2][0], fb[k2][1], acc[0][1]);
;             acc[1][0] = MFMA(fa[k2][1], fb[k2][0], acc[1][0]); acc[1][1] = MFMA(fa[k2][1], fb[k2][1], acc[1][1]);
;         }
; #pragma unroll
;         for (int k2 = 0; k2 < 2; ++k2) { const int ks = 2 + k2; ga[k2][0] = ld8(Ab + 16 * ks); ga[k2][1] = ld8(Ab + 32 * LS + 16 * ks); gb[k2][0] = ld8(Bb + 16 * ks); gb[k2][1] = ld8(Bb + 32 * LS + 16 * ks); }
; #pragma unroll
;         for (int k2 = 0; k2 < 2; ++k2) {
;             acc[0][0] = MFMA(ga[k2][0], gb[k2][0], acc[0][0]); acc[0][1] = MFMA(ga[k2][0], gb[k2][1], acc[0][1]);
;             acc[1][0] = MFMA(ga[k2][1], gb[k2][0], acc[1][0]); acc[1][1] = MFMA(ga[k2][1], gb[k2][1], acc[1][1]);
;         }
;         if (kt + 1 < nk) sstore(stset, buf ^ 1, kt + 1);
; #pragma unroll
;         for (int i = 0; i < 8; ++i) { __builtin_amdgcn_sched_group_barrier(0x008, 1, 0); __builtin_amdgcn_sched_group_barrier(0x100, 1, 0); }
; #pragma unroll
;         for (int i = 0; i < 8; ++i) { __builtin_amdgcn_sched_group_barrier(0x008, 1, 0); __builtin_amdgcn_sched_group_barrier(0x200, 1, 0); }
;         __builtin_amdgcn_sched_barrier(0);
;         __syncthreads();
	ds_read_b128 v[174:177], v196
	ds_read_b128 v[210:213], v197 offset:36864
	ds_read_b128 v[218:221], v197 offset:41472
	ds_read_b128 v[202:205], v196 offset:4608
	ds_read_b128 v[178:181], v196 offset:32
	ds_read_b128 v[222:225], v197 offset:41504
	ds_read_b128 v[206:209], v196 offset:4640
	ds_read_b128 v[214:217], v197 offset:36896
	s_waitcnt lgkmcnt(6)
	v_mfma_f32_32x32x16_bf16 v[52:67], v[174:177], v[210:213], v[52:67]
	global_load_dwordx4 v[88:91], v[164:165], off offset:512
	s_waitcnt lgkmcnt(5)
	v_mfma_f32_32x32x16_bf16 v[36:51], v[174:177], v[218:221], v[36:51]
	global_load_dwordx4 v[96:99], v[162:163], off offset:512
	s_waitcnt lgkmcnt(4)
	v_mfma_f32_32x32x16_bf16 v[4:19], v[202:205], v[218:221], v[4:19]
	global_load_dwordx4 v[100:103], v[160:161], off offset:512
	s_waitcnt lgkmcnt(2)
	v_mfma_f32_32x32x16_bf16 v[36:51], v[178:181], v[222:225], v[36:51]
	global_load_dwordx4 v[108:111], v[158:159], off offset:512
	s_waitcnt lgkmcnt(1)
	v_mfma_f32_32x32x16_bf16 v[4:19], v[206:209], v[222:225], v[4:19]
	global_load_dwordx4 v[116:119], v[156:157], off offset:512
	ds_read_b128 v[222:225], v197 offset:41568
	ds_read_b128 v[174:177], v196 offset:4672
	v_mfma_f32_32x32x16_bf16 v[20:35], v[202:205], v[210:213], v[20:35]
	global_load_dwordx4 v[120:123], v[154:155], off offset:512
	ds_read_b128 v[210:213], v196 offset:4704
	ds_read_b128 v[202:205], v196 offset:64
	s_waitcnt lgkmcnt(4)
	v_mfma_f32_32x32x16_bf16 v[52:67], v[178:181], v[214:217], v[52:67]
	global_load_dwordx4 v[124:127], v[152:153], off offset:512
	ds_read_b128 v[218:221], v197 offset:36960
	ds_read_b128 v[178:181], v197 offset:41536
	v_mfma_f32_32x32x16_bf16 v[20:35], v[206:209], v[214:217], v[20:35]
	global_load_dwordx4 v[128:131], v[146:147], off offset:512
	ds_read_b128 v[214:217], v197 offset:36928
	ds_read_b128 v[206:209], v196 offset:96
	s_waitcnt lgkmcnt(1)
	v_mfma_f32_32x32x16_bf16 v[52:67], v[202:205], v[214:217], v[52:67]
	s_waitcnt vmcnt(23)
	ds_write_b128 v167, v[132:135]
	v_mfma_f32_32x32x16_bf16 v[36:51], v[202:205], v[178:181], v[36:51]
	s_waitcnt vmcnt(22)
	ds_write_b128 v167, v[136:139] offset:36864
	v_mfma_f32_32x32x16_bf16 v[20:35], v[174:177], v[214:217], v[20:35]
	s_waitcnt vmcnt(21)
	ds_write_b128 v190, v[140:143]
	v_mfma_f32_32x32x16_bf16 v[4:19], v[174:177], v[178:181], v[4:19]
	s_waitcnt vmcnt(20)
	ds_write_b128 v190, v[198:201] offset:36864
	s_waitcnt lgkmcnt(4)
	v_mfma_f32_32x32x16_bf16 v[52:67], v[206:209], v[218:221], v[52:67]
	s_waitcnt vmcnt(19)
	ds_write_b128 v191, v[226:229]
	v_mfma_f32_32x32x16_bf16 v[36:51], v[206:209], v[222:225], v[36:51]
	s_waitcnt vmcnt(18)
	ds_write_b128 v191, v[230:233] offset:36864
	v_mfma_f32_32x32x16_bf16 v[20:35], v[210:213], v[218:221], v[20:35]
	s_waitcnt vmcnt(17)
	ds_write_b128 v192, v[242:245]
	v_mfma_f32_32x32x16_bf16 v[4:19], v[210:213], v[222:225], v[4:19]
	s_waitcnt vmcnt(16)
	ds_write_b128 v192, v[246:249] offset:36864
	s_waitcnt lgkmcnt(0)
	s_barrier
	ds_read_b128 v[174:177], v194
	ds_read_b128 v[210:213], v195 offset:36864
	ds_read_b128 v[218:221], v195 offset:41472
	ds_read_b128 v[202:205], v194 offset:4608
	ds_read_b128 v[178:181], v194 offset:32
	ds_read_b128 v[222:225], v195 offset:41504
	ds_read_b128 v[206:209], v194 offset:4640
	ds_read_b128 v[214:217], v195 offset:36896
	s_waitcnt lgkmcnt(6)
	v_mfma_f32_32x32x16_bf16 v[52:67], v[174:177], v[210:213], v[52:67]
	global_load_dwordx4 v[132:135], v[164:165], off offset:640
	s_waitcnt lgkmcnt(5)
	v_mfma_f32_32x32x16_bf16 v[36:51], v[174:177], v[218:221], v[36:51]
	global_load_dwordx4 v[136:139], v[162:163], off offset:640
	s_waitcnt lgkmcnt(4)
	v_mfma_f32_32x32x16_bf16 v[4:19], v[202:205], v[218:221], v[4:19]
	global_load_dwordx4 v[140:143], v[160:161], off offset:640
	s_waitcnt lgkmcnt(2)
	v_mfma_f32_32x32x16_bf16 v[36:51], v[178:181], v[222:225], v[36:51]
	global_load_dwordx4 v[198:201], v[158:159], off offset:640
	s_waitcnt lgkmcnt(1)
	v_mfma_f32_32x32x16_bf16 v[4:19], v[206:209], v[222:225], v[4:19]
	global_load_dwordx4 v[226:229], v[156:157], off offset:640
	ds_read_b128 v[222:225], v195 offset:41568
	ds_read_b128 v[174:177], v194 offset:4672
	v_mfma_f32_32x32x16_bf16 v[20:35], v[202:205], v[210:213], v[20:35]
	global_load_dwordx4 v[230:233], v[154:155], off offset:640
	ds_read_b128 v[210:213], v194 offset:4704
	ds_read_b128 v[202:205], v194 offset:64
	s_waitcnt lgkmcnt(4)
	v_mfma_f32_32x32x16_bf16 v[52:67], v[178:181], v[214:217], v[52:67]
	global_load_dwordx4 v[242:245], v[152:153], off offset:640
	ds_read_b128 v[218:221], v195 offset:36960
	ds_read_b128 v[178:181], v195 offset:41536
	v_mfma_f32_32x32x16_bf16 v[20:35], v[206:209], v[214:217], v[20:35]
	global_load_dwordx4 v[246:249], v[146:147], off offset:640
	ds_read_b128 v[214:217], v195 offset:36928
	ds_read_b128 v[206:209], v194 offset:96
	s_waitcnt lgkmcnt(1)
	v_mfma_f32_32x32x16_bf16 v[52:67], v[202:205], v[214:217], v[52:67]
	s_waitcnt vmcnt(23)
	ds_write_b128 v167, v[68:71] offset:18432
	v_mfma_f32_32x32x16_bf16 v[36:51], v[202:205], v[178:181], v[36:51]
	s_waitcnt vmcnt(22)
	ds_write_b128 v167, v[72:75] offset:55296
	v_mfma_f32_32x32x16_bf16 v[20:35], v[174:177], v[214:217], v[20:35]
	s_waitcnt vmcnt(21)
	ds_write_b128 v190, v[76:79] offset:18432
	v_mfma_f32_32x32x16_bf16 v[4:19], v[174:177], v[178:181], v[4:19]
	s_waitcnt vmcnt(20)
	ds_write_b128 v190, v[80:83] offset:55296
	s_waitcnt lgkmcnt(4)
	v_mfma_f32_32x32x16_bf16 v[52:67], v[206:209], v[218:221], v[52:67]
	s_waitcnt vmcnt(19)
	ds_write_b128 v191, v[84:87] offset:18432
	v_mfma_f32_32x32x16_bf16 v[36:51], v[206:209], v[222:225], v[36:51]
	s_waitcnt vmcnt(18)
	ds_write_b128 v191, v[92:95] offset:55296
	v_mfma_f32_32x32x16_bf16 v[20:35], v[210:213], v[218:221], v[20:35]
	s_waitcnt vmcnt(17)
	ds_write_b128 v192, v[104:107] offset:18432
	v_mfma_f32_32x32x16_bf16 v[4:19], v[210:213], v[222:225], v[4:19]
	s_waitcnt vmcnt(16)
	ds_write_b128 v192, v[112:115] offset:55296
	s_waitcnt lgkmcnt(0)
	s_barrier
; #define MFMA(a, b, c) __builtin_amdgcn_mfma_f32_32x32x16_bf16((a), (b), (c), 0, 0, 0)
; template <class Epi, class ColV>
; DI void gemm_tile(const bf16_t* __restrict__ A, int lda, const bf16_t* __restrict__ Bt, int ldb, int K, int m0, int n0, unsigned char* smem, Epi epi, ColV colv, const bf16_t* __restrict__ HYT = nullptr) {
;     ...
;     auto step = [&](int kt, u32x4 (&ldset)[8], const u32x4 (&stset)[8]) {
;         const int buf = kt & 1;
;         if (kt + 2 < nk) gload(ldset, kt + 2);
;         const bf16_t* Ab = As + (buf * 128 + 64 * wr + li) * LS + 8 * lh;
;         const bf16_t* Bb = Bs + (buf * 128 + 64 * wc + li) * LS + 8 * lh;
;         bf16x8 fa[2][2], fb[2][2], ga[2][2], gb[2][2];
; #pragma unroll
;         for (int k2 = 0; k2 < 2; ++k2) { fa[k2][0] = ld8(Ab + 16 * k2); fa[k2][1] = ld8(Ab + 32 * LS + 16 * k2); fb[k2][0] = ld8(Bb + 16 * k2); fb[k2][1] = ld8(Bb + 32 * LS + 16 * k2); }
;         __builtin_amdgcn_sched_barrier(0);
; #pragma unroll
;         for (int k2 = 0; k2 < 2; ++k2) {
;             acc[0][0] = MFMA(fa[k2][0], fb[k2][0], acc[0][0]); acc[0][1] = MFMA(fa[k2][0], fb[k2][1], acc[0][1]);
;             acc[1][0] = MFMA(fa[k2][1], fb[k2][0], acc[1][0]); acc[1][1] = MFMA(fa[k2][1], fb[k2][1], acc[1][1]);
;         }
; #pragma unroll
;         for (int k2 = 0; k2 < 2; ++k2) { const int ks = 2 + k2; ga[k2][0] = ld8(Ab + 16 * ks); ga[k2][1] = ld8(Ab + 32 * LS + 16 * ks); gb[k2][0] = ld8(Bb + 16 * ks); gb[k2][1] = ld8(Bb + 32 * LS + 16 * ks); }
; #pragma unroll
;         for (int k2 = 0; k2 < 2; ++k2) {
;             acc[0][0] = MFMA(ga[k2][0], gb[k2][0], acc[0][0]); acc[0][1] = MFMA(ga[k2][0], gb[k2][1], acc[0][1]);
;             acc[1][0] = MFMA(ga[k2][1], gb[k2][0], acc[1][0]); acc[1][1] = MFMA(ga[k2][1], gb[k2][1], acc[1][1]);
;         }
;         if (kt + 1 < nk) sstore(stset, buf ^ 1, kt + 1);
; #pragma unroll
;         for (int i = 0; i < 8; ++i) { __builtin_amdgcn_sched_group_barrier(0x008, 1, 0); __builtin_amdgcn_sched_group_barrier(0x100, 1, 0); }
; #pragma unroll
;         for (int i = 0; i < 8; ++i) { __builtin_amdgcn_sched_group_barrier(0x008, 1, 0); __builtin_amdgcn_sched_group_barrier(0x200, 1, 0); }
;         __builtin_amdgcn_sched_barrier(0);
;         __syncthreads();
	ds_read_b128 v[174:177], v196
	ds_read_b128 v[210:213], v197 offset:36864
	ds_read_b128 v[218:221], v197 offset:41472
	ds_read_b128 v[202:205], v196 offset:4608
	ds_read_b128 v[178:181], v196 offset:32
	ds_read_b128 v[222:225], v197 offset:41504
	ds_read_b128 v[206:209], v196 offset:4640
	ds_read_b128 v[214:217], v197 offset:36896
	s_waitcnt lgkmcnt(6)
	v_mfma_f32_32x32x16_bf16 v[52:67], v[174:177], v[210:213], v[52:67]
	global_load_dwordx4 v[68:71], v[164:165], off offset:768
	s_waitcnt lgkmcnt(5)
	v_mfma_f32_32x32x16_bf16 v[36:51], v[174:177], v[218:221], v[36:51]
	global_load_dwordx4 v[72:75], v[162:163], off offset:768
	s_waitcnt lgkmcnt(4)
	v_mfma_f32_32x32x16_bf16 v[4:19], v[202:205], v[218:221], v[4:19]
	global_load_dwordx4 v[76:79], v[160:161], off offset:768
	s_waitcnt lgkmcnt(2)
	v_mfma_f32_32x32x16_bf16 v[36:51], v[178:181], v[222:225], v[36:51]
	global_load_dwordx4 v[80:83], v[158:159], off offset:768
	s_waitcnt lgkmcnt(1)
	v_mfma_f32_32x32x16_bf16 v[4:19], v[206:209], v[222:225], v[4:19]
	global_load_dwordx4 v[84:87], v[156:157], off offset:768
	ds_read_b128 v[222:225], v197 offset:41568
	ds_read_b128 v[174:177], v196 offset:4672
	v_mfma_f32_32x32x16_bf16 v[20:35], v[202:205], v[210:213], v[20:35]
	global_load_dwordx4 v[92:95], v[154:155], off offset:768
	ds_read_b128 v[210:213], v196 offset:4704
	ds_read_b128 v[202:205], v196 offset:64
	s_waitcnt lgkmcnt(4)
	v_mfma_f32_32x32x16_bf16 v[52:67], v[178:181], v[214:217], v[52:67]
	global_load_dwordx4 v[104:107], v[152:153], off offset:768
	ds_read_b128 v[218:221], v197 offset:36960
	ds_read_b128 v[178:181], v197 offset:41536
	v_mfma_f32_32x32x16_bf16 v[20:35], v[206:209], v[214:217], v[20:35]
	global_load_dwordx4 v[112:115], v[146:147], off offset:768
	ds_read_b128 v[214:217], v197 offset:36928
	ds_read_b128 v[206:209], v196 offset:96
	s_waitcnt lgkmcnt(1)
	v_mfma_f32_32x32x16_bf16 v[52:67], v[202:205], v[214:217], v[52:67]
	s_waitcnt vmcnt(23)
	ds_write_b128 v167, v[88:91]
	v_mfma_f32_32x32x16_bf16 v[36:51], v[202:205], v[178:181], v[36:51]
	s_waitcnt vmcnt(22)
	ds_write_b128 v167, v[96:99] offset:36864
	v_mfma_f32_32x32x16_bf16 v[20:35], v[174:177], v[214:217], v[20:35]
	s_waitcnt vmcnt(21)
	ds_write_b128 v190, v[100:103]
	v_mfma_f32_32x32x16_bf16 v[4:19], v[174:177], v[178:181], v[4:19]
	s_waitcnt vmcnt(20)
	ds_write_b128 v190, v[108:111] offset:36864
	s_waitcnt lgkmcnt(4)
	v_mfma_f32_32x32x16_bf16 v[52:67], v[206:209], v[218:221], v[52:67]
	s_waitcnt vmcnt(19)
	ds_write_b128 v191, v[116:119]
	v_mfma_f32_32x32x16_bf16 v[36:51], v[206:209], v[222:225], v[36:51]
	s_waitcnt vmcnt(18)
	ds_write_b128 v191, v[120:123] offset:36864
	v_mfma_f32_32x32x16_bf16 v[20:35], v[210:213], v[218:221], v[20:35]
	s_waitcnt vmcnt(17)
	ds_write_b128 v192, v[124:127]
	v_mfma_f32_32x32x16_bf16 v[4:19], v[210:213], v[222:225], v[4:19]
	s_waitcnt vmcnt(16)
	ds_write_b128 v192, v[128:131] offset:36864
	s_waitcnt lgkmcnt(0)
	s_barrier
	ds_read_b128 v[174:177], v194
	ds_read_b128 v[210:213], v195 offset:36864
	ds_read_b128 v[218:221], v195 offset:41472
	ds_read_b128 v[202:205], v194 offset:4608
	ds_read_b128 v[178:181], v194 offset:32
	ds_read_b128 v[222:225], v195 offset:41504
	ds_read_b128 v[206:209], v194 offset:4640
	ds_read_b128 v[214:217], v195 offset:36896
	s_waitcnt lgkmcnt(6)
	v_mfma_f32_32x32x16_bf16 v[52:67], v[174:177], v[210:213], v[52:67]
	global_load_dwordx4 v[88:91], v[164:165], off offset:896
	s_waitcnt lgkmcnt(5)
	v_mfma_f32_32x32x16_bf16 v[36:51], v[174:177], v[218:221], v[36:51]
	global_load_dwordx4 v[96:99], v[162:163], off offset:896
	s_waitcnt lgkmcnt(4)
	v_mfma_f32_32x32x16_bf16 v[4:19], v[202:205], v[218:221], v[4:19]
	global_load_dwordx4 v[100:103], v[160:161], off offset:896
	s_waitcnt lgkmcnt(2)
	v_mfma_f32_32x32x16_bf16 v[36:51], v[178:181], v[222:225], v[36:51]
	global_load_dwordx4 v[108:111], v[158:159], off offset:896
	s_waitcnt lgkmcnt(1)
	v_mfma_f32_32x32x16_bf16 v[4:19], v[206:209], v[222:225], v[4:19]
	global_load_dwordx4 v[116:119], v[156:157], off offset:896
	ds_read_b128 v[222:225], v195 offset:41568
	ds_read_b128 v[174:177], v194 offset:4672
	v_mfma_f32_32x32x16_bf16 v[20:35], v[202:205], v[210:213], v[20:35]
	global_load_dwordx4 v[120:123], v[154:155], off offset:896
	ds_read_b128 v[210:213], v194 offset:4704
	ds_read_b128 v[202:205], v194 offset:64
	s_waitcnt lgkmcnt(4)
	v_mfma_f32_32x32x16_bf16 v[52:67], v[178:181], v[214:217], v[52:67]
	global_load_dwordx4 v[124:127], v[152:153], off offset:896
	ds_read_b128 v[218:221], v195 offset:36960
	ds_read_b128 v[178:181], v195 offset:41536
	v_mfma_f32_32x32x16_bf16 v[20:35], v[206:209], v[214:217], v[20:35]
	global_load_dwordx4 v[128:131], v[146:147], off offset:896
	ds_read_b128 v[214:217], v195 offset:36928
	ds_read_b128 v[206:209], v194 offset:96
	s_waitcnt lgkmcnt(1)
	v_mfma_f32_32x32x16_bf16 v[52:67], v[202:205], v[214:217], v[52:67]
	s_waitcnt vmcnt(23)
	ds_write_b128 v167, v[132:135] offset:18432
	v_mfma_f32_32x32x16_bf16 v[36:51], v[202:205], v[178:181], v[36:51]
	s_waitcnt vmcnt(22)
	ds_write_b128 v167, v[136:139] offset:55296
	v_mfma_f32_32x32x16_bf16 v[20:35], v[174:177], v[214:217], v[20:35]
	s_waitcnt vmcnt(21)
	ds_write_b128 v190, v[140:143] offset:18432
	v_mfma_f32_32x32x16_bf16 v[4:19], v[174:177], v[178:181], v[4:19]
	s_waitcnt vmcnt(20)
	ds_write_b128 v190, v[198:201] offset:55296
	s_waitcnt lgkmcnt(4)
	v_mfma_f32_32x32x16_bf16 v[52:67], v[206:209], v[218:221], v[52:67]
	s_waitcnt vmcnt(19)
	ds_write_b128 v191, v[226:229] offset:18432
	v_mfma_f32_32x32x16_bf16 v[36:51], v[206:209], v[222:225], v[36:51]
	s_waitcnt vmcnt(18)
	ds_write_b128 v191, v[230:233] offset:55296
	v_mfma_f32_32x32x16_bf16 v[20:35], v[210:213], v[218:221], v[20:35]
	s_waitcnt vmcnt(17)
	ds_write_b128 v192, v[242:245] offset:18432
	v_mfma_f32_32x32x16_bf16 v[4:19], v[210:213], v[222:225], v[4:19]
	s_waitcnt vmcnt(16)
	ds_write_b128 v192, v[246:249] offset:55296
	s_waitcnt lgkmcnt(0)
	s_barrier
; #define MFMA(a, b, c) __builtin_amdgcn_mfma_f32_32x32x16_bf16((a), (b), (c), 0, 0, 0)
; template <class Epi, class ColV>
; DI void gemm_tile(const bf16_t* __restrict__ A, int lda, const bf16_t* __restrict__ Bt, int ldb, int K, int m0, int n0, unsigned char* smem, Epi epi, ColV colv, const bf16_t* __restrict__ HYT = nullptr) {
;     ...
;     auto step = [&](int kt, u32x4 (&ldset)[8], const u32x4 (&stset)[8]) {
;         const int buf = kt & 1;
;         if (kt + 2 < nk) gload(ldset, kt + 2);
;         const bf16_t* Ab = As + (buf * 128 + 64 * wr + li) * LS + 8 * lh;
;         const bf16_t* Bb = Bs + (buf * 128 + 64 * wc + li) * LS + 8 * lh;
;         bf16x8 fa[2][2], fb[2][2], ga[2][2], gb[2][2];
; #pragma unroll
;         for (int k2 = 0; k2 < 2; ++k2) { fa[k2][0] = ld8(Ab + 16 * k2); fa[k2][1] = ld8(Ab + 32 * LS + 16 * k2); fb[k2][0] = ld8(Bb + 16 * k2); fb[k2][1] = ld8(Bb + 32 * LS + 16 * k2); }
;         __builtin_amdgcn_sched_barrier(0);
; #pragma unroll
;         for (int k2 = 0; k2 < 2; ++k2) {
;             acc[0][0] = MFMA(fa[k2][0], fb[k2][0], acc[0][0]); acc[0][1] = MFMA(fa[k2][0], fb[k2][1], acc[0][1]);
;             acc[1][0] = MFMA(fa[k2][1], fb[k2][0], acc[1][0]); acc[1][1] = MFMA(fa[k2][1], fb[k2][1], acc[1][1]);
;         }
; #pragma unroll
;         for (int k2 = 0; k2 < 2; ++k2) { const int ks = 2 + k2; ga[k2][0] = ld8(Ab + 16 * ks); ga[k2][1] = ld8(Ab + 32 * LS + 16 * ks); gb[k2][0] = ld8(Bb + 16 * ks); gb[k2][1] = ld8(Bb + 32 * LS + 16 * ks); }
; #pragma unroll
;         for (int k2 = 0; k2 < 2; ++k2) {
;             acc[0][0] = MFMA(ga[k2][0], gb[k2][0], acc[0][0]); acc[0][1] = MFMA(ga[k2][0], gb[k2][1], acc[0][1]);
;             acc[1][0] = MFMA(ga[k2][1], gb[k2][0], acc[1][0]); acc[1][1] = MFMA(ga[k2][1], gb[k2][1], acc[1][1]);
;         }
;         if (kt + 1 < nk) sstore(stset, buf ^ 1, kt + 1);
; #pragma unroll
;         for (int i = 0; i < 8; ++i) { __builtin_amdgcn_sched_group_barrier(0x008, 1, 0); __builtin_amdgcn_sched_group_barrier(0x100, 1, 0); }
; #pragma unroll
;         for (int i = 0; i < 8; ++i) { __builtin_amdgcn_sched_group_barrier(0x008, 1, 0); __builtin_amdgcn_sched_group_barrier(0x200, 1, 0); }
;         __builtin_amdgcn_sched_barrier(0);
;         __syncthreads();
	ds_read_b128 v[174:177], v196
	ds_read_b128 v[210:213], v197 offset:36864
	ds_read_b128 v[218:221], v197 offset:41472
	ds_read_b128 v[202:205], v196 offset:4608
	ds_read_b128 v[178:181], v196 offset:32
	ds_read_b128 v[222:225], v197 offset:41504
	ds_read_b128 v[206:209], v196 offset:4640
	ds_read_b128 v[214:217], v197 offset:36896
	s_waitcnt lgkmcnt(6)
	v_mfma_f32_32x32x16_bf16 v[52:67], v[174:177], v[210:213], v[52:67]
	global_load_dwordx4 v[132:135], v[164:165], off offset:1024
	s_waitcnt lgkmcnt(5)
	v_mfma_f32_32x32x16_bf16 v[36:51], v[174:177], v[218:221], v[36:51]
	global_load_dwordx4 v[136:139], v[162:163], off offset:1024
	s_waitcnt lgkmcnt(4)
	v_mfma_f32_32x32x16_bf16 v[4:19], v[202:205], v[218:221], v[4:19]
	global_load_dwordx4 v[140:143], v[160:161], off offset:1024
	s_waitcnt lgkmcnt(2)
	v_mfma_f32_32x32x16_bf16 v[36:51], v[178:181], v[222:225], v[36:51]
	global_load_dwordx4 v[198:201], v[158:159], off offset:1024
	s_waitcnt lgkmcnt(1)
	v_mfma_f32_32x32x16_bf16 v[4:19], v[206:209], v[222:225], v[4:19]
	global_load_dwordx4 v[226:229], v[156:157], off offset:1024
	ds_read_b128 v[222:225], v197 offset:41568
	ds_read_b128 v[174:177], v196 offset:4672
	v_mfma_f32_32x32x16_bf16 v[20:35], v[202:205], v[210:213], v[20:35]
	global_load_dwordx4 v[230:233], v[154:155], off offset:1024
	ds_read_b128 v[210:213], v196 offset:4704
	ds_read_b128 v[202:205], v196 offset:64
	s_waitcnt lgkmcnt(4)
	v_mfma_f32_32x32x16_bf16 v[52:67], v[178:181], v[214:217], v[52:67]
	global_load_dwordx4 v[242:245], v[152:153], off offset:1024
	ds_read_b128 v[218:221], v197 offset:36960
	ds_read_b128 v[178:181], v197 offset:41536
	v_mfma_f32_32x32x16_bf16 v[20:35], v[206:209], v[214:217], v[20:35]
	global_load_dwordx4 v[246:249], v[146:147], off offset:1024
	ds_read_b128 v[214:217], v197 offset:36928
	ds_read_b128 v[206:209], v196 offset:96
	s_waitcnt lgkmcnt(1)
	v_mfma_f32_32x32x16_bf16 v[52:67], v[202:205], v[214:217], v[52:67]
	s_waitcnt vmcnt(23)
	ds_write_b128 v167, v[68:71]
	v_mfma_f32_32x32x16_bf16 v[36:51], v[202:205], v[178:181], v[36:51]
	s_waitcnt vmcnt(22)
	ds_write_b128 v167, v[72:75] offset:36864
	v_mfma_f32_32x32x16_bf16 v[20:35], v[174:177], v[214:217], v[20:35]
	s_waitcnt vmcnt(21)
	ds_write_b128 v190, v[76:79]
	v_mfma_f32_32x32x16_bf16 v[4:19], v[174:177], v[178:181], v[4:19]
	s_waitcnt vmcnt(20)
	ds_write_b128 v190, v[80:83] offset:36864
	s_waitcnt lgkmcnt(4)
	v_mfma_f32_32x32x16_bf16 v[52:67], v[206:209], v[218:221], v[52:67]
	s_waitcnt vmcnt(19)
	ds_write_b128 v191, v[84:87]
	v_mfma_f32_32x32x16_bf16 v[36:51], v[206:209], v[222:225], v[36:51]
	s_waitcnt vmcnt(18)
	ds_write_b128 v191, v[92:95] offset:36864
	v_mfma_f32_32x32x16_bf16 v[20:35], v[210:213], v[218:221], v[20:35]
	s_waitcnt vmcnt(17)
	ds_write_b128 v192, v[104:107]
	v_mfma_f32_32x32x16_bf16 v[4:19], v[210:213], v[222:225], v[4:19]
	s_waitcnt vmcnt(16)
	ds_write_b128 v192, v[112:115] offset:36864
	s_waitcnt lgkmcnt(0)
	s_barrier
	ds_read_b128 v[174:177], v194
	ds_read_b128 v[210:213], v195 offset:36864
	ds_read_b128 v[218:221], v195 offset:41472
	ds_read_b128 v[202:205], v194 offset:4608
	ds_read_b128 v[178:181], v194 offset:32
	ds_read_b128 v[222:225], v195 offset:41504
	ds_read_b128 v[206:209], v194 offset:4640
	ds_read_b128 v[214:217], v195 offset:36896
	s_waitcnt lgkmcnt(6)
	v_mfma_f32_32x32x16_bf16 v[52:67], v[174:177], v[210:213], v[52:67]
	global_load_dwordx4 v[68:71], v[164:165], off offset:1152
	s_waitcnt lgkmcnt(5)
	v_mfma_f32_32x32x16_bf16 v[36:51], v[174:177], v[218:221], v[36:51]
	global_load_dwordx4 v[72:75], v[162:163], off offset:1152
	s_waitcnt lgkmcnt(4)
	v_mfma_f32_32x32x16_bf16 v[4:19], v[202:205], v[218:221], v[4:19]
	global_load_dwordx4 v[76:79], v[160:161], off offset:1152
	s_waitcnt lgkmcnt(2)
	v_mfma_f32_32x32x16_bf16 v[36:51], v[178:181], v[222:225], v[36:51]
	global_load_dwordx4 v[80:83], v[158:159], off offset:1152
	s_waitcnt lgkmcnt(1)
	v_mfma_f32_32x32x16_bf16 v[4:19], v[206:209], v[222:225], v[4:19]
	global_load_dwordx4 v[84:87], v[156:157], off offset:1152
	ds_read_b128 v[222:225], v195 offset:41568
	ds_read_b128 v[174:177], v194 offset:4672
	v_mfma_f32_32x32x16_bf16 v[20:35], v[202:205], v[210:213], v[20:35]
	global_load_dwordx4 v[92:95], v[154:155], off offset:1152
	ds_read_b128 v[210:213], v194 offset:4704
	ds_read_b128 v[202:205], v194 offset:64
	s_waitcnt lgkmcnt(4)
	v_mfma_f32_32x32x16_bf16 v[52:67], v[178:181], v[214:217], v[52:67]
	global_load_dwordx4 v[104:107], v[152:153], off offset:1152
	ds_read_b128 v[218:221], v195 offset:36960
	ds_read_b128 v[178:181], v195 offset:41536
	v_mfma_f32_32x32x16_bf16 v[20:35], v[206:209], v[214:217], v[20:35]
	global_load_dwordx4 v[112:115], v[146:147], off offset:1152
	ds_read_b128 v[214:217], v195 offset:36928
	ds_read_b128 v[206:209], v194 offset:96
	s_waitcnt lgkmcnt(1)
	v_mfma_f32_32x32x16_bf16 v[52:67], v[202:205], v[214:217], v[52:67]
	s_waitcnt vmcnt(23)
	ds_write_b128 v167, v[88:91] offset:18432
	v_mfma_f32_32x32x16_bf16 v[36:51], v[202:205], v[178:181], v[36:51]
	s_waitcnt vmcnt(22)
	ds_write_b128 v167, v[96:99] offset:55296
	v_mfma_f32_32x32x16_bf16 v[20:35], v[174:177], v[214:217], v[20:35]
	s_waitcnt vmcnt(21)
	ds_write_b128 v190, v[100:103] offset:18432
	v_mfma_f32_32x32x16_bf16 v[4:19], v[174:177], v[178:181], v[4:19]
	s_waitcnt vmcnt(20)
	ds_write_b128 v190, v[108:111] offset:55296
	s_waitcnt lgkmcnt(4)
	v_mfma_f32_32x32x16_bf16 v[52:67], v[206:209], v[218:221], v[52:67]
	s_waitcnt vmcnt(19)
	ds_write_b128 v191, v[116:119] offset:18432
	v_mfma_f32_32x32x16_bf16 v[36:51], v[206:209], v[222:225], v[36:51]
	s_waitcnt vmcnt(18)
	ds_write_b128 v191, v[120:123] offset:55296
	v_mfma_f32_32x32x16_bf16 v[20:35], v[210:213], v[218:221], v[20:35]
	s_waitcnt vmcnt(17)
	ds_write_b128 v192, v[124:127] offset:18432
	v_mfma_f32_32x32x16_bf16 v[4:19], v[210:213], v[222:225], v[4:19]
	s_waitcnt vmcnt(16)
	ds_write_b128 v192, v[128:131] offset:55296
	s_waitcnt lgkmcnt(0)
	s_barrier
; #define MFMA(a, b, c) __builtin_amdgcn_mfma_f32_32x32x16_bf16((a), (b), (c), 0, 0, 0)
; template <class Epi, class ColV>
; DI void gemm_tile(const bf16_t* __restrict__ A, int lda, const bf16_t* __restrict__ Bt, int ldb, int K, int m0, int n0, unsigned char* smem, Epi epi, ColV colv, const bf16_t* __restrict__ HYT = nullptr) {
;     ...
;     auto step = [&](int kt, u32x4 (&ldset)[8], const u32x4 (&stset)[8]) {
;         const int buf = kt & 1;
;         if (kt + 2 < nk) gload(ldset, kt + 2);
;         const bf16_t* Ab = As + (buf * 128 + 64 * wr + li) * LS + 8 * lh;
;         const bf16_t* Bb = Bs + (buf * 128 + 64 * wc + li) * LS + 8 * lh;
;         bf16x8 fa[2][2], fb[2][2], ga[2][2], gb[2][2];
; #pragma unroll
;         for (int k2 = 0; k2 < 2; ++k2) { fa[k2][0] = ld8(Ab + 16 * k2); fa[k2][1] = ld8(Ab + 32 * LS + 16 * k2); fb[k2][0] = ld8(Bb + 16 * k2); fb[k2][1] = ld8(Bb + 32 * LS + 16 * k2); }
;         __builtin_amdgcn_sched_barrier(0);
; #pragma unroll
;         for (int k2 = 0; k2 < 2; ++k2) {
;             acc[0][0] = MFMA(fa[k2][0], fb[k2][0], acc[0][0]); acc[0][1] = MFMA(fa[k2][0], fb[k2][1], acc[0][1]);
;             acc[1][0] = MFMA(fa[k2][1], fb[k2][0], acc[1][0]); acc[1][1] = MFMA(fa[k2][1], fb[k2][1], acc[1][1]);
;         }
; #pragma unroll
;         for (int k2 = 0; k2 < 2; ++k2) { const int ks = 2 + k2; ga[k2][0] = ld8(Ab + 16 * ks); ga[k2][1] = ld8(Ab + 32 * LS + 16 * ks); gb[k2][0] = ld8(Bb + 16 * ks); gb[k2][1] = ld8(Bb + 32 * LS + 16 * ks); }
; #pragma unroll
;         for (int k2 = 0; k2 < 2; ++k2) {
;             acc[0][0] = MFMA(ga[k2][0], gb[k2][0], acc[0][0]); acc[0][1] = MFMA(ga[k2][0], gb[k2][1], acc[0][1]);
;             acc[1][0] = MFMA(ga[k2][1], gb[k2][0], acc[1][0]); acc[1][1] = MFMA(ga[k2][1], gb[k2][1], acc[1][1]);
;         }
;         if (kt + 1 < nk) sstore(stset, buf ^ 1, kt + 1);
; #pragma unroll
;         for (int i = 0; i < 8; ++i) { __builtin_amdgcn_sched_group_barrier(0x008, 1, 0); __builtin_amdgcn_sched_group_barrier(0x100, 1, 0); }
; #pragma unroll
;         for (int i = 0; i < 8; ++i) { __builtin_amdgcn_sched_group_barrier(0x008, 1, 0); __builtin_amdgcn_sched_group_barrier(0x200, 1, 0); }
;         __builtin_amdgcn_sched_barrier(0);
;         __syncthreads();
	ds_read_b128 v[174:177], v196
	ds_read_b128 v[210:213], v197 offset:36864
	ds_read_b128 v[218:221], v197 offset:41472
	ds_read_b128 v[202:205], v196 offset:4608
	ds_read_b128 v[178:181], v196 offset:32
	ds_read_b128 v[222:225], v197 offset:41504
	ds_read_b128 v[206:209], v196 offset:4640
	ds_read_b128 v[214:217], v197 offset:36896
	s_waitcnt lgkmcnt(6)
	v_mfma_f32_32x32x16_bf16 v[52:67], v[174:177], v[210:213], v[52:67]
	global_load_dwordx4 v[88:91], v[164:165], off offset:1280
	s_waitcnt lgkmcnt(5)
	v_mfma_f32_32x32x16_bf16 v[36:51], v[174:177], v[218:221], v[36:51]
	global_load_dwordx4 v[96:99], v[162:163], off offset:1280
	s_waitcnt lgkmcnt(4)
	v_mfma_f32_32x32x16_bf16 v[4:19], v[202:205], v[218:221], v[4:19]
	global_load_dwordx4 v[100:103], v[160:161], off offset:1280
	s_waitcnt lgkmcnt(2)
	v_mfma_f32_32x32x16_bf16 v[36:51], v[178:181], v[222:225], v[36:51]
	global_load_dwordx4 v[108:111], v[158:159], off offset:1280
	s_waitcnt lgkmcnt(1)
	v_mfma_f32_32x32x16_bf16 v[4:19], v[206:209], v[222:225], v[4:19]
	global_load_dwordx4 v[116:119], v[156:157], off offset:1280
	ds_read_b128 v[222:225], v197 offset:41568
	ds_read_b128 v[174:177], v196 offset:4672
	v_mfma_f32_32x32x16_bf16 v[20:35], v[202:205], v[210:213], v[20:35]
	global_load_dwordx4 v[120:123], v[154:155], off offset:1280
	ds_read_b128 v[210:213], v196 offset:4704
	ds_read_b128 v[202:205], v196 offset:64
	s_waitcnt lgkmcnt(4)
	v_mfma_f32_32x32x16_bf16 v[52:67], v[178:181], v[214:217], v[52:67]
	global_load_dwordx4 v[124:127], v[152:153], off offset:1280
	ds_read_b128 v[218:221], v197 offset:36960
	ds_read_b128 v[178:181], v197 offset:41536
	v_mfma_f32_32x32x16_bf16 v[20:35], v[206:209], v[214:217], v[20:35]
	global_load_dwordx4 v[128:131], v[146:147], off offset:1280
	ds_read_b128 v[214:217], v197 offset:36928
	ds_read_b128 v[206:209], v196 offset:96
	s_waitcnt lgkmcnt(1)
	v_mfma_f32_32x32x16_bf16 v[52:67], v[202:205], v[214:217], v[52:67]
	s_waitcnt vmcnt(23)
	ds_write_b128 v167, v[132:135]
	v_mfma_f32_32x32x16_bf16 v[36:51], v[202:205], v[178:181], v[36:51]
	s_waitcnt vmcnt(22)
	ds_write_b128 v167, v[136:139] offset:36864
	v_mfma_f32_32x32x16_bf16 v[20:35], v[174:177], v[214:217], v[20:35]
	s_waitcnt vmcnt(21)
	ds_write_b128 v190, v[140:143]
	v_mfma_f32_32x32x16_bf16 v[4:19], v[174:177], v[178:181], v[4:19]
	s_waitcnt vmcnt(20)
	ds_write_b128 v190, v[198:201] offset:36864
	s_waitcnt lgkmcnt(4)
	v_mfma_f32_32x32x16_bf16 v[52:67], v[206:209], v[218:221], v[52:67]
	s_waitcnt vmcnt(19)
	ds_write_b128 v191, v[226:229]
	v_mfma_f32_32x32x16_bf16 v[36:51], v[206:209], v[222:225], v[36:51]
	s_waitcnt vmcnt(18)
	ds_write_b128 v191, v[230:233] offset:36864
	v_mfma_f32_32x32x16_bf16 v[20:35], v[210:213], v[218:221], v[20:35]
	s_waitcnt vmcnt(17)
	ds_write_b128 v192, v[242:245]
	v_mfma_f32_32x32x16_bf16 v[4:19], v[210:213], v[222:225], v[4:19]
	s_waitcnt vmcnt(16)
	ds_write_b128 v192, v[246:249] offset:36864
	s_waitcnt lgkmcnt(0)
	s_barrier
	ds_read_b128 v[174:177], v194
	ds_read_b128 v[210:213], v195 offset:36864
	ds_read_b128 v[218:221], v195 offset:41472
	ds_read_b128 v[202:205], v194 offset:4608
	ds_read_b128 v[178:181], v194 offset:32
	ds_read_b128 v[222:225], v195 offset:41504
	ds_read_b128 v[206:209], v194 offset:4640
	ds_read_b128 v[214:217], v195 offset:36896
	s_waitcnt lgkmcnt(6)
	v_mfma_f32_32x32x16_bf16 v[52:67], v[174:177], v[210:213], v[52:67]
	global_load_dwordx4 v[132:135], v[164:165], off offset:1408
	s_waitcnt lgkmcnt(5)
	v_mfma_f32_32x32x16_bf16 v[36:51], v[174:177], v[218:221], v[36:51]
	global_load_dwordx4 v[136:139], v[162:163], off offset:1408
	s_waitcnt lgkmcnt(4)
	v_mfma_f32_32x32x16_bf16 v[4:19], v[202:205], v[218:221], v[4:19]
	global_load_dwordx4 v[140:143], v[160:161], off offset:1408
	s_waitcnt lgkmcnt(2)
	v_mfma_f32_32x32x16_bf16 v[36:51], v[178:181], v[222:225], v[36:51]
	global_load_dwordx4 v[198:201], v[158:159], off offset:1408
	s_waitcnt lgkmcnt(1)
	v_mfma_f32_32x32x16_bf16 v[4:19], v[206:209], v[222:225], v[4:19]
	global_load_dwordx4 v[226:229], v[156:157], off offset:1408
	ds_read_b128 v[222:225], v195 offset:41568
	ds_read_b128 v[174:177], v194 offset:4672
	v_mfma_f32_32x32x16_bf16 v[20:35], v[202:205], v[210:213], v[20:35]
	global_load_dwordx4 v[230:233], v[154:155], off offset:1408
	ds_read_b128 v[210:213], v194 offset:4704
	ds_read_b128 v[202:205], v194 offset:64
	s_waitcnt lgkmcnt(4)
	v_mfma_f32_32x32x16_bf16 v[52:67], v[178:181], v[214:217], v[52:67]
	global_load_dwordx4 v[242:245], v[152:153], off offset:1408
	ds_read_b128 v[218:221], v195 offset:36960
	ds_read_b128 v[178:181], v195 offset:41536
	v_mfma_f32_32x32x16_bf16 v[20:35], v[206:209], v[214:217], v[20:35]
	global_load_dwordx4 v[246:249], v[146:147], off offset:1408
	ds_read_b128 v[214:217], v195 offset:36928
	ds_read_b128 v[206:209], v194 offset:96
	s_waitcnt lgkmcnt(1)
	v_mfma_f32_32x32x16_bf16 v[52:67], v[202:205], v[214:217], v[52:67]
	s_waitcnt vmcnt(23)
	ds_write_b128 v167, v[68:71] offset:18432
	v_mfma_f32_32x32x16_bf16 v[36:51], v[202:205], v[178:181], v[36:51]
	s_waitcnt vmcnt(22)
	ds_write_b128 v167, v[72:75] offset:55296
	v_mfma_f32_32x32x16_bf16 v[20:35], v[174:177], v[214:217], v[20:35]
	s_waitcnt vmcnt(21)
	ds_write_b128 v190, v[76:79] offset:18432
	v_mfma_f32_32x32x16_bf16 v[4:19], v[174:177], v[178:181], v[4:19]
	s_waitcnt vmcnt(20)
	ds_write_b128 v190, v[80:83] offset:55296
	s_waitcnt lgkmcnt(4)
	v_mfma_f32_32x32x16_bf16 v[52:67], v[206:209], v[218:221], v[52:67]
	s_waitcnt vmcnt(19)
	ds_write_b128 v191, v[84:87] offset:18432
	v_mfma_f32_32x32x16_bf16 v[36:51], v[206:209], v[222:225], v[36:51]
	s_waitcnt vmcnt(18)
	ds_write_b128 v191, v[92:95] offset:55296
	v_mfma_f32_32x32x16_bf16 v[20:35], v[210:213], v[218:221], v[20:35]
	s_waitcnt vmcnt(17)
	ds_write_b128 v192, v[104:107] offset:18432
	v_mfma_f32_32x32x16_bf16 v[4:19], v[210:213], v[222:225], v[4:19]
	s_waitcnt vmcnt(16)
	ds_write_b128 v192, v[112:115] offset:55296
	s_waitcnt lgkmcnt(0)
	s_barrier
; #define MFMA(a, b, c) __builtin_amdgcn_mfma_f32_32x32x16_bf16((a), (b), (c), 0, 0, 0)
; template <class Epi, class ColV>
; DI void gemm_tile(const bf16_t* __restrict__ A, int lda, const bf16_t* __restrict__ Bt, int ldb, int K, int m0, int n0, unsigned char* smem, Epi epi, ColV colv, const bf16_t* __restrict__ HYT = nullptr) {
;     ...
;     auto step = [&](int kt, u32x4 (&ldset)[8], const u32x4 (&stset)[8]) {
;         const int buf = kt & 1;
;         if (kt + 2 < nk) gload(ldset, kt + 2);
;         const bf16_t* Ab = As + (buf * 128 + 64 * wr + li) * LS + 8 * lh;
;         const bf16_t* Bb = Bs + (buf * 128 + 64 * wc + li) * LS + 8 * lh;
;         bf16x8 fa[2][2], fb[2][2], ga[2][2], gb[2][2];
; #pragma unroll
;         for (int k2 = 0; k2 < 2; ++k2) { fa[k2][0] = ld8(Ab + 16 * k2); fa[k2][1] = ld8(Ab + 32 * LS + 16 * k2); fb[k2][0] = ld8(Bb + 16 * k2); fb[k2][1] = ld8(Bb + 32 * LS + 16 * k2); }
;         __builtin_amdgcn_sched_barrier(0);
; #pragma unroll
;         for (int k2 = 0; k2 < 2; ++k2) {
;             acc[0][0] = MFMA(fa[k2][0], fb[k2][0], acc[0][0]); acc[0][1] = MFMA(fa[k2][0], fb[k2][1], acc[0][1]);
;             acc[1][0] = MFMA(fa[k2][1], fb[k2][0], acc[1][0]); acc[1][1] = MFMA(fa[k2][1], fb[k2][1], acc[1][1]);
;         }
; #pragma unroll
;         for (int k2 = 0; k2 < 2; ++k2) { const int ks = 2 + k2; ga[k2][0] = ld8(Ab + 16 * ks); ga[k2][1] = ld8(Ab + 32 * LS + 16 * ks); gb[k2][0] = ld8(Bb + 16 * ks); gb[k2][1] = ld8(Bb + 32 * LS + 16 * ks); }
; #pragma unroll
;         for (int k2 = 0; k2 < 2; ++k2) {
;             acc[0][0] = MFMA(ga[k2][0], gb[k2][0], acc[0][0]); acc[0][1] = MFMA(ga[k2][0], gb[k2][1], acc[0][1]);
;             acc[1][0] = MFMA(ga[k2][1], gb[k2][0], acc[1][0]); acc[1][1] = MFMA(ga[k2][1], gb[k2][1], acc[1][1]);
;         }
;         if (kt + 1 < nk) sstore(stset, buf ^ 1, kt + 1);
; #pragma unroll
;         for (int i = 0; i < 8; ++i) { __builtin_amdgcn_sched_group_barrier(0x008, 1, 0); __builtin_amdgcn_sched_group_barrier(0x100, 1, 0); }
; #pragma unroll
;         for (int i = 0; i < 8; ++i) { __builtin_amdgcn_sched_group_barrier(0x008, 1, 0); __builtin_amdgcn_sched_group_barrier(0x200, 1, 0); }
;         __builtin_amdgcn_sched_barrier(0);
;         __syncthreads();
	ds_read_b128 v[174:177], v196
	ds_read_b128 v[210:213], v197 offset:36864
	ds_read_b128 v[218:221], v197 offset:41472
	ds_read_b128 v[202:205], v196 offset:4608
	ds_read_b128 v[178:181], v196 offset:32
	ds_read_b128 v[222:225], v197 offset:41504
	ds_read_b128 v[206:209], v196 offset:4640
	ds_read_b128 v[214:217], v197 offset:36896
	s_waitcnt lgkmcnt(6)
	v_mfma_f32_32x32x16_bf16 v[52:67], v[174:177], v[210:213], v[52:67]
	global_load_dwordx4 v[68:71], v[164:165], off offset:1536
	s_waitcnt lgkmcnt(5)
	v_mfma_f32_32x32x16_bf16 v[36:51], v[174:177], v[218:221], v[36:51]
	global_load_dwordx4 v[72:75], v[162:163], off offset:1536
	s_waitcnt lgkmcnt(4)
	v_mfma_f32_32x32x16_bf16 v[4:19], v[202:205], v[218:221], v[4:19]
	global_load_dwordx4 v[76:79], v[160:161], off offset:1536
	s_waitcnt lgkmcnt(2)
	v_mfma_f32_32x32x16_bf16 v[36:51], v[178:181], v[222:225], v[36:51]
	global_load_dwordx4 v[80:83], v[158:159], off offset:1536
	s_waitcnt lgkmcnt(1)
	v_mfma_f32_32x32x16_bf16 v[4:19], v[206:209], v[222:225], v[4:19]
	global_load_dwordx4 v[84:87], v[156:157], off offset:1536
	ds_read_b128 v[222:225], v197 offset:41568
	ds_read_b128 v[174:177], v196 offset:4672
	v_mfma_f32_32x32x16_bf16 v[20:35], v[202:205], v[210:213], v[20:35]
	global_load_dwordx4 v[92:95], v[154:155], off offset:1536
	ds_read_b128 v[210:213], v196 offset:4704
	ds_read_b128 v[202:205], v196 offset:64
	s_waitcnt lgkmcnt(4)
	v_mfma_f32_32x32x16_bf16 v[52:67], v[178:181], v[214:217], v[52:67]
	global_load_dwordx4 v[104:107], v[152:153], off offset:1536
	ds_read_b128 v[218:221], v197 offset:36960
	ds_read_b128 v[178:181], v197 offset:41536
	v_mfma_f32_32x32x16_bf16 v[20:35], v[206:209], v[214:217], v[20:35]
	global_load_dwordx4 v[112:115], v[146:147], off offset:1536
	ds_read_b128 v[214:217], v197 offset:36928
	ds_read_b128 v[206:209], v196 offset:96
	s_waitcnt lgkmcnt(1)
	v_mfma_f32_32x32x16_bf16 v[52:67], v[202:205], v[214:217], v[52:67]
	s_waitcnt vmcnt(23)
	ds_write_b128 v167, v[88:91]
	v_mfma_f32_32x32x16_bf16 v[36:51], v[202:205], v[178:181], v[36:51]
	s_waitcnt vmcnt(22)
	ds_write_b128 v167, v[96:99] offset:36864
	v_mfma_f32_32x32x16_bf16 v[20:35], v[174:177], v[214:217], v[20:35]
	s_waitcnt vmcnt(21)
	ds_write_b128 v190, v[100:103]
	v_mfma_f32_32x32x16_bf16 v[4:19], v[174:177], v[178:181], v[4:19]
	s_waitcnt vmcnt(20)
	ds_write_b128 v190, v[108:111] offset:36864
	s_waitcnt lgkmcnt(4)
	v_mfma_f32_32x32x16_bf16 v[52:67], v[206:209], v[218:221], v[52:67]
	s_waitcnt vmcnt(19)
	ds_write_b128 v191, v[116:119]
	v_mfma_f32_32x32x16_bf16 v[36:51], v[206:209], v[222:225], v[36:51]
	s_waitcnt vmcnt(18)
	ds_write_b128 v191, v[120:123] offset:36864
	v_mfma_f32_32x32x16_bf16 v[20:35], v[210:213], v[218:221], v[20:35]
	s_waitcnt vmcnt(17)
	ds_write_b128 v192, v[124:127]
	v_mfma_f32_32x32x16_bf16 v[4:19], v[210:213], v[222:225], v[4:19]
	s_waitcnt vmcnt(16)
	ds_write_b128 v192, v[128:131] offset:36864
	s_waitcnt lgkmcnt(0)
	s_barrier
	ds_read_b128 v[174:177], v194
	ds_read_b128 v[210:213], v195 offset:36864
	ds_read_b128 v[218:221], v195 offset:41472
	ds_read_b128 v[202:205], v194 offset:4608
	ds_read_b128 v[178:181], v194 offset:32
	ds_read_b128 v[222:225], v195 offset:41504
	ds_read_b128 v[206:209], v194 offset:4640
	ds_read_b128 v[214:217], v195 offset:36896
	s_waitcnt lgkmcnt(6)
	v_mfma_f32_32x32x16_bf16 v[52:67], v[174:177], v[210:213], v[52:67]
	global_load_dwordx4 v[88:91], v[164:165], off offset:1664
	s_waitcnt lgkmcnt(5)
	v_mfma_f32_32x32x16_bf16 v[36:51], v[174:177], v[218:221], v[36:51]
	global_load_dwordx4 v[96:99], v[162:163], off offset:1664
	s_waitcnt lgkmcnt(4)
	v_mfma_f32_32x32x16_bf16 v[4:19], v[202:205], v[218:221], v[4:19]
	global_load_dwordx4 v[100:103], v[160:161], off offset:1664
	s_waitcnt lgkmcnt(2)
	v_mfma_f32_32x32x16_bf16 v[36:51], v[178:181], v[222:225], v[36:51]
	global_load_dwordx4 v[108:111], v[158:159], off offset:1664
	s_waitcnt lgkmcnt(1)
	v_mfma_f32_32x32x16_bf16 v[4:19], v[206:209], v[222:225], v[4:19]
	global_load_dwordx4 v[116:119], v[156:157], off offset:1664
	ds_read_b128 v[222:225], v195 offset:41568
	ds_read_b128 v[174:177], v194 offset:4672
	v_mfma_f32_32x32x16_bf16 v[20:35], v[202:205], v[210:213], v[20:35]
	global_load_dwordx4 v[120:123], v[154:155], off offset:1664
	ds_read_b128 v[210:213], v194 offset:4704
	ds_read_b128 v[202:205], v194 offset:64
	s_waitcnt lgkmcnt(4)
	v_mfma_f32_32x32x16_bf16 v[52:67], v[178:181], v[214:217], v[52:67]
	global_load_dwordx4 v[124:127], v[152:153], off offset:1664
	ds_read_b128 v[218:221], v195 offset:36960
	ds_read_b128 v[178:181], v195 offset:41536
	v_mfma_f32_32x32x16_bf16 v[20:35], v[206:209], v[214:217], v[20:35]
	global_load_dwordx4 v[128:131], v[146:147], off offset:1664
	ds_read_b128 v[214:217], v195 offset:36928
	ds_read_b128 v[206:209], v194 offset:96
	s_waitcnt lgkmcnt(1)
	v_mfma_f32_32x32x16_bf16 v[52:67], v[202:205], v[214:217], v[52:67]
	s_waitcnt vmcnt(23)
	ds_write_b128 v167, v[132:135] offset:18432
	v_mfma_f32_32x32x16_bf16 v[36:51], v[202:205], v[178:181], v[36:51]
	s_waitcnt vmcnt(22)
	ds_write_b128 v167, v[136:139] offset:55296
	v_mfma_f32_32x32x16_bf16 v[20:35], v[174:177], v[214:217], v[20:35]
	s_waitcnt vmcnt(21)
	ds_write_b128 v190, v[140:143] offset:18432
	v_mfma_f32_32x32x16_bf16 v[4:19], v[174:177], v[178:181], v[4:19]
	s_waitcnt vmcnt(20)
	ds_write_b128 v190, v[198:201] offset:55296
	s_waitcnt lgkmcnt(4)
	v_mfma_f32_32x32x16_bf16 v[52:67], v[206:209], v[218:221], v[52:67]
	s_waitcnt vmcnt(19)
	ds_write_b128 v191, v[226:229] offset:18432
	v_mfma_f32_32x32x16_bf16 v[36:51], v[206:209], v[222:225], v[36:51]
	s_waitcnt vmcnt(18)
	ds_write_b128 v191, v[230:233] offset:55296
	v_mfma_f32_32x32x16_bf16 v[20:35], v[210:213], v[218:221], v[20:35]
	s_waitcnt vmcnt(17)
	ds_write_b128 v192, v[242:245] offset:18432
	v_mfma_f32_32x32x16_bf16 v[4:19], v[210:213], v[222:225], v[4:19]
	s_waitcnt vmcnt(16)
	ds_write_b128 v192, v[246:249] offset:55296
	s_waitcnt lgkmcnt(0)
	s_barrier
; #define MFMA(a, b, c) __builtin_amdgcn_mfma_f32_32x32x16_bf16((a), (b), (c), 0, 0, 0)
; template <class Epi, class ColV>
; DI void gemm_tile(const bf16_t* __restrict__ A, int lda, const bf16_t* __restrict__ Bt, int ldb, int K, int m0, int n0, unsigned char* smem, Epi epi, ColV colv, const bf16_t* __restrict__ HYT = nullptr) {
;     ...
;     auto step = [&](int kt, u32x4 (&ldset)[8], const u32x4 (&stset)[8]) {
;         const int buf = kt & 1;
;         if (kt + 2 < nk) gload(ldset, kt + 2);
;         const bf16_t* Ab = As + (buf * 128 + 64 * wr + li) * LS + 8 * lh;
;         const bf16_t* Bb = Bs + (buf * 128 + 64 * wc + li) * LS + 8 * lh;
;         bf16x8 fa[2][2], fb[2][2], ga[2][2], gb[2][2];
; #pragma unroll
;         for (int k2 = 0; k2 < 2; ++k2) { fa[k2][0] = ld8(Ab + 16 * k2); fa[k2][1] = ld8(Ab + 32 * LS + 16 * k2); fb[k2][0] = ld8(Bb + 16 * k2); fb[k2][1] = ld8(Bb + 32 * LS + 16 * k2); }
;         __builtin_amdgcn_sched_barrier(0);
; #pragma unroll
;         for (int k2 = 0; k2 < 2; ++k2) {
;             acc[0][0] = MFMA(fa[k2][0], fb[k2][0], acc[0][0]); acc[0][1] = MFMA(fa[k2][0], fb[k2][1], acc[0][1]);
;             acc[1][0] = MFMA(fa[k2][1], fb[k2][0], acc[1][0]); acc[1][1] = MFMA(fa[k2][1], fb[k2][1], acc[1][1]);
;         }
; #pragma unroll
;         for (int k2 = 0; k2 < 2; ++k2) { const int ks = 2 + k2; ga[k2][0] = ld8(Ab + 16 * ks); ga[k2][1] = ld8(Ab + 32 * LS + 16 * ks); gb[k2][0] = ld8(Bb + 16 * ks); gb[k2][1] = ld8(Bb + 32 * LS + 16 * ks); }
; #pragma unroll
;         for (int k2 = 0; k2 < 2; ++k2) {
;             acc[0][0] = MFMA(ga[k2][0], gb[k2][0], acc[0][0]); acc[0][1] = MFMA(ga[k2][0], gb[k2][1], acc[0][1]);
;             acc[1][0] = MFMA(ga[k2][1], gb[k2][0], acc[1][0]); acc[1][1] = MFMA(ga[k2][1], gb[k2][1], acc[1][1]);
;         }
;         if (kt + 1 < nk) sstore(stset, buf ^ 1, kt + 1);
; #pragma unroll
;         for (int i = 0; i < 8; ++i) { __builtin_amdgcn_sched_group_barrier(0x008, 1, 0); __builtin_amdgcn_sched_group_barrier(0x100, 1, 0); }
; #pragma unroll
;         for (int i = 0; i < 8; ++i) { __builtin_amdgcn_sched_group_barrier(0x008, 1, 0); __builtin_amdgcn_sched_group_barrier(0x200, 1, 0); }
;         __builtin_amdgcn_sched_barrier(0);
;         __syncthreads();
	ds_read_b128 v[174:177], v196
	ds_read_b128 v[210:213], v197 offset:36864
	ds_read_b128 v[218:221], v197 offset:41472
	ds_read_b128 v[202:205], v196 offset:4608
	ds_read_b128 v[178:181], v196 offset:32
	ds_read_b128 v[222:225], v197 offset:41504
	ds_read_b128 v[206:209], v196 offset:4640
	ds_read_b128 v[214:217], v197 offset:36896
	s_waitcnt lgkmcnt(6)
	v_mfma_f32_32x32x16_bf16 v[52:67], v[174:177], v[210:213], v[52:67]
	global_load_dwordx4 v[132:135], v[164:165], off offset:1792
	s_waitcnt lgkmcnt(5)
	v_mfma_f32_32x32x16_bf16 v[36:51], v[174:177], v[218:221], v[36:51]
	global_load_dwordx4 v[136:139], v[162:163], off offset:1792
	s_waitcnt lgkmcnt(4)
	v_mfma_f32_32x32x16_bf16 v[4:19], v[202:205], v[218:221], v[4:19]
	global_load_dwordx4 v[140:143], v[160:161], off offset:1792
	s_waitcnt lgkmcnt(2)
	v_mfma_f32_32x32x16_bf16 v[36:51], v[178:181], v[222:225], v[36:51]
	global_load_dwordx4 v[198:201], v[158:159], off offset:1792
	s_waitcnt lgkmcnt(1)
	v_mfma_f32_32x32x16_bf16 v[4:19], v[206:209], v[222:225], v[4:19]
	global_load_dwordx4 v[226:229], v[156:157], off offset:1792
	ds_read_b128 v[222:225], v197 offset:41568
	ds_read_b128 v[174:177], v196 offset:4672
	v_mfma_f32_32x32x16_bf16 v[20:35], v[202:205], v[210:213], v[20:35]
	global_load_dwordx4 v[230:233], v[154:155], off offset:1792
	ds_read_b128 v[210:213], v196 offset:4704
	ds_read_b128 v[202:205], v196 offset:64
	s_waitcnt lgkmcnt(4)
	v_mfma_f32_32x32x16_bf16 v[52:67], v[178:181], v[214:217], v[52:67]
	global_load_dwordx4 v[242:245], v[152:153], off offset:1792
	ds_read_b128 v[218:221], v197 offset:36960
	ds_read_b128 v[178:181], v197 offset:41536
	v_mfma_f32_32x32x16_bf16 v[20:35], v[206:209], v[214:217], v[20:35]
	global_load_dwordx4 v[246:249], v[146:147], off offset:1792
	ds_read_b128 v[214:217], v197 offset:36928
	ds_read_b128 v[206:209], v196 offset:96
	s_waitcnt lgkmcnt(1)
	v_mfma_f32_32x32x16_bf16 v[52:67], v[202:205], v[214:217], v[52:67]
	s_waitcnt vmcnt(23)
	ds_write_b128 v167, v[68:71]
	v_mfma_f32_32x32x16_bf16 v[36:51], v[202:205], v[178:181], v[36:51]
	s_waitcnt vmcnt(22)
	ds_write_b128 v167, v[72:75] offset:36864
	v_mfma_f32_32x32x16_bf16 v[20:35], v[174:177], v[214:217], v[20:35]
	s_waitcnt vmcnt(21)
	ds_write_b128 v190, v[76:79]
	v_mfma_f32_32x32x16_bf16 v[4:19], v[174:177], v[178:181], v[4:19]
	s_waitcnt vmcnt(20)
	ds_write_b128 v190, v[80:83] offset:36864
	s_waitcnt lgkmcnt(4)
	v_mfma_f32_32x32x16_bf16 v[52:67], v[206:209], v[218:221], v[52:67]
	s_waitcnt vmcnt(19)
	ds_write_b128 v191, v[84:87]
	v_mfma_f32_32x32x16_bf16 v[36:51], v[206:209], v[222:225], v[36:51]
	s_waitcnt vmcnt(18)
	ds_write_b128 v191, v[92:95] offset:36864
	v_mfma_f32_32x32x16_bf16 v[20:35], v[210:213], v[218:221], v[20:35]
	s_waitcnt vmcnt(17)
	ds_write_b128 v192, v[104:107]
	v_mfma_f32_32x32x16_bf16 v[4:19], v[210:213], v[222:225], v[4:19]
	s_waitcnt vmcnt(16)
	ds_write_b128 v192, v[112:115] offset:36864
	s_waitcnt lgkmcnt(0)
	s_barrier
	ds_read_b128 v[174:177], v194
	ds_read_b128 v[210:213], v195 offset:36864
	ds_read_b128 v[218:221], v195 offset:41472
	ds_read_b128 v[202:205], v194 offset:4608
	ds_read_b128 v[178:181], v194 offset:32
	ds_read_b128 v[222:225], v195 offset:41504
	ds_read_b128 v[206:209], v194 offset:4640
	ds_read_b128 v[214:217], v195 offset:36896
	s_waitcnt lgkmcnt(6)
	v_mfma_f32_32x32x16_bf16 v[52:67], v[174:177], v[210:213], v[52:67]
	global_load_dwordx4 v[68:71], v[164:165], off offset:1920
	s_waitcnt lgkmcnt(5)
	v_mfma_f32_32x32x16_bf16 v[36:51], v[174:177], v[218:221], v[36:51]
	global_load_dwordx4 v[72:75], v[162:163], off offset:1920
	s_waitcnt lgkmcnt(4)
	v_mfma_f32_32x32x16_bf16 v[4:19], v[202:205], v[218:221], v[4:19]
	global_load_dwordx4 v[76:79], v[160:161], off offset:1920
	s_waitcnt lgkmcnt(2)
	v_mfma_f32_32x32x16_bf16 v[36:51], v[178:181], v[222:225], v[36:51]
	global_load_dwordx4 v[80:83], v[158:159], off offset:1920
	s_waitcnt lgkmcnt(1)
	v_mfma_f32_32x32x16_bf16 v[4:19], v[206:209], v[222:225], v[4:19]
	global_load_dwordx4 v[84:87], v[156:157], off offset:1920
	ds_read_b128 v[222:225], v195 offset:41568
	ds_read_b128 v[174:177], v194 offset:4672
	v_mfma_f32_32x32x16_bf16 v[20:35], v[202:205], v[210:213], v[20:35]
	global_load_dwordx4 v[92:95], v[154:155], off offset:1920
	ds_read_b128 v[210:213], v194 offset:4704
	ds_read_b128 v[202:205], v194 offset:64
	s_waitcnt lgkmcnt(4)
	v_mfma_f32_32x32x16_bf16 v[52:67], v[178:181], v[214:217], v[52:67]
	global_load_dwordx4 v[104:107], v[152:153], off offset:1920
	ds_read_b128 v[218:221], v195 offset:36960
	ds_read_b128 v[178:181], v195 offset:41536
	v_mfma_f32_32x32x16_bf16 v[20:35], v[206:209], v[214:217], v[20:35]
	global_load_dwordx4 v[112:115], v[146:147], off offset:1920
	ds_read_b128 v[214:217], v195 offset:36928
	ds_read_b128 v[206:209], v194 offset:96
	s_waitcnt lgkmcnt(1)
	v_mfma_f32_32x32x16_bf16 v[52:67], v[202:205], v[214:217], v[52:67]
	s_waitcnt vmcnt(23)
	ds_write_b128 v167, v[88:91] offset:18432
	v_mfma_f32_32x32x16_bf16 v[36:51], v[202:205], v[178:181], v[36:51]
	s_waitcnt vmcnt(22)
	ds_write_b128 v167, v[96:99] offset:55296
	v_mfma_f32_32x32x16_bf16 v[20:35], v[174:177], v[214:217], v[20:35]
	s_waitcnt vmcnt(21)
	ds_write_b128 v190, v[100:103] offset:18432
	v_mfma_f32_32x32x16_bf16 v[4:19], v[174:177], v[178:181], v[4:19]
	s_waitcnt vmcnt(20)
	ds_write_b128 v190, v[108:111] offset:55296
	s_waitcnt lgkmcnt(4)
	v_mfma_f32_32x32x16_bf16 v[52:67], v[206:209], v[218:221], v[52:67]
	s_waitcnt vmcnt(19)
	ds_write_b128 v191, v[116:119] offset:18432
	v_mfma_f32_32x32x16_bf16 v[36:51], v[206:209], v[222:225], v[36:51]
	s_waitcnt vmcnt(18)
	ds_write_b128 v191, v[120:123] offset:55296
	v_mfma_f32_32x32x16_bf16 v[20:35], v[210:213], v[218:221], v[20:35]
	s_waitcnt vmcnt(17)
	ds_write_b128 v192, v[124:127] offset:18432
	v_mfma_f32_32x32x16_bf16 v[4:19], v[210:213], v[222:225], v[4:19]
	s_waitcnt vmcnt(16)
	ds_write_b128 v192, v[128:131] offset:55296
	s_waitcnt lgkmcnt(0)
	s_barrier
; template <class Epi, class ColV>
; DI void gemm_tile(const bf16_t* __restrict__ A, int lda, const bf16_t* __restrict__ Bt, int ldb, int K, int m0, int n0, unsigned char* smem, Epi epi, ColV colv, const bf16_t* __restrict__ HYT = nullptr) {
;     ...
;     auto step = [&](int kt, u32x4 (&ldset)[8], const u32x4 (&stset)[8]) {
;         const int buf = kt & 1;
;         if (kt + 2 < nk) gload(ldset, kt + 2);
;         const bf16_t* Ab = As + (buf * 128 + 64 * wr + li) * LS + 8 * lh;
;         const bf16_t* Bb = Bs + (buf * 128 + 64 * wc + li) * LS + 8 * lh;
;         bf16x8 fa[2][2], fb[2][2], ga[2][2], gb[2][2];
; #pragma unroll
;         for (int k2 = 0; k2 < 2; ++k2) { fa[k2][0] = ld8(Ab + 16 * k2); fa[k2][1] = ld8(Ab + 32 * LS + 16 * k2); fb[k2][0] = ld8(Bb + 16 * k2); fb[k2][1] = ld8(Bb + 32 * LS + 16 * k2); }
;         __builtin_amdgcn_sched_barrier(0);
; #pragma unroll
;         for (int k2 = 0; k2 < 2; ++k2) {
;             acc[0][0] = MFMA(fa[k2][0], fb[k2][0], acc[0][0]); acc[0][1] = MFMA(fa[k2][0], fb[k2][1], acc[0][1]);
;             acc[1][0] = MFMA(fa[k2][1], fb[k2][0], acc[1][0]); acc[1][1] = MFMA(fa[k2][1], fb[k2][1], acc[1][1]);
;         }
; #pragma unroll
;         for (int k2 = 0; k2 < 2; ++k2) { const int ks = 2 + k2; ga[k2][0] = ld8(Ab + 16 * ks); ga[k2][1] = ld8(Ab + 32 * LS + 16 * ks); gb[k2][0] = ld8(Bb + 16 * ks); gb[k2][1] = ld8(Bb + 32 * LS + 16 * ks); }
; #pragma unroll
;         for (int k2 = 0; k2 < 2; ++k2) {
;             acc[0][0] = MFMA(ga[k2][0], gb[k2][0], acc[0][0]); acc[0][1] = MFMA(ga[k2][0], gb[k2][1], acc[0][1]);
;             acc[1][0] = MFMA(ga[k2][1], gb[k2][0], acc[1][0]); acc[1][1] = MFMA(ga[k2][1], gb[k2][1], acc[1][1]);
;         }
;         if (kt + 1 < nk) sstore(stset, buf ^ 1, kt + 1);
; #pragma unroll
;         for (int i = 0; i < 8; ++i) { __builtin_amdgcn_sched_group_barrier(0x008, 1, 0); __builtin_amdgcn_sched_group_barrier(0x100, 1, 0); }
; #pragma unroll
;         for (int i = 0; i < 8; ++i) { __builtin_amdgcn_sched_group_barrier(0x008, 1, 0); __builtin_amdgcn_sched_group_barrier(0x200, 1, 0); }
;         __builtin_amdgcn_sched_barrier(0);
;         __syncthreads();
;     };
;     gload(R0, 0); gload(R1, 1);
;     sstore(R0, 0, 0); __syncthreads();
;     for (int kt = 0; kt < nk; kt += 2) {
;         step(kt, R0, R1);
;         if (kt + 1 < nk) step(kt + 1, R1, R0);
;     }
	ds_read_b128 v[174:177], v196
	ds_read_b128 v[210:213], v197 offset:36864
	ds_read_b128 v[218:221], v197 offset:41472
	ds_read_b128 v[202:205], v196 offset:4608
	ds_read_b128 v[178:181], v196 offset:32
	ds_read_b128 v[222:225], v197 offset:41504
	ds_read_b128 v[206:209], v196 offset:4640
	ds_read_b128 v[214:217], v197 offset:36896
	s_waitcnt lgkmcnt(6)
	v_mfma_f32_32x32x16_bf16 v[52:67], v[174:177], v[210:213], v[52:67]
	s_waitcnt lgkmcnt(5)
	v_mfma_f32_32x32x16_bf16 v[36:51], v[174:177], v[218:221], v[36:51]
	s_waitcnt lgkmcnt(4)
	v_mfma_f32_32x32x16_bf16 v[4:19], v[202:205], v[218:221], v[4:19]
	s_waitcnt lgkmcnt(2)
	v_mfma_f32_32x32x16_bf16 v[36:51], v[178:181], v[222:225], v[36:51]
	s_waitcnt lgkmcnt(1)
	v_mfma_f32_32x32x16_bf16 v[4:19], v[206:209], v[222:225], v[4:19]
	ds_read_b128 v[222:225], v197 offset:41568
	ds_read_b128 v[174:177], v196 offset:4672
	v_mfma_f32_32x32x16_bf16 v[20:35], v[202:205], v[210:213], v[20:35]
	ds_read_b128 v[210:213], v196 offset:4704
	ds_read_b128 v[202:205], v196 offset:64
	s_waitcnt lgkmcnt(4)
	v_mfma_f32_32x32x16_bf16 v[52:67], v[178:181], v[214:217], v[52:67]
	ds_read_b128 v[218:221], v197 offset:36960
	ds_read_b128 v[178:181], v197 offset:41536
	v_mfma_f32_32x32x16_bf16 v[20:35], v[206:209], v[214:217], v[20:35]
	ds_read_b128 v[214:217], v197 offset:36928
	ds_read_b128 v[206:209], v196 offset:96
	s_waitcnt lgkmcnt(1)
	v_mfma_f32_32x32x16_bf16 v[52:67], v[202:205], v[214:217], v[52:67]
	s_waitcnt vmcnt(15)
	ds_write_b128 v167, v[132:135]
	v_mfma_f32_32x32x16_bf16 v[36:51], v[202:205], v[178:181], v[36:51]
	s_waitcnt vmcnt(14)
	ds_write_b128 v167, v[136:139] offset:36864
	v_mfma_f32_32x32x16_bf16 v[20:35], v[174:177], v[214:217], v[20:35]
	s_waitcnt vmcnt(13)
	ds_write_b128 v190, v[140:143]
	v_mfma_f32_32x32x16_bf16 v[4:19], v[174:177], v[178:181], v[4:19]
	s_waitcnt vmcnt(12)
	ds_write_b128 v190, v[198:201] offset:36864
	s_waitcnt lgkmcnt(4)
	v_mfma_f32_32x32x16_bf16 v[52:67], v[206:209], v[218:221], v[52:67]
	s_waitcnt vmcnt(11)
	ds_write_b128 v191, v[226:229]
	v_mfma_f32_32x32x16_bf16 v[36:51], v[206:209], v[222:225], v[36:51]
	s_waitcnt vmcnt(10)
	ds_write_b128 v191, v[230:233] offset:36864
	v_mfma_f32_32x32x16_bf16 v[20:35], v[210:213], v[218:221], v[20:35]
	s_waitcnt vmcnt(9)
	ds_write_b128 v192, v[242:245]
	v_mfma_f32_32x32x16_bf16 v[4:19], v[210:213], v[222:225], v[4:19]
	s_waitcnt vmcnt(8)
	ds_write_b128 v192, v[246:249] offset:36864
	s_waitcnt lgkmcnt(0)
	s_barrier
	ds_read_b128 v[174:177], v194
	ds_read_b128 v[210:213], v195 offset:36864
	ds_read_b128 v[218:221], v195 offset:41472
	ds_read_b128 v[202:205], v194 offset:4608
	ds_read_b128 v[178:181], v194 offset:32
	ds_read_b128 v[222:225], v195 offset:41504
	ds_read_b128 v[206:209], v194 offset:4640
	ds_read_b128 v[214:217], v195 offset:36896
	s_waitcnt lgkmcnt(6)
	v_mfma_f32_32x32x16_bf16 v[52:67], v[174:177], v[210:213], v[52:67]
	s_waitcnt lgkmcnt(5)
	v_mfma_f32_32x32x16_bf16 v[36:51], v[174:177], v[218:221], v[36:51]
	s_waitcnt lgkmcnt(4)
	v_mfma_f32_32x32x16_bf16 v[4:19], v[202:205], v[218:221], v[4:19]
	s_waitcnt lgkmcnt(2)
	v_mfma_f32_32x32x16_bf16 v[36:51], v[178:181], v[222:225], v[36:51]
	s_waitcnt lgkmcnt(1)
	v_mfma_f32_32x32x16_bf16 v[4:19], v[206:209], v[222:225], v[4:19]
	ds_read_b128 v[222:225], v195 offset:41568
	ds_read_b128 v[174:177], v194 offset:4672
	v_mfma_f32_32x32x16_bf16 v[20:35], v[202:205], v[210:213], v[20:35]
	ds_read_b128 v[210:213], v194 offset:4704
	ds_read_b128 v[202:205], v194 offset:64
	s_waitcnt lgkmcnt(4)
	v_mfma_f32_32x32x16_bf16 v[52:67], v[178:181], v[214:217], v[52:67]
	ds_read_b128 v[218:221], v195 offset:36960
	ds_read_b128 v[178:181], v195 offset:41536
	v_mfma_f32_32x32x16_bf16 v[20:35], v[206:209], v[214:217], v[20:35]
	ds_read_b128 v[214:217], v195 offset:36928
	ds_read_b128 v[206:209], v194 offset:96
	s_waitcnt lgkmcnt(1)
	v_mfma_f32_32x32x16_bf16 v[52:67], v[202:205], v[214:217], v[52:67]
	s_waitcnt vmcnt(7)
	ds_write_b128 v167, v[68:71] offset:18432
	v_mfma_f32_32x32x16_bf16 v[36:51], v[202:205], v[178:181], v[36:51]
	s_waitcnt vmcnt(6)
	ds_write_b128 v167, v[72:75] offset:55296
	v_mfma_f32_32x32x16_bf16 v[20:35], v[174:177], v[214:217], v[20:35]
	s_waitcnt vmcnt(5)
	ds_write_b128 v190, v[76:79] offset:18432
	v_mfma_f32_32x32x16_bf16 v[4:19], v[174:177], v[178:181], v[4:19]
	s_waitcnt vmcnt(4)
	ds_write_b128 v190, v[80:83] offset:55296
	s_waitcnt lgkmcnt(4)
	v_mfma_f32_32x32x16_bf16 v[52:67], v[206:209], v[218:221], v[52:67]
	s_waitcnt vmcnt(3)
	ds_write_b128 v191, v[84:87] offset:18432
	v_mfma_f32_32x32x16_bf16 v[36:51], v[206:209], v[222:225], v[36:51]
	s_waitcnt vmcnt(2)
	ds_write_b128 v191, v[92:95] offset:55296
	v_mfma_f32_32x32x16_bf16 v[20:35], v[210:213], v[218:221], v[20:35]
	s_waitcnt vmcnt(1)
	ds_write_b128 v192, v[104:107] offset:18432
	v_mfma_f32_32x32x16_bf16 v[4:19], v[210:213], v[222:225], v[4:19]
	s_waitcnt vmcnt(0)
	ds_write_b128 v192, v[112:115] offset:55296
	s_waitcnt lgkmcnt(0)
	s_barrier
	ds_read_b128 v[174:177], v196
	ds_read_b128 v[210:213], v197 offset:36864
	ds_read_b128 v[218:221], v197 offset:41472
	ds_read_b128 v[202:205], v196 offset:4608
	ds_read_b128 v[178:181], v196 offset:32
	ds_read_b128 v[222:225], v197 offset:41504
	ds_read_b128 v[206:209], v196 offset:4640
	ds_read_b128 v[214:217], v197 offset:36896
	s_waitcnt lgkmcnt(6)
	v_mfma_f32_32x32x16_bf16 v[52:67], v[174:177], v[210:213], v[52:67]
	s_waitcnt lgkmcnt(5)
	v_mfma_f32_32x32x16_bf16 v[36:51], v[174:177], v[218:221], v[36:51]
	s_waitcnt lgkmcnt(4)
	v_mfma_f32_32x32x16_bf16 v[4:19], v[202:205], v[218:221], v[4:19]
	s_waitcnt lgkmcnt(2)
	v_mfma_f32_32x32x16_bf16 v[36:51], v[178:181], v[222:225], v[36:51]
	s_waitcnt lgkmcnt(1)
	v_mfma_f32_32x32x16_bf16 v[4:19], v[206:209], v[222:225], v[4:19]
	ds_read_b128 v[222:225], v197 offset:41568
	ds_read_b128 v[174:177], v196 offset:4672
	v_mfma_f32_32x32x16_bf16 v[20:35], v[202:205], v[210:213], v[20:35]
	ds_read_b128 v[210:213], v196 offset:4704
	ds_read_b128 v[202:205], v196 offset:64
	s_waitcnt lgkmcnt(4)
	v_mfma_f32_32x32x16_bf16 v[52:67], v[178:181], v[214:217], v[52:67]
	ds_read_b128 v[218:221], v197 offset:36960
	ds_read_b128 v[178:181], v197 offset:41536
	v_mfma_f32_32x32x16_bf16 v[20:35], v[206:209], v[214:217], v[20:35]
	ds_read_b128 v[214:217], v197 offset:36928
	ds_read_b128 v[206:209], v196 offset:96
	s_waitcnt lgkmcnt(1)
	v_mfma_f32_32x32x16_bf16 v[52:67], v[202:205], v[214:217], v[52:67]
	v_mfma_f32_32x32x16_bf16 v[36:51], v[202:205], v[178:181], v[36:51]
	v_mfma_f32_32x32x16_bf16 v[20:35], v[174:177], v[214:217], v[20:35]
	v_mfma_f32_32x32x16_bf16 v[4:19], v[174:177], v[178:181], v[4:19]
	s_waitcnt lgkmcnt(0)
	v_mfma_f32_32x32x16_bf16 v[52:67], v[206:209], v[218:221], v[52:67]
	v_mfma_f32_32x32x16_bf16 v[36:51], v[206:209], v[222:225], v[36:51]
	v_mfma_f32_32x32x16_bf16 v[20:35], v[210:213], v[218:221], v[20:35]
	v_mfma_f32_32x32x16_bf16 v[4:19], v[210:213], v[222:225], v[4:19]
	s_waitcnt lgkmcnt(0)
	s_barrier
	s_nop 7
	s_nop 3
	s_branch .LBB0_53

; template <class Epi, class ColV>
; DI void gemm_tile(const bf16_t* __restrict__ A, int lda, const bf16_t* __restrict__ Bt, int ldb, int K, int m0, int n0, unsigned char* smem, Epi epi, ColV colv, const bf16_t* __restrict__ HYT = nullptr) {
;     ...
;     const int tid = get_tid(), lane = tid & 63, wave = tid >> 6, wr = wave >> 1, wc = wave & 1, li = lane & 31, lh = lane >> 5;
;     f32x16 acc[2][2];
; #pragma unroll
;     for (int a = 0; a < 2; ++a)
; #pragma unroll
;         for (int b = 0; b < 2; ++b) acc[a][b] = zero16();
;     u32x4 R0[8], R1[8];
;     const int nk = K >> 6;
;     auto gload = [&](u32x4 (&r)[8], int kt) {
; #pragma unroll
;         for (int i = 0; i < 4; ++i) { int id = tid + 256 * i, row = id >> 3, kc = id & 7;
;             if (HYT && kt >= 12) r[i] = *(const u32x4*)(HYT + (size_t)((kt - 12) * 64 + (id >> 4)) * NT + m0 + (id & 15) * 8);
;             else r[i] = *(const u32x4*)(A + (size_t)(m0 + row) * lda + kt * 64 + kc * 8);
;             r[4 + i] = *(const u32x4*)(Bt + (size_t)(n0 + row) * ldb + kt * 64 + kc * 8); }
;     };
;     auto sstore = [&](const u32x4 (&r)[8], int buf, int kt) {
; #pragma unroll
;         for (int i = 0; i < 4; ++i) { int id = tid + 256 * i, row = id >> 3, kc = id & 7;
;             if (HYT && kt >= 12) { const int kk = id >> 4, rr = (id & 15) * 8; bf16_t* d = As + (buf * 128 + rr) * LS + kk; const bf16x8 v = __builtin_bit_cast(bf16x8, r[i]);
; #pragma unroll
;                 for (int e = 0; e < 8; ++e) d[e * LS] = (bf16_t)v[e]; }
;             else *(u32x4*)(As + (buf * 128 + row) * LS + kc * 8) = r[i];
;             *(u32x4*)(Bs + (buf * 128 + row) * LS + kc * 8) = r[4 + i]; }
;     };
;     auto step = [&](int kt, u32x4 (&ldset)[8], const u32x4 (&stset)[8]) {
;         const int buf = kt & 1;
;         if (kt + 2 < nk) gload(ldset, kt + 2);
;         const bf16_t* Ab = As + (buf * 128 + 64 * wr + li) * LS + 8 * lh;
;         const bf16_t* Bb = Bs + (buf * 128 + 64 * wc + li) * LS + 8 * lh;
;         bf16x8 fa[2][2], fb[2][2], ga[2][2], gb[2][2];
; #pragma unroll
;         for (int k2 = 0; k2 < 2; ++k2) { fa[k2][0] = ld8(Ab + 16 * k2); fa[k2][1] = ld8(Ab + 32 * LS + 16 * k2); fb[k2][0] = ld8(Bb + 16 * k2); fb[k2][1] = ld8(Bb + 32 * LS + 16 * k2); }
;         __builtin_amdgcn_sched_barrier(0);
; #pragma unroll
;         for (int k2 = 0; k2 < 2; ++k2) {
.LBB0_1556:
	s_mul_hi_i32 s10, s14, 0x38e38e39
	s_lshr_b32 s11, s10, 31
	s_ashr_i32 s10, s10, 2
	s_add_i32 s10, s10, s11
	s_mul_i32 s11, s10, 18
	s_lshl_b32 s10, s10, 10
	v_mov_b32_e32 v28, v168
	s_or_b32 s18, s10, s76
	s_sub_i32 s11, s14, s11
	v_ashrrev_i32_e32 v29, 3, v28
	v_add_u32_e32 v0, s18, v29
	s_lshl_b32 s15, s11, 7
	v_ashrrev_i32_e32 v1, 31, v0
	v_readlane_b32 s10, v252, 8
	v_lshlrev_b64 v[4:5], 11, v[0:1]
	v_readlane_b32 s11, v252, 9
	v_lshlrev_b32_e32 v2, 4, v28
	v_add_u32_e32 v10, 0x100, v28
	v_add_u32_e32 v16, 0x200, v28
	v_add_u32_e32 v22, 0x300, v28
	v_lshl_add_u64 v[0:1], s[10:11], 0, v[4:5]
	v_and_b32_e32 v2, 0x70, v2
	v_ashrrev_i32_e32 v30, 3, v10
	v_ashrrev_i32_e32 v31, 3, v16
	v_ashrrev_i32_e32 v32, 3, v22
	v_lshl_add_u64 v[6:7], v[0:1], 0, v[2:3]
	v_add_u32_e32 v0, s15, v29
	v_add_u32_e32 v10, s18, v30
	v_add_u32_e32 v14, s15, v30
	v_add_u32_e32 v16, s18, v31
	v_add_u32_e32 v20, s15, v31
	v_add_u32_e32 v22, s18, v32
	v_add_u32_e32 v26, s15, v32
	v_ashrrev_i32_e32 v1, 31, v0
	v_ashrrev_i32_e32 v11, 31, v10
	v_ashrrev_i32_e32 v15, 31, v14
	v_ashrrev_i32_e32 v17, 31, v16
	v_ashrrev_i32_e32 v21, 31, v20
	v_ashrrev_i32_e32 v23, 31, v22
	v_ashrrev_i32_e32 v27, 31, v26
	v_lshlrev_b64 v[0:1], 11, v[0:1]
	v_lshlrev_b64 v[10:11], 11, v[10:11]
	v_lshlrev_b64 v[14:15], 11, v[14:15]
	v_lshlrev_b64 v[16:17], 11, v[16:17]
	v_lshlrev_b64 v[20:21], 11, v[20:21]
	v_lshlrev_b64 v[22:23], 11, v[22:23]
	v_lshlrev_b64 v[26:27], 11, v[26:27]
	v_lshl_add_u64 v[0:1], s[0:1], 0, v[0:1]
	v_lshl_add_u64 v[12:13], s[10:11], 0, v[10:11]
	v_lshl_add_u64 v[132:133], s[0:1], 0, v[14:15]
	v_lshl_add_u64 v[18:19], s[10:11], 0, v[16:17]
	v_lshl_add_u64 v[134:135], s[0:1], 0, v[20:21]
	v_lshl_add_u64 v[24:25], s[10:11], 0, v[22:23]
	v_lshl_add_u64 v[136:137], s[0:1], 0, v[26:27]
	v_lshl_add_u64 v[8:9], v[0:1], 0, v[2:3]
	v_lshl_add_u64 v[12:13], v[12:13], 0, v[2:3]
	v_lshl_add_u64 v[14:15], v[132:133], 0, v[2:3]
	v_lshl_add_u64 v[18:19], v[18:19], 0, v[2:3]
	v_lshl_add_u64 v[20:21], v[134:135], 0, v[2:3]
	v_lshl_add_u64 v[24:25], v[24:25], 0, v[2:3]
	v_lshl_add_u64 v[26:27], v[136:137], 0, v[2:3]
	global_load_dwordx4 v[68:71], v[6:7], off
	global_load_dwordx4 v[72:75], v[8:9], off
	global_load_dwordx4 v[76:79], v[12:13], off
	global_load_dwordx4 v[80:83], v[14:15], off
	global_load_dwordx4 v[84:87], v[18:19], off
	global_load_dwordx4 v[88:91], v[20:21], off
	global_load_dwordx4 v[92:95], v[24:25], off
	global_load_dwordx4 v[104:107], v[26:27], off
	global_load_dwordx4 v[96:99], v[6:7], off offset:128
	global_load_dwordx4 v[108:111], v[12:13], off offset:128
	global_load_dwordx4 v[116:119], v[18:19], off offset:128
	global_load_dwordx4 v[124:127], v[24:25], off offset:128
	global_load_dwordx4 v[100:103], v[8:9], off offset:128
	global_load_dwordx4 v[112:115], v[14:15], off offset:128
	global_load_dwordx4 v[120:123], v[20:21], off offset:128
	global_load_dwordx4 v[128:131], v[26:27], off offset:128
	v_ashrrev_i32_e32 v6, 1, v28
	v_and_b32_e32 v151, 31, v28
	v_and_b32_e32 v193, 0xffffffc0, v6
	v_bfe_u32 v166, v28, 5, 1
	v_or_b32_e32 v6, v193, v151
	v_mul_lo_u32 v6, v6, s6
	v_lshlrev_b32_e32 v7, 4, v166
	v_add3_u32 v194, 0, v6, v7
	v_and_b32_e32 v6, 0x5f, v28
	v_mul_u32_u24_e32 v6, 0x90, v6
	v_and_b32_e32 v148, 64, v28
	v_mul_lo_u32 v29, v29, s6
	v_mul_lo_u32 v30, v30, s6
	v_mul_lo_u32 v31, v31, s6
	v_mul_lo_u32 v32, v32, s6
	v_add3_u32 v195, 0, v6, v7
	v_or_b32_e32 v6, 0x80, v151
	v_add3_u32 v167, 0, v29, v2
	v_add3_u32 v190, 0, v30, v2
	v_add3_u32 v191, 0, v31, v2
	v_add3_u32 v192, 0, v32, v2
	v_add_u32_e32 v8, v6, v193
	v_or_b32_e32 v6, v6, v148
	v_add_u32_e32 v2, 0, v2
	v_mul_lo_u32 v8, v8, s6
	v_mul_u32_u24_e32 v6, 0x90, v6
	v_add_u32_e32 v198, v2, v29
	v_add_u32_e32 v199, v2, v30
	v_add_u32_e32 v200, v2, v31
	v_add_u32_e32 v201, v2, v32
	v_and_b32_e32 v2, 7, v28
	v_lshl_add_u64 v[144:145], s[26:27], 0, v[4:5]
	v_add3_u32 v196, 0, v8, v7
	v_add3_u32 v197, 0, v6, v7
	v_lshlrev_b32_e32 v2, 4, v2
	v_lshl_add_u64 v[138:139], s[26:27], 0, v[22:23]
	v_lshl_add_u64 v[140:141], s[26:27], 0, v[16:17]
	v_lshl_add_u64 v[142:143], s[26:27], 0, v[10:11]
	s_mov_b32 s19, 0
	s_waitcnt vmcnt(33)
	s_waitcnt vmcnt(32)
	s_waitcnt vmcnt(15)
	ds_write_b128 v167, v[68:71]
	s_waitcnt vmcnt(14)
	ds_write_b128 v167, v[72:75] offset:36864
	s_waitcnt vmcnt(13)
	ds_write_b128 v190, v[76:79]
	s_waitcnt vmcnt(12)
	ds_write_b128 v190, v[80:83] offset:36864
	s_waitcnt vmcnt(11)
	ds_write_b128 v191, v[84:87]
	s_waitcnt vmcnt(10)
	ds_write_b128 v191, v[88:91] offset:36864
	s_waitcnt vmcnt(9)
	ds_write_b128 v192, v[92:95]
	s_waitcnt vmcnt(8)
	ds_write_b128 v192, v[104:107] offset:36864
	s_waitcnt lgkmcnt(0)
	s_barrier
	s_branch .LBB0_1558
; #define MFMA(a, b, c) __builtin_amdgcn_mfma_f32_32x32x16_bf16((a), (b), (c), 0, 0, 0)
; template <class Epi, class ColV>
; DI void gemm_tile(const bf16_t* __restrict__ A, int lda, const bf16_t* __restrict__ Bt, int ldb, int K, int m0, int n0, unsigned char* smem, Epi epi, ColV colv, const bf16_t* __restrict__ HYT = nullptr) {
;     ...
;     auto step = [&](int kt, u32x4 (&ldset)[8], const u32x4 (&stset)[8]) {
;         const int buf = kt & 1;
;         if (kt + 2 < nk) gload(ldset, kt + 2);
;         const bf16_t* Ab = As + (buf * 128 + 64 * wr + li) * LS + 8 * lh;
;         const bf16_t* Bb = Bs + (buf * 128 + 64 * wc + li) * LS + 8 * lh;
;         bf16x8 fa[2][2], fb[2][2], ga[2][2], gb[2][2];
; #pragma unroll
;         for (int k2 = 0; k2 < 2; ++k2) { fa[k2][0] = ld8(Ab + 16 * k2); fa[k2][1] = ld8(Ab + 32 * LS + 16 * k2); fb[k2][0] = ld8(Bb + 16 * k2); fb[k2][1] = ld8(Bb + 32 * LS + 16 * k2); }
;         __builtin_amdgcn_sched_barrier(0);
; #pragma unroll
;         for (int k2 = 0; k2 < 2; ++k2) {
;             acc[0][0] = MFMA(fa[k2][0], fb[k2][0], acc[0][0]); acc[0][1] = MFMA(fa[k2][0], fb[k2][1], acc[0][1]);
;             acc[1][0] = MFMA(fa[k2][1], fb[k2][0], acc[1][0]); acc[1][1] = MFMA(fa[k2][1], fb[k2][1], acc[1][1]);
;         }
; #pragma unroll
;         for (int k2 = 0; k2 < 2; ++k2) { const int ks = 2 + k2; ga[k2][0] = ld8(Ab + 16 * ks); ga[k2][1] = ld8(Ab + 32 * LS + 16 * ks); gb[k2][0] = ld8(Bb + 16 * ks); gb[k2][1] = ld8(Bb + 32 * LS + 16 * ks); }
; #pragma unroll
;         for (int k2 = 0; k2 < 2; ++k2) {
;             acc[0][0] = MFMA(ga[k2][0], gb[k2][0], acc[0][0]); acc[0][1] = MFMA(ga[k2][0], gb[k2][1], acc[0][1]);
;             acc[1][0] = MFMA(ga[k2][1], gb[k2][0], acc[1][0]); acc[1][1] = MFMA(ga[k2][1], gb[k2][1], acc[1][1]);
;         }
;         if (kt + 1 < nk) sstore(stset, buf ^ 1, kt + 1);
; #pragma unroll
;         for (int i = 0; i < 8; ++i) { __builtin_amdgcn_sched_group_barrier(0x008, 1, 0); __builtin_amdgcn_sched_group_barrier(0x100, 1, 0); }
; #pragma unroll
;         for (int i = 0; i < 8; ++i) { __builtin_amdgcn_sched_group_barrier(0x008, 1, 0); __builtin_amdgcn_sched_group_barrier(0x200, 1, 0); }
;         __builtin_amdgcn_sched_barrier(0);
;         __syncthreads();
;     };
.LBB0_1558:
	s_cmp_lt_u32 s19, 14
	s_cselect_b64 s[12:13], -1, 0
	s_cmp_gt_u32 s19, 13
	s_cselect_b64 s[10:11], -1, 0
	s_and_b64 vcc, exec, s[10:11]
	v_lshl_add_u64 v[164:165], v[144:145], 0, v[2:3]
	v_lshl_add_u64 v[162:163], v[0:1], 0, v[2:3]
	v_lshl_add_u64 v[160:161], v[142:143], 0, v[2:3]
	v_lshl_add_u64 v[158:159], v[132:133], 0, v[2:3]
	v_lshl_add_u64 v[156:157], v[140:141], 0, v[2:3]
	v_lshl_add_u64 v[154:155], v[134:135], 0, v[2:3]
	v_lshl_add_u64 v[152:153], v[138:139], 0, v[2:3]
	v_lshl_add_u64 v[146:147], v[136:137], 0, v[2:3]
	s_mov_b32 s100, 0x26ca000
	s_mov_b32 s101, 0
	v_lshl_add_u64 v[164:165], v[164:165], 0, s[100:101]
	v_lshl_add_u64 v[160:161], v[160:161], 0, s[100:101]
	v_lshl_add_u64 v[156:157], v[156:157], 0, s[100:101]
	v_lshl_add_u64 v[152:153], v[152:153], 0, s[100:101]
	ds_read_b128 v[202:205], v194
	ds_read_b128 v[218:221], v195 offset:36864
	ds_read_b128 v[226:229], v195 offset:41472
	ds_read_b128 v[210:213], v194 offset:4608
	ds_read_b128 v[206:209], v194 offset:32
	ds_read_b128 v[230:233], v195 offset:41504
	ds_read_b128 v[214:217], v194 offset:4640
	ds_read_b128 v[222:225], v195 offset:36896
	s_waitcnt lgkmcnt(6)
	v_mfma_f32_32x32x16_bf16 v[52:67], v[202:205], v[218:221], 0
	global_load_dwordx4 v[132:135], v[164:165], off offset:256
	global_load_dwordx4 v[136:139], v[162:163], off offset:256
	s_waitcnt lgkmcnt(5)
	v_mfma_f32_32x32x16_bf16 v[36:51], v[202:205], v[226:229], 0
	global_load_dwordx4 v[140:143], v[160:161], off offset:256
	global_load_dwordx4 v[198:201], v[158:159], off offset:256
	s_waitcnt lgkmcnt(4)
	v_mfma_f32_32x32x16_bf16 v[4:19], v[210:213], v[226:229], 0
	global_load_dwordx4 v[174:177], v[156:157], off offset:256
	global_load_dwordx4 v[178:181], v[154:155], off offset:256
	s_waitcnt lgkmcnt(2)
	v_mfma_f32_32x32x16_bf16 v[36:51], v[206:209], v[230:233], v[36:51]
	global_load_dwordx4 v[242:245], v[152:153], off offset:256
	global_load_dwordx4 v[246:249], v[146:147], off offset:256
	s_waitcnt lgkmcnt(1)
	v_mfma_f32_32x32x16_bf16 v[4:19], v[214:217], v[230:233], v[4:19]
	global_load_dwordx4 v[68:71], v[164:165], off offset:384
	global_load_dwordx4 v[72:75], v[162:163], off offset:384
	ds_read_b128 v[230:233], v195 offset:41568
	ds_read_b128 v[202:205], v194 offset:4672
	v_mfma_f32_32x32x16_bf16 v[20:35], v[210:213], v[218:221], 0
	global_load_dwordx4 v[76:79], v[160:161], off offset:384
	global_load_dwordx4 v[80:83], v[158:159], off offset:384
	ds_read_b128 v[218:221], v194 offset:4704
	ds_read_b128 v[210:213], v194 offset:64
	s_waitcnt lgkmcnt(4)
	v_mfma_f32_32x32x16_bf16 v[52:67], v[206:209], v[222:225], v[52:67]
	global_load_dwordx4 v[84:87], v[156:157], off offset:384
	global_load_dwordx4 v[88:91], v[154:155], off offset:384
	ds_read_b128 v[226:229], v195 offset:36960
	ds_read_b128 v[206:209], v195 offset:41536
	v_mfma_f32_32x32x16_bf16 v[20:35], v[214:217], v[222:225], v[20:35]
	global_load_dwordx4 v[92:95], v[152:153], off offset:384
	global_load_dwordx4 v[104:107], v[146:147], off offset:384
	ds_read_b128 v[222:225], v195 offset:36928
	ds_read_b128 v[214:217], v194 offset:96
	s_waitcnt lgkmcnt(1)
	v_mfma_f32_32x32x16_bf16 v[52:67], v[210:213], v[222:225], v[52:67]
	s_waitcnt vmcnt(16)
	ds_write_b128 v167, v[96:99] offset:18432
	v_mfma_f32_32x32x16_bf16 v[36:51], v[210:213], v[206:209], v[36:51]
	ds_write_b128 v167, v[100:103] offset:55296
	v_mfma_f32_32x32x16_bf16 v[20:35], v[202:205], v[222:225], v[20:35]
	ds_write_b128 v190, v[108:111] offset:18432
	v_mfma_f32_32x32x16_bf16 v[4:19], v[202:205], v[206:209], v[4:19]
	ds_write_b128 v190, v[112:115] offset:55296
	s_waitcnt lgkmcnt(4)
	v_mfma_f32_32x32x16_bf16 v[52:67], v[214:217], v[226:229], v[52:67]
	ds_write_b128 v191, v[116:119] offset:18432
	v_mfma_f32_32x32x16_bf16 v[36:51], v[214:217], v[230:233], v[36:51]
	ds_write_b128 v191, v[120:123] offset:55296
	v_mfma_f32_32x32x16_bf16 v[20:35], v[218:221], v[226:229], v[20:35]
	ds_write_b128 v192, v[124:127] offset:18432
	v_mfma_f32_32x32x16_bf16 v[4:19], v[218:221], v[230:233], v[4:19]
	ds_write_b128 v192, v[128:131] offset:55296
	s_waitcnt lgkmcnt(0)
	s_barrier
	ds_read_b128 v[202:205], v196
	ds_read_b128 v[218:221], v197 offset:36864
	ds_read_b128 v[226:229], v197 offset:41472
	ds_read_b128 v[210:213], v196 offset:4608
	ds_read_b128 v[206:209], v196 offset:32
	ds_read_b128 v[230:233], v197 offset:41504
	ds_read_b128 v[214:217], v196 offset:4640
	ds_read_b128 v[222:225], v197 offset:36896
	s_waitcnt lgkmcnt(6)
	v_mfma_f32_32x32x16_bf16 v[52:67], v[202:205], v[218:221], v[52:67]
	global_load_dwordx4 v[96:99], v[164:165], off offset:512
	s_waitcnt lgkmcnt(5)
	v_mfma_f32_32x32x16_bf16 v[36:51], v[202:205], v[226:229], v[36:51]
	global_load_dwordx4 v[100:103], v[162:163], off offset:512
	s_waitcnt lgkmcnt(4)
	v_mfma_f32_32x32x16_bf16 v[4:19], v[210:213], v[226:229], v[4:19]
	global_load_dwordx4 v[108:111], v[160:161], off offset:512
	s_waitcnt lgkmcnt(2)
	v_mfma_f32_32x32x16_bf16 v[36:51], v[206:209], v[230:233], v[36:51]
	global_load_dwordx4 v[112:115], v[158:159], off offset:512
	s_waitcnt lgkmcnt(1)
	v_mfma_f32_32x32x16_bf16 v[4:19], v[214:217], v[230:233], v[4:19]
	global_load_dwordx4 v[116:119], v[156:157], off offset:512
	ds_read_b128 v[230:233], v197 offset:41568
	ds_read_b128 v[202:205], v196 offset:4672
	v_mfma_f32_32x32x16_bf16 v[20:35], v[210:213], v[218:221], v[20:35]
	global_load_dwordx4 v[120:123], v[154:155], off offset:512
	ds_read_b128 v[218:221], v196 offset:4704
	ds_read_b128 v[210:213], v196 offset:64
	s_waitcnt lgkmcnt(4)
	v_mfma_f32_32x32x16_bf16 v[52:67], v[206:209], v[222:225], v[52:67]
	global_load_dwordx4 v[124:127], v[152:153], off offset:512
	ds_read_b128 v[226:229], v197 offset:36960
	ds_read_b128 v[206:209], v197 offset:41536
	v_mfma_f32_32x32x16_bf16 v[20:35], v[214:217], v[222:225], v[20:35]
	global_load_dwordx4 v[128:131], v[146:147], off offset:512
	ds_read_b128 v[222:225], v197 offset:36928
	ds_read_b128 v[214:217], v196 offset:96
	s_waitcnt lgkmcnt(1)
	v_mfma_f32_32x32x16_bf16 v[52:67], v[210:213], v[222:225], v[52:67]
	s_waitcnt vmcnt(23)
	ds_write_b128 v167, v[132:135]
	v_mfma_f32_32x32x16_bf16 v[36:51], v[210:213], v[206:209], v[36:51]
	s_waitcnt vmcnt(22)
	ds_write_b128 v167, v[136:139] offset:36864
	v_mfma_f32_32x32x16_bf16 v[20:35], v[202:205], v[222:225], v[20:35]
	s_waitcnt vmcnt(21)
	ds_write_b128 v190, v[140:143]
	v_mfma_f32_32x32x16_bf16 v[4:19], v[202:205], v[206:209], v[4:19]
	s_waitcnt vmcnt(20)
	ds_write_b128 v190, v[198:201] offset:36864
	s_waitcnt lgkmcnt(4)
	v_mfma_f32_32x32x16_bf16 v[52:67], v[214:217], v[226:229], v[52:67]
	s_waitcnt vmcnt(19)
	ds_write_b128 v191, v[174:177]
	v_mfma_f32_32x32x16_bf16 v[36:51], v[214:217], v[230:233], v[36:51]
	s_waitcnt vmcnt(18)
	ds_write_b128 v191, v[178:181] offset:36864
	v_mfma_f32_32x32x16_bf16 v[20:35], v[218:221], v[226:229], v[20:35]
	s_waitcnt vmcnt(17)
	ds_write_b128 v192, v[242:245]
	v_mfma_f32_32x32x16_bf16 v[4:19], v[218:221], v[230:233], v[4:19]
	s_waitcnt vmcnt(16)
	ds_write_b128 v192, v[246:249] offset:36864
	s_waitcnt lgkmcnt(0)
	s_barrier
; #define MFMA(a, b, c) __builtin_amdgcn_mfma_f32_32x32x16_bf16((a), (b), (c), 0, 0, 0)
; template <class Epi, class ColV>
; DI void gemm_tile(const bf16_t* __restrict__ A, int lda, const bf16_t* __restrict__ Bt, int ldb, int K, int m0, int n0, unsigned char* smem, Epi epi, ColV colv, const bf16_t* __restrict__ HYT = nullptr) {
;     ...
;     auto step = [&](int kt, u32x4 (&ldset)[8], const u32x4 (&stset)[8]) {
;         const int buf = kt & 1;
;         if (kt + 2 < nk) gload(ldset, kt + 2);
;         const bf16_t* Ab = As + (buf * 128 + 64 * wr + li) * LS + 8 * lh;
;         const bf16_t* Bb = Bs + (buf * 128 + 64 * wc + li) * LS + 8 * lh;
;         bf16x8 fa[2][2], fb[2][2], ga[2][2], gb[2][2];
; #pragma unroll
;         for (int k2 = 0; k2 < 2; ++k2) { fa[k2][0] = ld8(Ab + 16 * k2); fa[k2][1] = ld8(Ab + 32 * LS + 16 * k2); fb[k2][0] = ld8(Bb + 16 * k2); fb[k2][1] = ld8(Bb + 32 * LS + 16 * k2); }
;         __builtin_amdgcn_sched_barrier(0);
; #pragma unroll
;         for (int k2 = 0; k2 < 2; ++k2) {
;             acc[0][0] = MFMA(fa[k2][0], fb[k2][0], acc[0][0]); acc[0][1] = MFMA(fa[k2][0], fb[k2][1], acc[0][1]);
;             acc[1][0] = MFMA(fa[k2][1], fb[k2][0], acc[1][0]); acc[1][1] = MFMA(fa[k2][1], fb[k2][1], acc[1][1]);
;         }
; #pragma unroll
;         for (int k2 = 0; k2 < 2; ++k2) { const int ks = 2 + k2; ga[k2][0] = ld8(Ab + 16 * ks); ga[k2][1] = ld8(Ab + 32 * LS + 16 * ks); gb[k2][0] = ld8(Bb + 16 * ks); gb[k2][1] = ld8(Bb + 32 * LS + 16 * ks); }
; #pragma unroll
;         for (int k2 = 0; k2 < 2; ++k2) {
;             acc[0][0] = MFMA(ga[k2][0], gb[k2][0], acc[0][0]); acc[0][1] = MFMA(ga[k2][0], gb[k2][1], acc[0][1]);
;             acc[1][0] = MFMA(ga[k2][1], gb[k2][0], acc[1][0]); acc[1][1] = MFMA(ga[k2][1], gb[k2][1], acc[1][1]);
;         }
;         if (kt + 1 < nk) sstore(stset, buf ^ 1, kt + 1);
; #pragma unroll
;         for (int i = 0; i < 8; ++i) { __builtin_amdgcn_sched_group_barrier(0x008, 1, 0); __builtin_amdgcn_sched_group_barrier(0x100, 1, 0); }
; #pragma unroll
;         for (int i = 0; i < 8; ++i) { __builtin_amdgcn_sched_group_barrier(0x008, 1, 0); __builtin_amdgcn_sched_group_barrier(0x200, 1, 0); }
;         __builtin_amdgcn_sched_barrier(0);
;         __syncthreads();
	ds_read_b128 v[202:205], v194
	ds_read_b128 v[218:221], v195 offset:36864
	ds_read_b128 v[226:229], v195 offset:41472
	ds_read_b128 v[210:213], v194 offset:4608
	ds_read_b128 v[206:209], v194 offset:32
	ds_read_b128 v[230:233], v195 offset:41504
	ds_read_b128 v[214:217], v194 offset:4640
	ds_read_b128 v[222:225], v195 offset:36896
	s_waitcnt lgkmcnt(6)
	v_mfma_f32_32x32x16_bf16 v[52:67], v[202:205], v[218:221], v[52:67]
	global_load_dwordx4 v[132:135], v[164:165], off offset:640
	s_waitcnt lgkmcnt(5)
	v_mfma_f32_32x32x16_bf16 v[36:51], v[202:205], v[226:229], v[36:51]
	global_load_dwordx4 v[136:139], v[162:163], off offset:640
	s_waitcnt lgkmcnt(4)
	v_mfma_f32_32x32x16_bf16 v[4:19], v[210:213], v[226:229], v[4:19]
	global_load_dwordx4 v[140:143], v[160:161], off offset:640
	s_waitcnt lgkmcnt(2)
	v_mfma_f32_32x32x16_bf16 v[36:51], v[206:209], v[230:233], v[36:51]
	global_load_dwordx4 v[198:201], v[158:159], off offset:640
	s_waitcnt lgkmcnt(1)
	v_mfma_f32_32x32x16_bf16 v[4:19], v[214:217], v[230:233], v[4:19]
	global_load_dwordx4 v[174:177], v[156:157], off offset:640
	ds_read_b128 v[230:233], v195 offset:41568
	ds_read_b128 v[202:205], v194 offset:4672
	v_mfma_f32_32x32x16_bf16 v[20:35], v[210:213], v[218:221], v[20:35]
	global_load_dwordx4 v[178:181], v[154:155], off offset:640
	ds_read_b128 v[218:221], v194 offset:4704
	ds_read_b128 v[210:213], v194 offset:64
	s_waitcnt lgkmcnt(4)
	v_mfma_f32_32x32x16_bf16 v[52:67], v[206:209], v[222:225], v[52:67]
	global_load_dwordx4 v[242:245], v[152:153], off offset:640
	ds_read_b128 v[226:229], v195 offset:36960
	ds_read_b128 v[206:209], v195 offset:41536
	v_mfma_f32_32x32x16_bf16 v[20:35], v[214:217], v[222:225], v[20:35]
	global_load_dwordx4 v[246:249], v[146:147], off offset:640
	ds_read_b128 v[222:225], v195 offset:36928
	ds_read_b128 v[214:217], v194 offset:96
	s_waitcnt lgkmcnt(1)
	v_mfma_f32_32x32x16_bf16 v[52:67], v[210:213], v[222:225], v[52:67]
	s_waitcnt vmcnt(23)
	ds_write_b128 v167, v[68:71] offset:18432
	v_mfma_f32_32x32x16_bf16 v[36:51], v[210:213], v[206:209], v[36:51]
	s_waitcnt vmcnt(22)
	ds_write_b128 v167, v[72:75] offset:55296
	v_mfma_f32_32x32x16_bf16 v[20:35], v[202:205], v[222:225], v[20:35]
	s_waitcnt vmcnt(21)
	ds_write_b128 v190, v[76:79] offset:18432
	v_mfma_f32_32x32x16_bf16 v[4:19], v[202:205], v[206:209], v[4:19]
	s_waitcnt vmcnt(20)
	ds_write_b128 v190, v[80:83] offset:55296
	s_waitcnt lgkmcnt(4)
	v_mfma_f32_32x32x16_bf16 v[52:67], v[214:217], v[226:229], v[52:67]
	s_waitcnt vmcnt(19)
	ds_write_b128 v191, v[84:87] offset:18432
	v_mfma_f32_32x32x16_bf16 v[36:51], v[214:217], v[230:233], v[36:51]
	s_waitcnt vmcnt(18)
	ds_write_b128 v191, v[88:91] offset:55296
	v_mfma_f32_32x32x16_bf16 v[20:35], v[218:221], v[226:229], v[20:35]
	s_waitcnt vmcnt(17)
	ds_write_b128 v192, v[92:95] offset:18432
	v_mfma_f32_32x32x16_bf16 v[4:19], v[218:221], v[230:233], v[4:19]
	s_waitcnt vmcnt(16)
	ds_write_b128 v192, v[104:107] offset:55296
	s_waitcnt lgkmcnt(0)
	s_barrier
	ds_read_b128 v[202:205], v196
	ds_read_b128 v[218:221], v197 offset:36864
	ds_read_b128 v[226:229], v197 offset:41472
	ds_read_b128 v[210:213], v196 offset:4608
	ds_read_b128 v[206:209], v196 offset:32
	ds_read_b128 v[230:233], v197 offset:41504
	ds_read_b128 v[214:217], v196 offset:4640
	ds_read_b128 v[222:225], v197 offset:36896
	s_waitcnt lgkmcnt(6)
	v_mfma_f32_32x32x16_bf16 v[52:67], v[202:205], v[218:221], v[52:67]
	global_load_dwordx4 v[68:71], v[164:165], off offset:768
	s_waitcnt lgkmcnt(5)
	v_mfma_f32_32x32x16_bf16 v[36:51], v[202:205], v[226:229], v[36:51]
	global_load_dwordx4 v[72:75], v[162:163], off offset:768
	s_waitcnt lgkmcnt(4)
	v_mfma_f32_32x32x16_bf16 v[4:19], v[210:213], v[226:229], v[4:19]
	global_load_dwordx4 v[76:79], v[160:161], off offset:768
	s_waitcnt lgkmcnt(2)
	v_mfma_f32_32x32x16_bf16 v[36:51], v[206:209], v[230:233], v[36:51]
	global_load_dwordx4 v[80:83], v[158:159], off offset:768
	s_waitcnt lgkmcnt(1)
	v_mfma_f32_32x32x16_bf16 v[4:19], v[214:217], v[230:233], v[4:19]
	global_load_dwordx4 v[84:87], v[156:157], off offset:768
	ds_read_b128 v[230:233], v197 offset:41568
	ds_read_b128 v[202:205], v196 offset:4672
	v_mfma_f32_32x32x16_bf16 v[20:35], v[210:213], v[218:221], v[20:35]
	global_load_dwordx4 v[88:91], v[154:155], off offset:768
	ds_read_b128 v[218:221], v196 offset:4704
	ds_read_b128 v[210:213], v196 offset:64
	s_waitcnt lgkmcnt(4)
	v_mfma_f32_32x32x16_bf16 v[52:67], v[206:209], v[222:225], v[52:67]
	global_load_dwordx4 v[92:95], v[152:153], off offset:768
	ds_read_b128 v[226:229], v197 offset:36960
	ds_read_b128 v[206:209], v197 offset:41536
	v_mfma_f32_32x32x16_bf16 v[20:35], v[214:217], v[222:225], v[20:35]
	global_load_dwordx4 v[104:107], v[146:147], off offset:768
	ds_read_b128 v[222:225], v197 offset:36928
	ds_read_b128 v[214:217], v196 offset:96
	s_waitcnt lgkmcnt(1)
	v_mfma_f32_32x32x16_bf16 v[52:67], v[210:213], v[222:225], v[52:67]
	s_waitcnt vmcnt(23)
	ds_write_b128 v167, v[96:99]
	v_mfma_f32_32x32x16_bf16 v[36:51], v[210:213], v[206:209], v[36:51]
	s_waitcnt vmcnt(22)
	ds_write_b128 v167, v[100:103] offset:36864
	v_mfma_f32_32x32x16_bf16 v[20:35], v[202:205], v[222:225], v[20:35]
	s_waitcnt vmcnt(21)
	ds_write_b128 v190, v[108:111]
	v_mfma_f32_32x32x16_bf16 v[4:19], v[202:205], v[206:209], v[4:19]
	s_waitcnt vmcnt(20)
	ds_write_b128 v190, v[112:115] offset:36864
	s_waitcnt lgkmcnt(4)
	v_mfma_f32_32x32x16_bf16 v[52:67], v[214:217], v[226:229], v[52:67]
	s_waitcnt vmcnt(19)
	ds_write_b128 v191, v[116:119]
	v_mfma_f32_32x32x16_bf16 v[36:51], v[214:217], v[230:233], v[36:51]
	s_waitcnt vmcnt(18)
	ds_write_b128 v191, v[120:123] offset:36864
	v_mfma_f32_32x32x16_bf16 v[20:35], v[218:221], v[226:229], v[20:35]
	s_waitcnt vmcnt(17)
	ds_write_b128 v192, v[124:127]
	v_mfma_f32_32x32x16_bf16 v[4:19], v[218:221], v[230:233], v[4:19]
	s_waitcnt vmcnt(16)
	ds_write_b128 v192, v[128:131] offset:36864
	s_waitcnt lgkmcnt(0)
	s_barrier
; #define MFMA(a, b, c) __builtin_amdgcn_mfma_f32_32x32x16_bf16((a), (b), (c), 0, 0, 0)
; template <class Epi, class ColV>
; DI void gemm_tile(const bf16_t* __restrict__ A, int lda, const bf16_t* __restrict__ Bt, int ldb, int K, int m0, int n0, unsigned char* smem, Epi epi, ColV colv, const bf16_t* __restrict__ HYT = nullptr) {
;     ...
;     auto step = [&](int kt, u32x4 (&ldset)[8], const u32x4 (&stset)[8]) {
;         const int buf = kt & 1;
;         if (kt + 2 < nk) gload(ldset, kt + 2);
;         const bf16_t* Ab = As + (buf * 128 + 64 * wr + li) * LS + 8 * lh;
;         const bf16_t* Bb = Bs + (buf * 128 + 64 * wc + li) * LS + 8 * lh;
;         bf16x8 fa[2][2], fb[2][2], ga[2][2], gb[2][2];
; #pragma unroll
;         for (int k2 = 0; k2 < 2; ++k2) { fa[k2][0] = ld8(Ab + 16 * k2); fa[k2][1] = ld8(Ab + 32 * LS + 16 * k2); fb[k2][0] = ld8(Bb + 16 * k2); fb[k2][1] = ld8(Bb + 32 * LS + 16 * k2); }
;         __builtin_amdgcn_sched_barrier(0);
; #pragma unroll
;         for (int k2 = 0; k2 < 2; ++k2) {
;             acc[0][0] = MFMA(fa[k2][0], fb[k2][0], acc[0][0]); acc[0][1] = MFMA(fa[k2][0], fb[k2][1], acc[0][1]);
;             acc[1][0] = MFMA(fa[k2][1], fb[k2][0], acc[1][0]); acc[1][1] = MFMA(fa[k2][1], fb[k2][1], acc[1][1]);
;         }
; #pragma unroll
;         for (int k2 = 0; k2 < 2; ++k2) { const int ks = 2 + k2; ga[k2][0] = ld8(Ab + 16 * ks); ga[k2][1] = ld8(Ab + 32 * LS + 16 * ks); gb[k2][0] = ld8(Bb + 16 * ks); gb[k2][1] = ld8(Bb + 32 * LS + 16 * ks); }
; #pragma unroll
;         for (int k2 = 0; k2 < 2; ++k2) {
;             acc[0][0] = MFMA(ga[k2][0], gb[k2][0], acc[0][0]); acc[0][1] = MFMA(ga[k2][0], gb[k2][1], acc[0][1]);
;             acc[1][0] = MFMA(ga[k2][1], gb[k2][0], acc[1][0]); acc[1][1] = MFMA(ga[k2][1], gb[k2][1], acc[1][1]);
;         }
;         if (kt + 1 < nk) sstore(stset, buf ^ 1, kt + 1);
; #pragma unroll
;         for (int i = 0; i < 8; ++i) { __builtin_amdgcn_sched_group_barrier(0x008, 1, 0); __builtin_amdgcn_sched_group_barrier(0x100, 1, 0); }
; #pragma unroll
;         for (int i = 0; i < 8; ++i) { __builtin_amdgcn_sched_group_barrier(0x008, 1, 0); __builtin_amdgcn_sched_group_barrier(0x200, 1, 0); }
;         __builtin_amdgcn_sched_barrier(0);
;         __syncthreads();
	ds_read_b128 v[202:205], v194
	ds_read_b128 v[218:221], v195 offset:36864
	ds_read_b128 v[226:229], v195 offset:41472
	ds_read_b128 v[210:213], v194 offset:4608
	ds_read_b128 v[206:209], v194 offset:32
	ds_read_b128 v[230:233], v195 offset:41504
	ds_read_b128 v[214:217], v194 offset:4640
	ds_read_b128 v[222:225], v195 offset:36896
	s_waitcnt lgkmcnt(6)
	v_mfma_f32_32x32x16_bf16 v[52:67], v[202:205], v[218:221], v[52:67]
	global_load_dwordx4 v[96:99], v[164:165], off offset:896
	s_waitcnt lgkmcnt(5)
	v_mfma_f32_32x32x16_bf16 v[36:51], v[202:205], v[226:229], v[36:51]
	global_load_dwordx4 v[100:103], v[162:163], off offset:896
	s_waitcnt lgkmcnt(4)
	v_mfma_f32_32x32x16_bf16 v[4:19], v[210:213], v[226:229], v[4:19]
	global_load_dwordx4 v[108:111], v[160:161], off offset:896
	s_waitcnt lgkmcnt(2)
	v_mfma_f32_32x32x16_bf16 v[36:51], v[206:209], v[230:233], v[36:51]
	global_load_dwordx4 v[112:115], v[158:159], off offset:896
	s_waitcnt lgkmcnt(1)
	v_mfma_f32_32x32x16_bf16 v[4:19], v[214:217], v[230:233], v[4:19]
	global_load_dwordx4 v[116:119], v[156:157], off offset:896
	ds_read_b128 v[230:233], v195 offset:41568
	ds_read_b128 v[202:205], v194 offset:4672
	v_mfma_f32_32x32x16_bf16 v[20:35], v[210:213], v[218:221], v[20:35]
	global_load_dwordx4 v[120:123], v[154:155], off offset:896
	ds_read_b128 v[218:221], v194 offset:4704
	ds_read_b128 v[210:213], v194 offset:64
	s_waitcnt lgkmcnt(4)
	v_mfma_f32_32x32x16_bf16 v[52:67], v[206:209], v[222:225], v[52:67]
	global_load_dwordx4 v[124:127], v[152:153], off offset:896
	ds_read_b128 v[226:229], v195 offset:36960
	ds_read_b128 v[206:209], v195 offset:41536
	v_mfma_f32_32x32x16_bf16 v[20:35], v[214:217], v[222:225], v[20:35]
	global_load_dwordx4 v[128:131], v[146:147], off offset:896
	ds_read_b128 v[222:225], v195 offset:36928
	ds_read_b128 v[214:217], v194 offset:96
	s_waitcnt lgkmcnt(1)
	v_mfma_f32_32x32x16_bf16 v[52:67], v[210:213], v[222:225], v[52:67]
	s_waitcnt vmcnt(23)
	ds_write_b128 v167, v[132:135] offset:18432
	v_mfma_f32_32x32x16_bf16 v[36:51], v[210:213], v[206:209], v[36:51]
	s_waitcnt vmcnt(22)
	ds_write_b128 v167, v[136:139] offset:55296
	v_mfma_f32_32x32x16_bf16 v[20:35], v[202:205], v[222:225], v[20:35]
	s_waitcnt vmcnt(21)
	ds_write_b128 v190, v[140:143] offset:18432
	v_mfma_f32_32x32x16_bf16 v[4:19], v[202:205], v[206:209], v[4:19]
	s_waitcnt vmcnt(20)
	ds_write_b128 v190, v[198:201] offset:55296
	s_waitcnt lgkmcnt(4)
	v_mfma_f32_32x32x16_bf16 v[52:67], v[214:217], v[226:229], v[52:67]
	s_waitcnt vmcnt(19)
	ds_write_b128 v191, v[174:177] offset:18432
	v_mfma_f32_32x32x16_bf16 v[36:51], v[214:217], v[230:233], v[36:51]
	s_waitcnt vmcnt(18)
	ds_write_b128 v191, v[178:181] offset:55296
	v_mfma_f32_32x32x16_bf16 v[20:35], v[218:221], v[226:229], v[20:35]
	s_waitcnt vmcnt(17)
	ds_write_b128 v192, v[242:245] offset:18432
	v_mfma_f32_32x32x16_bf16 v[4:19], v[218:221], v[230:233], v[4:19]
	s_waitcnt vmcnt(16)
	ds_write_b128 v192, v[246:249] offset:55296
	s_waitcnt lgkmcnt(0)
	s_barrier
	ds_read_b128 v[202:205], v196
	ds_read_b128 v[218:221], v197 offset:36864
	ds_read_b128 v[226:229], v197 offset:41472
	ds_read_b128 v[210:213], v196 offset:4608
	ds_read_b128 v[206:209], v196 offset:32
	ds_read_b128 v[230:233], v197 offset:41504
	ds_read_b128 v[214:217], v196 offset:4640
	ds_read_b128 v[222:225], v197 offset:36896
	s_waitcnt lgkmcnt(6)
	v_mfma_f32_32x32x16_bf16 v[52:67], v[202:205], v[218:221], v[52:67]
	global_load_dwordx4 v[132:135], v[164:165], off offset:1024
	s_waitcnt lgkmcnt(5)
	v_mfma_f32_32x32x16_bf16 v[36:51], v[202:205], v[226:229], v[36:51]
	global_load_dwordx4 v[136:139], v[162:163], off offset:1024
	s_waitcnt lgkmcnt(4)
	v_mfma_f32_32x32x16_bf16 v[4:19], v[210:213], v[226:229], v[4:19]
	global_load_dwordx4 v[140:143], v[160:161], off offset:1024
	s_waitcnt lgkmcnt(2)
	v_mfma_f32_32x32x16_bf16 v[36:51], v[206:209], v[230:233], v[36:51]
	global_load_dwordx4 v[198:201], v[158:159], off offset:1024
	s_waitcnt lgkmcnt(1)
	v_mfma_f32_32x32x16_bf16 v[4:19], v[214:217], v[230:233], v[4:19]
	global_load_dwordx4 v[174:177], v[156:157], off offset:1024
	ds_read_b128 v[230:233], v197 offset:41568
	ds_read_b128 v[202:205], v196 offset:4672
	v_mfma_f32_32x32x16_bf16 v[20:35], v[210:213], v[218:221], v[20:35]
	global_load_dwordx4 v[178:181], v[154:155], off offset:1024
	ds_read_b128 v[218:221], v196 offset:4704
	ds_read_b128 v[210:213], v196 offset:64
	s_waitcnt lgkmcnt(4)
	v_mfma_f32_32x32x16_bf16 v[52:67], v[206:209], v[222:225], v[52:67]
	global_load_dwordx4 v[242:245], v[152:153], off offset:1024
	ds_read_b128 v[226:229], v197 offset:36960
	ds_read_b128 v[206:209], v197 offset:41536
	v_mfma_f32_32x32x16_bf16 v[20:35], v[214:217], v[222:225], v[20:35]
	global_load_dwordx4 v[246:249], v[146:147], off offset:1024
	ds_read_b128 v[222:225], v197 offset:36928
	ds_read_b128 v[214:217], v196 offset:96
	s_waitcnt lgkmcnt(1)
	v_mfma_f32_32x32x16_bf16 v[52:67], v[210:213], v[222:225], v[52:67]
	s_waitcnt vmcnt(23)
	ds_write_b128 v167, v[68:71]
	v_mfma_f32_32x32x16_bf16 v[36:51], v[210:213], v[206:209], v[36:51]
	s_waitcnt vmcnt(22)
	ds_write_b128 v167, v[72:75] offset:36864
	v_mfma_f32_32x32x16_bf16 v[20:35], v[202:205], v[222:225], v[20:35]
	s_waitcnt vmcnt(21)
	ds_write_b128 v190, v[76:79]
	v_mfma_f32_32x32x16_bf16 v[4:19], v[202:205], v[206:209], v[4:19]
	s_waitcnt vmcnt(20)
	ds_write_b128 v190, v[80:83] offset:36864
	s_waitcnt lgkmcnt(4)
	v_mfma_f32_32x32x16_bf16 v[52:67], v[214:217], v[226:229], v[52:67]
	s_waitcnt vmcnt(19)
	ds_write_b128 v191, v[84:87]
	v_mfma_f32_32x32x16_bf16 v[36:51], v[214:217], v[230:233], v[36:51]
	s_waitcnt vmcnt(18)
	ds_write_b128 v191, v[88:91] offset:36864
	v_mfma_f32_32x32x16_bf16 v[20:35], v[218:221], v[226:229], v[20:35]
	s_waitcnt vmcnt(17)
	ds_write_b128 v192, v[92:95]
	v_mfma_f32_32x32x16_bf16 v[4:19], v[218:221], v[230:233], v[4:19]
	s_waitcnt vmcnt(16)
	ds_write_b128 v192, v[104:107] offset:36864
	s_waitcnt lgkmcnt(0)
	s_barrier
; #define MFMA(a, b, c) __builtin_amdgcn_mfma_f32_32x32x16_bf16((a), (b), (c), 0, 0, 0)
; template <class Epi, class ColV>
; DI void gemm_tile(const bf16_t* __restrict__ A, int lda, const bf16_t* __restrict__ Bt, int ldb, int K, int m0, int n0, unsigned char* smem, Epi epi, ColV colv, const bf16_t* __restrict__ HYT = nullptr) {
;     ...
;     auto step = [&](int kt, u32x4 (&ldset)[8], const u32x4 (&stset)[8]) {
;         const int buf = kt & 1;
;         if (kt + 2 < nk) gload(ldset, kt + 2);
;         const bf16_t* Ab = As + (buf * 128 + 64 * wr + li) * LS + 8 * lh;
;         const bf16_t* Bb = Bs + (buf * 128 + 64 * wc + li) * LS + 8 * lh;
;         bf16x8 fa[2][2], fb[2][2], ga[2][2], gb[2][2];
; #pragma unroll
;         for (int k2 = 0; k2 < 2; ++k2) { fa[k2][0] = ld8(Ab + 16 * k2); fa[k2][1] = ld8(Ab + 32 * LS + 16 * k2); fb[k2][0] = ld8(Bb + 16 * k2); fb[k2][1] = ld8(Bb + 32 * LS + 16 * k2); }
;         __builtin_amdgcn_sched_barrier(0);
; #pragma unroll
;         for (int k2 = 0; k2 < 2; ++k2) {
;             acc[0][0] = MFMA(fa[k2][0], fb[k2][0], acc[0][0]); acc[0][1] = MFMA(fa[k2][0], fb[k2][1], acc[0][1]);
;             acc[1][0] = MFMA(fa[k2][1], fb[k2][0], acc[1][0]); acc[1][1] = MFMA(fa[k2][1], fb[k2][1], acc[1][1]);
;         }
; #pragma unroll
;         for (int k2 = 0; k2 < 2; ++k2) { const int ks = 2 + k2; ga[k2][0] = ld8(Ab + 16 * ks); ga[k2][1] = ld8(Ab + 32 * LS + 16 * ks); gb[k2][0] = ld8(Bb + 16 * ks); gb[k2][1] = ld8(Bb + 32 * LS + 16 * ks); }
; #pragma unroll
;         for (int k2 = 0; k2 < 2; ++k2) {
;             acc[0][0] = MFMA(ga[k2][0], gb[k2][0], acc[0][0]); acc[0][1] = MFMA(ga[k2][0], gb[k2][1], acc[0][1]);
;             acc[1][0] = MFMA(ga[k2][1], gb[k2][0], acc[1][0]); acc[1][1] = MFMA(ga[k2][1], gb[k2][1], acc[1][1]);
;         }
;         if (kt + 1 < nk) sstore(stset, buf ^ 1, kt + 1);
; #pragma unroll
;         for (int i = 0; i < 8; ++i) { __builtin_amdgcn_sched_group_barrier(0x008, 1, 0); __builtin_amdgcn_sched_group_barrier(0x100, 1, 0); }
; #pragma unroll
;         for (int i = 0; i < 8; ++i) { __builtin_amdgcn_sched_group_barrier(0x008, 1, 0); __builtin_amdgcn_sched_group_barrier(0x200, 1, 0); }
;         __builtin_amdgcn_sched_barrier(0);
;         __syncthreads();
	ds_read_b128 v[202:205], v194
	ds_read_b128 v[218:221], v195 offset:36864
	ds_read_b128 v[226:229], v195 offset:41472
	ds_read_b128 v[210:213], v194 offset:4608
	ds_read_b128 v[206:209], v194 offset:32
	ds_read_b128 v[230:233], v195 offset:41504
	ds_read_b128 v[214:217], v194 offset:4640
	ds_read_b128 v[222:225], v195 offset:36896
	s_waitcnt lgkmcnt(6)
	v_mfma_f32_32x32x16_bf16 v[52:67], v[202:205], v[218:221], v[52:67]
	global_load_dwordx4 v[68:71], v[164:165], off offset:1152
	s_waitcnt lgkmcnt(5)
	v_mfma_f32_32x32x16_bf16 v[36:51], v[202:205], v[226:229], v[36:51]
	global_load_dwordx4 v[72:75], v[162:163], off offset:1152
	s_waitcnt lgkmcnt(4)
	v_mfma_f32_32x32x16_bf16 v[4:19], v[210:213], v[226:229], v[4:19]
	global_load_dwordx4 v[76:79], v[160:161], off offset:1152
	s_waitcnt lgkmcnt(2)
	v_mfma_f32_32x32x16_bf16 v[36:51], v[206:209], v[230:233], v[36:51]
	global_load_dwordx4 v[80:83], v[158:159], off offset:1152
	s_waitcnt lgkmcnt(1)
	v_mfma_f32_32x32x16_bf16 v[4:19], v[214:217], v[230:233], v[4:19]
	global_load_dwordx4 v[84:87], v[156:157], off offset:1152
	ds_read_b128 v[230:233], v195 offset:41568
	ds_read_b128 v[202:205], v194 offset:4672
	v_mfma_f32_32x32x16_bf16 v[20:35], v[210:213], v[218:221], v[20:35]
	global_load_dwordx4 v[88:91], v[154:155], off offset:1152
	ds_read_b128 v[218:221], v194 offset:4704
	ds_read_b128 v[210:213], v194 offset:64
	s_waitcnt lgkmcnt(4)
	v_mfma_f32_32x32x16_bf16 v[52:67], v[206:209], v[222:225], v[52:67]
	global_load_dwordx4 v[92:95], v[152:153], off offset:1152
	ds_read_b128 v[226:229], v195 offset:36960
	ds_read_b128 v[206:209], v195 offset:41536
	v_mfma_f32_32x32x16_bf16 v[20:35], v[214:217], v[222:225], v[20:35]
	global_load_dwordx4 v[104:107], v[146:147], off offset:1152
	ds_read_b128 v[222:225], v195 offset:36928
	ds_read_b128 v[214:217], v194 offset:96
	s_waitcnt lgkmcnt(1)
	v_mfma_f32_32x32x16_bf16 v[52:67], v[210:213], v[222:225], v[52:67]
	s_waitcnt vmcnt(23)
	ds_write_b128 v167, v[96:99] offset:18432
	v_mfma_f32_32x32x16_bf16 v[36:51], v[210:213], v[206:209], v[36:51]
	s_waitcnt vmcnt(22)
	ds_write_b128 v167, v[100:103] offset:55296
	v_mfma_f32_32x32x16_bf16 v[20:35], v[202:205], v[222:225], v[20:35]
	s_waitcnt vmcnt(21)
	ds_write_b128 v190, v[108:111] offset:18432
	v_mfma_f32_32x32x16_bf16 v[4:19], v[202:205], v[206:209], v[4:19]
	s_waitcnt vmcnt(20)
	ds_write_b128 v190, v[112:115] offset:55296
	s_waitcnt lgkmcnt(4)
	v_mfma_f32_32x32x16_bf16 v[52:67], v[214:217], v[226:229], v[52:67]
	s_waitcnt vmcnt(19)
	ds_write_b128 v191, v[116:119] offset:18432
	v_mfma_f32_32x32x16_bf16 v[36:51], v[214:217], v[230:233], v[36:51]
	s_waitcnt vmcnt(18)
	ds_write_b128 v191, v[120:123] offset:55296
	v_mfma_f32_32x32x16_bf16 v[20:35], v[218:221], v[226:229], v[20:35]
	s_waitcnt vmcnt(17)
	ds_write_b128 v192, v[124:127] offset:18432
	v_mfma_f32_32x32x16_bf16 v[4:19], v[218:221], v[230:233], v[4:19]
	s_waitcnt vmcnt(16)
	ds_write_b128 v192, v[128:131] offset:55296
	s_waitcnt lgkmcnt(0)
	s_barrier
	ds_read_b128 v[202:205], v196
	ds_read_b128 v[218:221], v197 offset:36864
	ds_read_b128 v[226:229], v197 offset:41472
	ds_read_b128 v[210:213], v196 offset:4608
	ds_read_b128 v[206:209], v196 offset:32
	ds_read_b128 v[230:233], v197 offset:41504
	ds_read_b128 v[214:217], v196 offset:4640
	ds_read_b128 v[222:225], v197 offset:36896
	s_waitcnt lgkmcnt(6)
	v_mfma_f32_32x32x16_bf16 v[52:67], v[202:205], v[218:221], v[52:67]
	global_load_dwordx4 v[96:99], v[164:165], off offset:1280
	s_waitcnt lgkmcnt(5)
	v_mfma_f32_32x32x16_bf16 v[36:51], v[202:205], v[226:229], v[36:51]
	global_load_dwordx4 v[100:103], v[162:163], off offset:1280
	s_waitcnt lgkmcnt(4)
	v_mfma_f32_32x32x16_bf16 v[4:19], v[210:213], v[226:229], v[4:19]
	global_load_dwordx4 v[108:111], v[160:161], off offset:1280
	s_waitcnt lgkmcnt(2)
	v_mfma_f32_32x32x16_bf16 v[36:51], v[206:209], v[230:233], v[36:51]
	global_load_dwordx4 v[112:115], v[158:159], off offset:1280
	s_waitcnt lgkmcnt(1)
	v_mfma_f32_32x32x16_bf16 v[4:19], v[214:217], v[230:233], v[4:19]
	global_load_dwordx4 v[116:119], v[156:157], off offset:1280
	ds_read_b128 v[230:233], v197 offset:41568
	ds_read_b128 v[202:205], v196 offset:4672
	v_mfma_f32_32x32x16_bf16 v[20:35], v[210:213], v[218:221], v[20:35]
	global_load_dwordx4 v[120:123], v[154:155], off offset:1280
	ds_read_b128 v[218:221], v196 offset:4704
	ds_read_b128 v[210:213], v196 offset:64
	s_waitcnt lgkmcnt(4)
	v_mfma_f32_32x32x16_bf16 v[52:67], v[206:209], v[222:225], v[52:67]
	global_load_dwordx4 v[124:127], v[152:153], off offset:1280
	ds_read_b128 v[226:229], v197 offset:36960
	ds_read_b128 v[206:209], v197 offset:41536
	v_mfma_f32_32x32x16_bf16 v[20:35], v[214:217], v[222:225], v[20:35]
	global_load_dwordx4 v[128:131], v[146:147], off offset:1280
	ds_read_b128 v[222:225], v197 offset:36928
	ds_read_b128 v[214:217], v196 offset:96
	s_waitcnt lgkmcnt(1)
	v_mfma_f32_32x32x16_bf16 v[52:67], v[210:213], v[222:225], v[52:67]
	s_waitcnt vmcnt(23)
	ds_write_b128 v167, v[132:135]
	v_mfma_f32_32x32x16_bf16 v[36:51], v[210:213], v[206:209], v[36:51]
	s_waitcnt vmcnt(22)
	ds_write_b128 v167, v[136:139] offset:36864
	v_mfma_f32_32x32x16_bf16 v[20:35], v[202:205], v[222:225], v[20:35]
	s_waitcnt vmcnt(21)
	ds_write_b128 v190, v[140:143]
	v_mfma_f32_32x32x16_bf16 v[4:19], v[202:205], v[206:209], v[4:19]
	s_waitcnt vmcnt(20)
	ds_write_b128 v190, v[198:201] offset:36864
	s_waitcnt lgkmcnt(4)
	v_mfma_f32_32x32x16_bf16 v[52:67], v[214:217], v[226:229], v[52:67]
	s_waitcnt vmcnt(19)
	ds_write_b128 v191, v[174:177]
	v_mfma_f32_32x32x16_bf16 v[36:51], v[214:217], v[230:233], v[36:51]
	s_waitcnt vmcnt(18)
	ds_write_b128 v191, v[178:181] offset:36864
	v_mfma_f32_32x32x16_bf16 v[20:35], v[218:221], v[226:229], v[20:35]
	s_waitcnt vmcnt(17)
	ds_write_b128 v192, v[242:245]
	v_mfma_f32_32x32x16_bf16 v[4:19], v[218:221], v[230:233], v[4:19]
	s_waitcnt vmcnt(16)
	ds_write_b128 v192, v[246:249] offset:36864
	s_waitcnt lgkmcnt(0)
	s_barrier
; #define MFMA(a, b, c) __builtin_amdgcn_mfma_f32_32x32x16_bf16((a), (b), (c), 0, 0, 0)
; template <class Epi, class ColV>
; DI void gemm_tile(const bf16_t* __restrict__ A, int lda, const bf16_t* __restrict__ Bt, int ldb, int K, int m0, int n0, unsigned char* smem, Epi epi, ColV colv, const bf16_t* __restrict__ HYT = nullptr) {
;     ...
;     auto step = [&](int kt, u32x4 (&ldset)[8], const u32x4 (&stset)[8]) {
;         const int buf = kt & 1;
;         if (kt + 2 < nk) gload(ldset, kt + 2);
;         const bf16_t* Ab = As + (buf * 128 + 64 * wr + li) * LS + 8 * lh;
;         const bf16_t* Bb = Bs + (buf * 128 + 64 * wc + li) * LS + 8 * lh;
;         bf16x8 fa[2][2], fb[2][2], ga[2][2], gb[2][2];
; #pragma unroll
;         for (int k2 = 0; k2 < 2; ++k2) { fa[k2][0] = ld8(Ab + 16 * k2); fa[k2][1] = ld8(Ab + 32 * LS + 16 * k2); fb[k2][0] = ld8(Bb + 16 * k2); fb[k2][1] = ld8(Bb + 32 * LS + 16 * k2); }
;         __builtin_amdgcn_sched_barrier(0);
; #pragma unroll
;         for (int k2 = 0; k2 < 2; ++k2) {
;             acc[0][0] = MFMA(fa[k2][0], fb[k2][0], acc[0][0]); acc[0][1] = MFMA(fa[k2][0], fb[k2][1], acc[0][1]);
;             acc[1][0] = MFMA(fa[k2][1], fb[k2][0], acc[1][0]); acc[1][1] = MFMA(fa[k2][1], fb[k2][1], acc[1][1]);
;         }
; #pragma unroll
;         for (int k2 = 0; k2 < 2; ++k2) { const int ks = 2 + k2; ga[k2][0] = ld8(Ab + 16 * ks); ga[k2][1] = ld8(Ab + 32 * LS + 16 * ks); gb[k2][0] = ld8(Bb + 16 * ks); gb[k2][1] = ld8(Bb + 32 * LS + 16 * ks); }
; #pragma unroll
;         for (int k2 = 0; k2 < 2; ++k2) {
;             acc[0][0] = MFMA(ga[k2][0], gb[k2][0], acc[0][0]); acc[0][1] = MFMA(ga[k2][0], gb[k2][1], acc[0][1]);
;             acc[1][0] = MFMA(ga[k2][1], gb[k2][0], acc[1][0]); acc[1][1] = MFMA(ga[k2][1], gb[k2][1], acc[1][1]);
;         }
;         if (kt + 1 < nk) sstore(stset, buf ^ 1, kt + 1);
; #pragma unroll
;         for (int i = 0; i < 8; ++i) { __builtin_amdgcn_sched_group_barrier(0x008, 1, 0); __builtin_amdgcn_sched_group_barrier(0x100, 1, 0); }
; #pragma unroll
;         for (int i = 0; i < 8; ++i) { __builtin_amdgcn_sched_group_barrier(0x008, 1, 0); __builtin_amdgcn_sched_group_barrier(0x200, 1, 0); }
;         __builtin_amdgcn_sched_barrier(0);
;         __syncthreads();
	ds_read_b128 v[202:205], v194
	ds_read_b128 v[218:221], v195 offset:36864
	ds_read_b128 v[226:229], v195 offset:41472
	ds_read_b128 v[210:213], v194 offset:4608
	ds_read_b128 v[206:209], v194 offset:32
	ds_read_b128 v[230:233], v195 offset:41504
	ds_read_b128 v[214:217], v194 offset:4640
	ds_read_b128 v[222:225], v195 offset:36896
	s_waitcnt lgkmcnt(6)
	v_mfma_f32_32x32x16_bf16 v[52:67], v[202:205], v[218:221], v[52:67]
	global_load_dwordx4 v[132:135], v[164:165], off offset:1408
	s_waitcnt lgkmcnt(5)
	v_mfma_f32_32x32x16_bf16 v[36:51], v[202:205], v[226:229], v[36:51]
	global_load_dwordx4 v[136:139], v[162:163], off offset:1408
	s_waitcnt lgkmcnt(4)
	v_mfma_f32_32x32x16_bf16 v[4:19], v[210:213], v[226:229], v[4:19]
	global_load_dwordx4 v[140:143], v[160:161], off offset:1408
	s_waitcnt lgkmcnt(2)
	v_mfma_f32_32x32x16_bf16 v[36:51], v[206:209], v[230:233], v[36:51]
	global_load_dwordx4 v[198:201], v[158:159], off offset:1408
	s_waitcnt lgkmcnt(1)
	v_mfma_f32_32x32x16_bf16 v[4:19], v[214:217], v[230:233], v[4:19]
	global_load_dwordx4 v[174:177], v[156:157], off offset:1408
	ds_read_b128 v[230:233], v195 offset:41568
	ds_read_b128 v[202:205], v194 offset:4672
	v_mfma_f32_32x32x16_bf16 v[20:35], v[210:213], v[218:221], v[20:35]
	global_load_dwordx4 v[178:181], v[154:155], off offset:1408
	ds_read_b128 v[218:221], v194 offset:4704
	ds_read_b128 v[210:213], v194 offset:64
	s_waitcnt lgkmcnt(4)
	v_mfma_f32_32x32x16_bf16 v[52:67], v[206:209], v[222:225], v[52:67]
	global_load_dwordx4 v[242:245], v[152:153], off offset:1408
	ds_read_b128 v[226:229], v195 offset:36960
	ds_read_b128 v[206:209], v195 offset:41536
	v_mfma_f32_32x32x16_bf16 v[20:35], v[214:217], v[222:225], v[20:35]
	global_load_dwordx4 v[246:249], v[146:147], off offset:1408
	ds_read_b128 v[222:225], v195 offset:36928
	ds_read_b128 v[214:217], v194 offset:96
	s_waitcnt lgkmcnt(1)
	v_mfma_f32_32x32x16_bf16 v[52:67], v[210:213], v[222:225], v[52:67]
	s_waitcnt vmcnt(23)
	ds_write_b128 v167, v[68:71] offset:18432
	v_mfma_f32_32x32x16_bf16 v[36:51], v[210:213], v[206:209], v[36:51]
	s_waitcnt vmcnt(22)
	ds_write_b128 v167, v[72:75] offset:55296
	v_mfma_f32_32x32x16_bf16 v[20:35], v[202:205], v[222:225], v[20:35]
	s_waitcnt vmcnt(21)
	ds_write_b128 v190, v[76:79] offset:18432
	v_mfma_f32_32x32x16_bf16 v[4:19], v[202:205], v[206:209], v[4:19]
	s_waitcnt vmcnt(20)
	ds_write_b128 v190, v[80:83] offset:55296
	s_waitcnt lgkmcnt(4)
	v_mfma_f32_32x32x16_bf16 v[52:67], v[214:217], v[226:229], v[52:67]
	s_waitcnt vmcnt(19)
	ds_write_b128 v191, v[84:87] offset:18432
	v_mfma_f32_32x32x16_bf16 v[36:51], v[214:217], v[230:233], v[36:51]
	s_waitcnt vmcnt(18)
	ds_write_b128 v191, v[88:91] offset:55296
	v_mfma_f32_32x32x16_bf16 v[20:35], v[218:221], v[226:229], v[20:35]
	s_waitcnt vmcnt(17)
	ds_write_b128 v192, v[92:95] offset:18432
	v_mfma_f32_32x32x16_bf16 v[4:19], v[218:221], v[230:233], v[4:19]
	s_waitcnt vmcnt(16)
	ds_write_b128 v192, v[104:107] offset:55296
	s_waitcnt lgkmcnt(0)
	s_barrier
	ds_read_b128 v[202:205], v196
	ds_read_b128 v[218:221], v197 offset:36864
	ds_read_b128 v[226:229], v197 offset:41472
	ds_read_b128 v[210:213], v196 offset:4608
	ds_read_b128 v[206:209], v196 offset:32
	ds_read_b128 v[230:233], v197 offset:41504
	ds_read_b128 v[214:217], v196 offset:4640
	ds_read_b128 v[222:225], v197 offset:36896
	s_waitcnt lgkmcnt(6)
	v_mfma_f32_32x32x16_bf16 v[52:67], v[202:205], v[218:221], v[52:67]
	global_load_dwordx4 v[68:71], v[164:165], off offset:1536
	s_waitcnt lgkmcnt(5)
	v_mfma_f32_32x32x16_bf16 v[36:51], v[202:205], v[226:229], v[36:51]
	global_load_dwordx4 v[72:75], v[162:163], off offset:1536
	s_waitcnt lgkmcnt(4)
	v_mfma_f32_32x32x16_bf16 v[4:19], v[210:213], v[226:229], v[4:19]
	global_load_dwordx4 v[76:79], v[160:161], off offset:1536
	s_waitcnt lgkmcnt(2)
	v_mfma_f32_32x32x16_bf16 v[36:51], v[206:209], v[230:233], v[36:51]
	global_load_dwordx4 v[80:83], v[158:159], off offset:1536
	s_waitcnt lgkmcnt(1)
	v_mfma_f32_32x32x16_bf16 v[4:19], v[214:217], v[230:233], v[4:19]
	global_load_dwordx4 v[84:87], v[156:157], off offset:1536
	ds_read_b128 v[230:233], v197 offset:41568
	ds_read_b128 v[202:205], v196 offset:4672
	v_mfma_f32_32x32x16_bf16 v[20:35], v[210:213], v[218:221], v[20:35]
	global_load_dwordx4 v[88:91], v[154:155], off offset:1536
	ds_read_b128 v[218:221], v196 offset:4704
	ds_read_b128 v[210:213], v196 offset:64
	s_waitcnt lgkmcnt(4)
	v_mfma_f32_32x32x16_bf16 v[52:67], v[206:209], v[222:225], v[52:67]
	global_load_dwordx4 v[92:95], v[152:153], off offset:1536
	ds_read_b128 v[226:229], v197 offset:36960
	ds_read_b128 v[206:209], v197 offset:41536
	v_mfma_f32_32x32x16_bf16 v[20:35], v[214:217], v[222:225], v[20:35]
	global_load_dwordx4 v[104:107], v[146:147], off offset:1536
	ds_read_b128 v[222:225], v197 offset:36928
	ds_read_b128 v[214:217], v196 offset:96
	s_waitcnt lgkmcnt(1)
	v_mfma_f32_32x32x16_bf16 v[52:67], v[210:213], v[222:225], v[52:67]
	s_waitcnt vmcnt(23)
	ds_write_b128 v167, v[96:99]
	v_mfma_f32_32x32x16_bf16 v[36:51], v[210:213], v[206:209], v[36:51]
	s_waitcnt vmcnt(22)
	ds_write_b128 v167, v[100:103] offset:36864
	v_mfma_f32_32x32x16_bf16 v[20:35], v[202:205], v[222:225], v[20:35]
	s_waitcnt vmcnt(21)
	ds_write_b128 v190, v[108:111]
	v_mfma_f32_32x32x16_bf16 v[4:19], v[202:205], v[206:209], v[4:19]
	s_waitcnt vmcnt(20)
	ds_write_b128 v190, v[112:115] offset:36864
	s_waitcnt lgkmcnt(4)
	v_mfma_f32_32x32x16_bf16 v[52:67], v[214:217], v[226:229], v[52:67]
	s_waitcnt vmcnt(19)
	ds_write_b128 v191, v[116:119]
	v_mfma_f32_32x32x16_bf16 v[36:51], v[214:217], v[230:233], v[36:51]
	s_waitcnt vmcnt(18)
	ds_write_b128 v191, v[120:123] offset:36864
	v_mfma_f32_32x32x16_bf16 v[20:35], v[218:221], v[226:229], v[20:35]
	s_waitcnt vmcnt(17)
	ds_write_b128 v192, v[124:127]
	v_mfma_f32_32x32x16_bf16 v[4:19], v[218:221], v[230:233], v[4:19]
	s_waitcnt vmcnt(16)
	ds_write_b128 v192, v[128:131] offset:36864
	s_waitcnt lgkmcnt(0)
	s_barrier
; #define MFMA(a, b, c) __builtin_amdgcn_mfma_f32_32x32x16_bf16((a), (b), (c), 0, 0, 0)
; template <class Epi, class ColV>
; DI void gemm_tile(const bf16_t* __restrict__ A, int lda, const bf16_t* __restrict__ Bt, int ldb, int K, int m0, int n0, unsigned char* smem, Epi epi, ColV colv, const bf16_t* __restrict__ HYT = nullptr) {
;     ...
;     auto step = [&](int kt, u32x4 (&ldset)[8], const u32x4 (&stset)[8]) {
;         const int buf = kt & 1;
;         if (kt + 2 < nk) gload(ldset, kt + 2);
;         const bf16_t* Ab = As + (buf * 128 + 64 * wr + li) * LS + 8 * lh;
;         const bf16_t* Bb = Bs + (buf * 128 + 64 * wc + li) * LS + 8 * lh;
;         bf16x8 fa[2][2], fb[2][2], ga[2][2], gb[2][2];
; #pragma unroll
;         for (int k2 = 0; k2 < 2; ++k2) { fa[k2][0] = ld8(Ab + 16 * k2); fa[k2][1] = ld8(Ab + 32 * LS + 16 * k2); fb[k2][0] = ld8(Bb + 16 * k2); fb[k2][1] = ld8(Bb + 32 * LS + 16 * k2); }
;         __builtin_amdgcn_sched_barrier(0);
; #pragma unroll
;         for (int k2 = 0; k2 < 2; ++k2) {
;             acc[0][0] = MFMA(fa[k2][0], fb[k2][0], acc[0][0]); acc[0][1] = MFMA(fa[k2][0], fb[k2][1], acc[0][1]);
;             acc[1][0] = MFMA(fa[k2][1], fb[k2][0], acc[1][0]); acc[1][1] = MFMA(fa[k2][1], fb[k2][1], acc[1][1]);
;         }
; #pragma unroll
;         for (int k2 = 0; k2 < 2; ++k2) { const int ks = 2 + k2; ga[k2][0] = ld8(Ab + 16 * ks); ga[k2][1] = ld8(Ab + 32 * LS + 16 * ks); gb[k2][0] = ld8(Bb + 16 * ks); gb[k2][1] = ld8(Bb + 32 * LS + 16 * ks); }
; #pragma unroll
;         for (int k2 = 0; k2 < 2; ++k2) {
;             acc[0][0] = MFMA(ga[k2][0], gb[k2][0], acc[0][0]); acc[0][1] = MFMA(ga[k2][0], gb[k2][1], acc[0][1]);
;             acc[1][0] = MFMA(ga[k2][1], gb[k2][0], acc[1][0]); acc[1][1] = MFMA(ga[k2][1], gb[k2][1], acc[1][1]);
;         }
;         if (kt + 1 < nk) sstore(stset, buf ^ 1, kt + 1);
; #pragma unroll
;         for (int i = 0; i < 8; ++i) { __builtin_amdgcn_sched_group_barrier(0x008, 1, 0); __builtin_amdgcn_sched_group_barrier(0x100, 1, 0); }
; #pragma unroll
;         for (int i = 0; i < 8; ++i) { __builtin_amdgcn_sched_group_barrier(0x008, 1, 0); __builtin_amdgcn_sched_group_barrier(0x200, 1, 0); }
;         __builtin_amdgcn_sched_barrier(0);
;         __syncthreads();
	ds_read_b128 v[202:205], v194
	ds_read_b128 v[218:221], v195 offset:36864
	ds_read_b128 v[226:229], v195 offset:41472
	ds_read_b128 v[210:213], v194 offset:4608
	ds_read_b128 v[206:209], v194 offset:32
	ds_read_b128 v[230:233], v195 offset:41504
	ds_read_b128 v[214:217], v194 offset:4640
	ds_read_b128 v[222:225], v195 offset:36896
	s_waitcnt lgkmcnt(6)
	v_mfma_f32_32x32x16_bf16 v[52:67], v[202:205], v[218:221], v[52:67]
	global_load_dwordx4 v[96:99], v[164:165], off offset:1664
	s_waitcnt lgkmcnt(5)
	v_mfma_f32_32x32x16_bf16 v[36:51], v[202:205], v[226:229], v[36:51]
	global_load_dwordx4 v[100:103], v[162:163], off offset:1664
	s_waitcnt lgkmcnt(4)
	v_mfma_f32_32x32x16_bf16 v[4:19], v[210:213], v[226:229], v[4:19]
	global_load_dwordx4 v[108:111], v[160:161], off offset:1664
	s_waitcnt lgkmcnt(2)
	v_mfma_f32_32x32x16_bf16 v[36:51], v[206:209], v[230:233], v[36:51]
	global_load_dwordx4 v[112:115], v[158:159], off offset:1664
	s_waitcnt lgkmcnt(1)
	v_mfma_f32_32x32x16_bf16 v[4:19], v[214:217], v[230:233], v[4:19]
	global_load_dwordx4 v[116:119], v[156:157], off offset:1664
	ds_read_b128 v[230:233], v195 offset:41568
	ds_read_b128 v[202:205], v194 offset:4672
	v_mfma_f32_32x32x16_bf16 v[20:35], v[210:213], v[218:221], v[20:35]
	global_load_dwordx4 v[120:123], v[154:155], off offset:1664
	ds_read_b128 v[218:221], v194 offset:4704
	ds_read_b128 v[210:213], v194 offset:64
	s_waitcnt lgkmcnt(4)
	v_mfma_f32_32x32x16_bf16 v[52:67], v[206:209], v[222:225], v[52:67]
	global_load_dwordx4 v[124:127], v[152:153], off offset:1664
	ds_read_b128 v[226:229], v195 offset:36960
	ds_read_b128 v[206:209], v195 offset:41536
	v_mfma_f32_32x32x16_bf16 v[20:35], v[214:217], v[222:225], v[20:35]
	global_load_dwordx4 v[128:131], v[146:147], off offset:1664
	ds_read_b128 v[222:225], v195 offset:36928
	ds_read_b128 v[214:217], v194 offset:96
	s_waitcnt lgkmcnt(1)
	v_mfma_f32_32x32x16_bf16 v[52:67], v[210:213], v[222:225], v[52:67]
	s_waitcnt vmcnt(23)
	ds_write_b128 v167, v[132:135] offset:18432
	v_mfma_f32_32x32x16_bf16 v[36:51], v[210:213], v[206:209], v[36:51]
	s_waitcnt vmcnt(22)
	ds_write_b128 v167, v[136:139] offset:55296
	v_mfma_f32_32x32x16_bf16 v[20:35], v[202:205], v[222:225], v[20:35]
	s_waitcnt vmcnt(21)
	ds_write_b128 v190, v[140:143] offset:18432
	v_mfma_f32_32x32x16_bf16 v[4:19], v[202:205], v[206:209], v[4:19]
	s_waitcnt vmcnt(20)
	ds_write_b128 v190, v[198:201] offset:55296
	s_waitcnt lgkmcnt(4)
	v_mfma_f32_32x32x16_bf16 v[52:67], v[214:217], v[226:229], v[52:67]
	s_waitcnt vmcnt(19)
	ds_write_b128 v191, v[174:177] offset:18432
	v_mfma_f32_32x32x16_bf16 v[36:51], v[214:217], v[230:233], v[36:51]
	s_waitcnt vmcnt(18)
	ds_write_b128 v191, v[178:181] offset:55296
	v_mfma_f32_32x32x16_bf16 v[20:35], v[218:221], v[226:229], v[20:35]
	s_waitcnt vmcnt(17)
	ds_write_b128 v192, v[242:245] offset:18432
	v_mfma_f32_32x32x16_bf16 v[4:19], v[218:221], v[230:233], v[4:19]
	s_waitcnt vmcnt(16)
	ds_write_b128 v192, v[246:249] offset:55296
	s_waitcnt lgkmcnt(0)
	s_barrier
	ds_read_b128 v[202:205], v196
	ds_read_b128 v[218:221], v197 offset:36864
	ds_read_b128 v[226:229], v197 offset:41472
	ds_read_b128 v[210:213], v196 offset:4608
	ds_read_b128 v[206:209], v196 offset:32
	ds_read_b128 v[230:233], v197 offset:41504
	ds_read_b128 v[214:217], v196 offset:4640
	ds_read_b128 v[222:225], v197 offset:36896
	s_waitcnt lgkmcnt(6)
	v_mfma_f32_32x32x16_bf16 v[52:67], v[202:205], v[218:221], v[52:67]
	global_load_dwordx4 v[132:135], v[164:165], off offset:1792
	s_waitcnt lgkmcnt(5)
	v_mfma_f32_32x32x16_bf16 v[36:51], v[202:205], v[226:229], v[36:51]
	global_load_dwordx4 v[136:139], v[162:163], off offset:1792
	s_waitcnt lgkmcnt(4)
	v_mfma_f32_32x32x16_bf16 v[4:19], v[210:213], v[226:229], v[4:19]
	global_load_dwordx4 v[140:143], v[160:161], off offset:1792
	s_waitcnt lgkmcnt(2)
	v_mfma_f32_32x32x16_bf16 v[36:51], v[206:209], v[230:233], v[36:51]
	global_load_dwordx4 v[198:201], v[158:159], off offset:1792
	s_waitcnt lgkmcnt(1)
	v_mfma_f32_32x32x16_bf16 v[4:19], v[214:217], v[230:233], v[4:19]
	global_load_dwordx4 v[174:177], v[156:157], off offset:1792
	ds_read_b128 v[230:233], v197 offset:41568
	ds_read_b128 v[202:205], v196 offset:4672
	v_mfma_f32_32x32x16_bf16 v[20:35], v[210:213], v[218:221], v[20:35]
	global_load_dwordx4 v[178:181], v[154:155], off offset:1792
	ds_read_b128 v[218:221], v196 offset:4704
	ds_read_b128 v[210:213], v196 offset:64
	s_waitcnt lgkmcnt(4)
	v_mfma_f32_32x32x16_bf16 v[52:67], v[206:209], v[222:225], v[52:67]
	global_load_dwordx4 v[242:245], v[152:153], off offset:1792
	ds_read_b128 v[226:229], v197 offset:36960
	ds_read_b128 v[206:209], v197 offset:41536
	v_mfma_f32_32x32x16_bf16 v[20:35], v[214:217], v[222:225], v[20:35]
	global_load_dwordx4 v[246:249], v[146:147], off offset:1792
	ds_read_b128 v[222:225], v197 offset:36928
	ds_read_b128 v[214:217], v196 offset:96
	s_waitcnt lgkmcnt(1)
	v_mfma_f32_32x32x16_bf16 v[52:67], v[210:213], v[222:225], v[52:67]
	s_waitcnt vmcnt(23)
	ds_write_b128 v167, v[68:71]
	v_mfma_f32_32x32x16_bf16 v[36:51], v[210:213], v[206:209], v[36:51]
	s_waitcnt vmcnt(22)
	ds_write_b128 v167, v[72:75] offset:36864
	v_mfma_f32_32x32x16_bf16 v[20:35], v[202:205], v[222:225], v[20:35]
	s_waitcnt vmcnt(21)
	ds_write_b128 v190, v[76:79]
	v_mfma_f32_32x32x16_bf16 v[4:19], v[202:205], v[206:209], v[4:19]
	s_waitcnt vmcnt(20)
	ds_write_b128 v190, v[80:83] offset:36864
	s_waitcnt lgkmcnt(4)
	v_mfma_f32_32x32x16_bf16 v[52:67], v[214:217], v[226:229], v[52:67]
	s_waitcnt vmcnt(19)
	ds_write_b128 v191, v[84:87]
	v_mfma_f32_32x32x16_bf16 v[36:51], v[214:217], v[230:233], v[36:51]
	s_waitcnt vmcnt(18)
	ds_write_b128 v191, v[88:91] offset:36864
	v_mfma_f32_32x32x16_bf16 v[20:35], v[218:221], v[226:229], v[20:35]
	s_waitcnt vmcnt(17)
	ds_write_b128 v192, v[92:95]
	v_mfma_f32_32x32x16_bf16 v[4:19], v[218:221], v[230:233], v[4:19]
	s_waitcnt vmcnt(16)
	ds_write_b128 v192, v[104:107] offset:36864
	s_waitcnt lgkmcnt(0)
	s_barrier
; #define MFMA(a, b, c) __builtin_amdgcn_mfma_f32_32x32x16_bf16((a), (b), (c), 0, 0, 0)
; template <class Epi, class ColV>
; DI void gemm_tile(const bf16_t* __restrict__ A, int lda, const bf16_t* __restrict__ Bt, int ldb, int K, int m0, int n0, unsigned char* smem, Epi epi, ColV colv, const bf16_t* __restrict__ HYT = nullptr) {
;     ...
;     auto step = [&](int kt, u32x4 (&ldset)[8], const u32x4 (&stset)[8]) {
;         const int buf = kt & 1;
;         if (kt + 2 < nk) gload(ldset, kt + 2);
;         const bf16_t* Ab = As + (buf * 128 + 64 * wr + li) * LS + 8 * lh;
;         const bf16_t* Bb = Bs + (buf * 128 + 64 * wc + li) * LS + 8 * lh;
;         bf16x8 fa[2][2], fb[2][2], ga[2][2], gb[2][2];
; #pragma unroll
;         for (int k2 = 0; k2 < 2; ++k2) { fa[k2][0] = ld8(Ab + 16 * k2); fa[k2][1] = ld8(Ab + 32 * LS + 16 * k2); fb[k2][0] = ld8(Bb + 16 * k2); fb[k2][1] = ld8(Bb + 32 * LS + 16 * k2); }
;         __builtin_amdgcn_sched_barrier(0);
; #pragma unroll
;         for (int k2 = 0; k2 < 2; ++k2) {
;             acc[0][0] = MFMA(fa[k2][0], fb[k2][0], acc[0][0]); acc[0][1] = MFMA(fa[k2][0], fb[k2][1], acc[0][1]);
;             acc[1][0] = MFMA(fa[k2][1], fb[k2][0], acc[1][0]); acc[1][1] = MFMA(fa[k2][1], fb[k2][1], acc[1][1]);
;         }
; #pragma unroll
;         for (int k2 = 0; k2 < 2; ++k2) { const int ks = 2 + k2; ga[k2][0] = ld8(Ab + 16 * ks); ga[k2][1] = ld8(Ab + 32 * LS + 16 * ks); gb[k2][0] = ld8(Bb + 16 * ks); gb[k2][1] = ld8(Bb + 32 * LS + 16 * ks); }
; #pragma unroll
;         for (int k2 = 0; k2 < 2; ++k2) {
;             acc[0][0] = MFMA(ga[k2][0], gb[k2][0], acc[0][0]); acc[0][1] = MFMA(ga[k2][0], gb[k2][1], acc[0][1]);
;             acc[1][0] = MFMA(ga[k2][1], gb[k2][0], acc[1][0]); acc[1][1] = MFMA(ga[k2][1], gb[k2][1], acc[1][1]);
;         }
;         if (kt + 1 < nk) sstore(stset, buf ^ 1, kt + 1);
; #pragma unroll
;         for (int i = 0; i < 8; ++i) { __builtin_amdgcn_sched_group_barrier(0x008, 1, 0); __builtin_amdgcn_sched_group_barrier(0x100, 1, 0); }
; #pragma unroll
;         for (int i = 0; i < 8; ++i) { __builtin_amdgcn_sched_group_barrier(0x008, 1, 0); __builtin_amdgcn_sched_group_barrier(0x200, 1, 0); }
;         __builtin_amdgcn_sched_barrier(0);
;         __syncthreads();
	ds_read_b128 v[202:205], v194
	ds_read_b128 v[218:221], v195 offset:36864
	ds_read_b128 v[226:229], v195 offset:41472
	ds_read_b128 v[210:213], v194 offset:4608
	ds_read_b128 v[206:209], v194 offset:32
	ds_read_b128 v[230:233], v195 offset:41504
	ds_read_b128 v[214:217], v194 offset:4640
	ds_read_b128 v[222:225], v195 offset:36896
	s_waitcnt lgkmcnt(6)
	v_mfma_f32_32x32x16_bf16 v[52:67], v[202:205], v[218:221], v[52:67]
	global_load_dwordx4 v[68:71], v[164:165], off offset:1920
	s_waitcnt lgkmcnt(5)
	v_mfma_f32_32x32x16_bf16 v[36:51], v[202:205], v[226:229], v[36:51]
	global_load_dwordx4 v[72:75], v[162:163], off offset:1920
	s_waitcnt lgkmcnt(4)
	v_mfma_f32_32x32x16_bf16 v[4:19], v[210:213], v[226:229], v[4:19]
	global_load_dwordx4 v[76:79], v[160:161], off offset:1920
	s_waitcnt lgkmcnt(2)
	v_mfma_f32_32x32x16_bf16 v[36:51], v[206:209], v[230:233], v[36:51]
	global_load_dwordx4 v[80:83], v[158:159], off offset:1920
	s_waitcnt lgkmcnt(1)
	v_mfma_f32_32x32x16_bf16 v[4:19], v[214:217], v[230:233], v[4:19]
	global_load_dwordx4 v[84:87], v[156:157], off offset:1920
	ds_read_b128 v[230:233], v195 offset:41568
	ds_read_b128 v[202:205], v194 offset:4672
	v_mfma_f32_32x32x16_bf16 v[20:35], v[210:213], v[218:221], v[20:35]
	global_load_dwordx4 v[88:91], v[154:155], off offset:1920
	ds_read_b128 v[218:221], v194 offset:4704
	ds_read_b128 v[210:213], v194 offset:64
	s_waitcnt lgkmcnt(4)
	v_mfma_f32_32x32x16_bf16 v[52:67], v[206:209], v[222:225], v[52:67]
	global_load_dwordx4 v[92:95], v[152:153], off offset:1920
	ds_read_b128 v[226:229], v195 offset:36960
	ds_read_b128 v[206:209], v195 offset:41536
	v_mfma_f32_32x32x16_bf16 v[20:35], v[214:217], v[222:225], v[20:35]
	global_load_dwordx4 v[104:107], v[146:147], off offset:1920
	ds_read_b128 v[222:225], v195 offset:36928
	ds_read_b128 v[214:217], v194 offset:96
	s_waitcnt lgkmcnt(1)
	v_mfma_f32_32x32x16_bf16 v[52:67], v[210:213], v[222:225], v[52:67]
	s_waitcnt vmcnt(23)
	ds_write_b128 v167, v[96:99] offset:18432
	v_mfma_f32_32x32x16_bf16 v[36:51], v[210:213], v[206:209], v[36:51]
	s_waitcnt vmcnt(22)
	ds_write_b128 v167, v[100:103] offset:55296
	v_mfma_f32_32x32x16_bf16 v[20:35], v[202:205], v[222:225], v[20:35]
	s_waitcnt vmcnt(21)
	ds_write_b128 v190, v[108:111] offset:18432
	v_mfma_f32_32x32x16_bf16 v[4:19], v[202:205], v[206:209], v[4:19]
	s_waitcnt vmcnt(20)
	ds_write_b128 v190, v[112:115] offset:55296
	s_waitcnt lgkmcnt(4)
	v_mfma_f32_32x32x16_bf16 v[52:67], v[214:217], v[226:229], v[52:67]
	s_waitcnt vmcnt(19)
	ds_write_b128 v191, v[116:119] offset:18432
	v_mfma_f32_32x32x16_bf16 v[36:51], v[214:217], v[230:233], v[36:51]
	s_waitcnt vmcnt(18)
	ds_write_b128 v191, v[120:123] offset:55296
	v_mfma_f32_32x32x16_bf16 v[20:35], v[218:221], v[226:229], v[20:35]
	s_waitcnt vmcnt(17)
	ds_write_b128 v192, v[124:127] offset:18432
	v_mfma_f32_32x32x16_bf16 v[4:19], v[218:221], v[230:233], v[4:19]
	s_waitcnt vmcnt(16)
	ds_write_b128 v192, v[128:131] offset:55296
	s_waitcnt lgkmcnt(0)
	s_barrier
	ds_read_b128 v[202:205], v196
	ds_read_b128 v[218:221], v197 offset:36864
	ds_read_b128 v[226:229], v197 offset:41472
	ds_read_b128 v[210:213], v196 offset:4608
	ds_read_b128 v[206:209], v196 offset:32
	ds_read_b128 v[230:233], v197 offset:41504
	ds_read_b128 v[214:217], v196 offset:4640
	ds_read_b128 v[222:225], v197 offset:36896
	s_waitcnt lgkmcnt(6)
	v_mfma_f32_32x32x16_bf16 v[52:67], v[202:205], v[218:221], v[52:67]
	s_waitcnt lgkmcnt(5)
	v_mfma_f32_32x32x16_bf16 v[36:51], v[202:205], v[226:229], v[36:51]
	s_waitcnt lgkmcnt(4)
	v_mfma_f32_32x32x16_bf16 v[4:19], v[210:213], v[226:229], v[4:19]
	s_waitcnt lgkmcnt(2)
	v_mfma_f32_32x32x16_bf16 v[36:51], v[206:209], v[230:233], v[36:51]
	s_waitcnt lgkmcnt(1)
	v_mfma_f32_32x32x16_bf16 v[4:19], v[214:217], v[230:233], v[4:19]
	ds_read_b128 v[230:233], v197 offset:41568
	ds_read_b128 v[202:205], v196 offset:4672
	v_mfma_f32_32x32x16_bf16 v[20:35], v[210:213], v[218:221], v[20:35]
	ds_read_b128 v[218:221], v196 offset:4704
	ds_read_b128 v[210:213], v196 offset:64
	s_waitcnt lgkmcnt(4)
	v_mfma_f32_32x32x16_bf16 v[52:67], v[206:209], v[222:225], v[52:67]
	ds_read_b128 v[226:229], v197 offset:36960
	ds_read_b128 v[206:209], v197 offset:41536
	v_mfma_f32_32x32x16_bf16 v[20:35], v[214:217], v[222:225], v[20:35]
	ds_read_b128 v[222:225], v197 offset:36928
	ds_read_b128 v[214:217], v196 offset:96
	s_waitcnt lgkmcnt(1)
	v_mfma_f32_32x32x16_bf16 v[52:67], v[210:213], v[222:225], v[52:67]
	s_waitcnt vmcnt(15)
	ds_write_b128 v167, v[132:135]
	v_mfma_f32_32x32x16_bf16 v[36:51], v[210:213], v[206:209], v[36:51]
	s_waitcnt vmcnt(14)
	ds_write_b128 v167, v[136:139] offset:36864
	v_mfma_f32_32x32x16_bf16 v[20:35], v[202:205], v[222:225], v[20:35]
	s_waitcnt vmcnt(13)
	ds_write_b128 v190, v[140:143]
	v_mfma_f32_32x32x16_bf16 v[4:19], v[202:205], v[206:209], v[4:19]
	s_waitcnt vmcnt(12)
	ds_write_b128 v190, v[198:201] offset:36864
	s_waitcnt lgkmcnt(4)
	v_mfma_f32_32x32x16_bf16 v[52:67], v[214:217], v[226:229], v[52:67]
	s_waitcnt vmcnt(11)
	ds_write_b128 v191, v[174:177]
	v_mfma_f32_32x32x16_bf16 v[36:51], v[214:217], v[230:233], v[36:51]
	s_waitcnt vmcnt(10)
	ds_write_b128 v191, v[178:181] offset:36864
	v_mfma_f32_32x32x16_bf16 v[20:35], v[218:221], v[226:229], v[20:35]
	s_waitcnt vmcnt(9)
	ds_write_b128 v192, v[242:245]
	v_mfma_f32_32x32x16_bf16 v[4:19], v[218:221], v[230:233], v[4:19]
	s_waitcnt vmcnt(8)
	ds_write_b128 v192, v[246:249] offset:36864
	s_waitcnt lgkmcnt(0)
	s_barrier
; #define MFMA(a, b, c) __builtin_amdgcn_mfma_f32_32x32x16_bf16((a), (b), (c), 0, 0, 0)
; template <class Epi, class ColV>
; DI void gemm_tile(const bf16_t* __restrict__ A, int lda, const bf16_t* __restrict__ Bt, int ldb, int K, int m0, int n0, unsigned char* smem, Epi epi, ColV colv, const bf16_t* __restrict__ HYT = nullptr) {
;     ...
;     auto step = [&](int kt, u32x4 (&ldset)[8], const u32x4 (&stset)[8]) {
;         const int buf = kt & 1;
;         if (kt + 2 < nk) gload(ldset, kt + 2);
;         const bf16_t* Ab = As + (buf * 128 + 64 * wr + li) * LS + 8 * lh;
;         const bf16_t* Bb = Bs + (buf * 128 + 64 * wc + li) * LS + 8 * lh;
;         bf16x8 fa[2][2], fb[2][2], ga[2][2], gb[2][2];
; #pragma unroll
;         for (int k2 = 0; k2 < 2; ++k2) { fa[k2][0] = ld8(Ab + 16 * k2); fa[k2][1] = ld8(Ab + 32 * LS + 16 * k2); fb[k2][0] = ld8(Bb + 16 * k2); fb[k2][1] = ld8(Bb + 32 * LS + 16 * k2); }
;         __builtin_amdgcn_sched_barrier(0);
; #pragma unroll
;         for (int k2 = 0; k2 < 2; ++k2) {
;             acc[0][0] = MFMA(fa[k2][0], fb[k2][0], acc[0][0]); acc[0][1] = MFMA(fa[k2][0], fb[k2][1], acc[0][1]);
;             acc[1][0] = MFMA(fa[k2][1], fb[k2][0], acc[1][0]); acc[1][1] = MFMA(fa[k2][1], fb[k2][1], acc[1][1]);
;         }
; #pragma unroll
;         for (int k2 = 0; k2 < 2; ++k2) { const int ks = 2 + k2; ga[k2][0] = ld8(Ab + 16 * ks); ga[k2][1] = ld8(Ab + 32 * LS + 16 * ks); gb[k2][0] = ld8(Bb + 16 * ks); gb[k2][1] = ld8(Bb + 32 * LS + 16 * ks); }
; #pragma unroll
;         for (int k2 = 0; k2 < 2; ++k2) {
;             acc[0][0] = MFMA(ga[k2][0], gb[k2][0], acc[0][0]); acc[0][1] = MFMA(ga[k2][0], gb[k2][1], acc[0][1]);
;             acc[1][0] = MFMA(ga[k2][1], gb[k2][0], acc[1][0]); acc[1][1] = MFMA(ga[k2][1], gb[k2][1], acc[1][1]);
;         }
;         if (kt + 1 < nk) sstore(stset, buf ^ 1, kt + 1);
; #pragma unroll
;         for (int i = 0; i < 8; ++i) { __builtin_amdgcn_sched_group_barrier(0x008, 1, 0); __builtin_amdgcn_sched_group_barrier(0x100, 1, 0); }
; #pragma unroll
;         for (int i = 0; i < 8; ++i) { __builtin_amdgcn_sched_group_barrier(0x008, 1, 0); __builtin_amdgcn_sched_group_barrier(0x200, 1, 0); }
;         __builtin_amdgcn_sched_barrier(0);
;         __syncthreads();
;     };
	ds_read_b128 v[202:205], v194
	ds_read_b128 v[218:221], v195 offset:36864
	ds_read_b128 v[226:229], v195 offset:41472
	ds_read_b128 v[210:213], v194 offset:4608
	ds_read_b128 v[206:209], v194 offset:32
	ds_read_b128 v[230:233], v195 offset:41504
	ds_read_b128 v[214:217], v194 offset:4640
	ds_read_b128 v[222:225], v195 offset:36896
	s_waitcnt lgkmcnt(6)
	v_mfma_f32_32x32x16_bf16 v[52:67], v[202:205], v[218:221], v[52:67]
	s_waitcnt lgkmcnt(5)
	v_mfma_f32_32x32x16_bf16 v[36:51], v[202:205], v[226:229], v[36:51]
	s_waitcnt lgkmcnt(4)
	v_mfma_f32_32x32x16_bf16 v[4:19], v[210:213], v[226:229], v[4:19]
	s_waitcnt lgkmcnt(2)
	v_mfma_f32_32x32x16_bf16 v[36:51], v[206:209], v[230:233], v[36:51]
	s_waitcnt lgkmcnt(1)
	v_mfma_f32_32x32x16_bf16 v[4:19], v[214:217], v[230:233], v[4:19]
	ds_read_b128 v[230:233], v195 offset:41568
	ds_read_b128 v[202:205], v194 offset:4672
	v_mfma_f32_32x32x16_bf16 v[20:35], v[210:213], v[218:221], v[20:35]
	ds_read_b128 v[218:221], v194 offset:4704
	ds_read_b128 v[210:213], v194 offset:64
	s_waitcnt lgkmcnt(4)
	v_mfma_f32_32x32x16_bf16 v[52:67], v[206:209], v[222:225], v[52:67]
	ds_read_b128 v[226:229], v195 offset:36960
	ds_read_b128 v[206:209], v195 offset:41536
	v_mfma_f32_32x32x16_bf16 v[20:35], v[214:217], v[222:225], v[20:35]
	ds_read_b128 v[222:225], v195 offset:36928
	ds_read_b128 v[214:217], v194 offset:96
	s_waitcnt lgkmcnt(1)
	v_mfma_f32_32x32x16_bf16 v[52:67], v[210:213], v[222:225], v[52:67]
	s_waitcnt vmcnt(7)
	ds_write_b128 v167, v[68:71] offset:18432
	v_mfma_f32_32x32x16_bf16 v[36:51], v[210:213], v[206:209], v[36:51]
	s_waitcnt vmcnt(6)
	ds_write_b128 v167, v[72:75] offset:55296
	v_mfma_f32_32x32x16_bf16 v[20:35], v[202:205], v[222:225], v[20:35]
	s_waitcnt vmcnt(5)
	ds_write_b128 v190, v[76:79] offset:18432
	v_mfma_f32_32x32x16_bf16 v[4:19], v[202:205], v[206:209], v[4:19]
	s_waitcnt vmcnt(4)
	ds_write_b128 v190, v[80:83] offset:55296
	s_waitcnt lgkmcnt(4)
	v_mfma_f32_32x32x16_bf16 v[52:67], v[214:217], v[226:229], v[52:67]
	s_waitcnt vmcnt(3)
	ds_write_b128 v191, v[84:87] offset:18432
	v_mfma_f32_32x32x16_bf16 v[36:51], v[214:217], v[230:233], v[36:51]
	s_waitcnt vmcnt(2)
	ds_write_b128 v191, v[88:91] offset:55296
	v_mfma_f32_32x32x16_bf16 v[20:35], v[218:221], v[226:229], v[20:35]
	s_waitcnt vmcnt(1)
	ds_write_b128 v192, v[92:95] offset:18432
	v_mfma_f32_32x32x16_bf16 v[4:19], v[218:221], v[230:233], v[4:19]
	s_waitcnt vmcnt(0)
	ds_write_b128 v192, v[104:107] offset:55296
	s_waitcnt lgkmcnt(0)
	s_barrier
	ds_read_b128 v[202:205], v196
	ds_read_b128 v[218:221], v197 offset:36864
	ds_read_b128 v[226:229], v197 offset:41472
	ds_read_b128 v[210:213], v196 offset:4608
	ds_read_b128 v[206:209], v196 offset:32
	ds_read_b128 v[230:233], v197 offset:41504
	ds_read_b128 v[214:217], v196 offset:4640
	ds_read_b128 v[222:225], v197 offset:36896
	s_waitcnt lgkmcnt(6)
	v_mfma_f32_32x32x16_bf16 v[52:67], v[202:205], v[218:221], v[52:67]
	s_waitcnt lgkmcnt(5)
	v_mfma_f32_32x32x16_bf16 v[36:51], v[202:205], v[226:229], v[36:51]
	s_waitcnt lgkmcnt(4)
	v_mfma_f32_32x32x16_bf16 v[4:19], v[210:213], v[226:229], v[4:19]
	s_waitcnt lgkmcnt(2)
	v_mfma_f32_32x32x16_bf16 v[36:51], v[206:209], v[230:233], v[36:51]
	s_waitcnt lgkmcnt(1)
	v_mfma_f32_32x32x16_bf16 v[4:19], v[214:217], v[230:233], v[4:19]
	ds_read_b128 v[230:233], v197 offset:41568
	ds_read_b128 v[202:205], v196 offset:4672
	v_mfma_f32_32x32x16_bf16 v[20:35], v[210:213], v[218:221], v[20:35]
	ds_read_b128 v[218:221], v196 offset:4704
	ds_read_b128 v[210:213], v196 offset:64
	s_waitcnt lgkmcnt(4)
	v_mfma_f32_32x32x16_bf16 v[52:67], v[206:209], v[222:225], v[52:67]
	ds_read_b128 v[226:229], v197 offset:36960
	ds_read_b128 v[206:209], v197 offset:41536
	v_mfma_f32_32x32x16_bf16 v[20:35], v[214:217], v[222:225], v[20:35]
	ds_read_b128 v[222:225], v197 offset:36928
	ds_read_b128 v[214:217], v196 offset:96
	s_waitcnt lgkmcnt(1)
	v_mfma_f32_32x32x16_bf16 v[52:67], v[210:213], v[222:225], v[52:67]
	v_mfma_f32_32x32x16_bf16 v[36:51], v[210:213], v[206:209], v[36:51]
	v_mfma_f32_32x32x16_bf16 v[20:35], v[202:205], v[222:225], v[20:35]
	v_mfma_f32_32x32x16_bf16 v[4:19], v[202:205], v[206:209], v[4:19]
	s_waitcnt lgkmcnt(0)
	v_mfma_f32_32x32x16_bf16 v[52:67], v[214:217], v[226:229], v[52:67]
	v_mfma_f32_32x32x16_bf16 v[36:51], v[214:217], v[230:233], v[36:51]
	v_mfma_f32_32x32x16_bf16 v[20:35], v[218:221], v[226:229], v[20:35]
	v_mfma_f32_32x32x16_bf16 v[4:19], v[218:221], v[230:233], v[4:19]
	s_waitcnt lgkmcnt(0)
	s_barrier
	s_nop 7
	s_nop 3
	s_branch .LBB0_1555
